# v40 + relaxed counted DMA waits: vmcnt(8) at phases 4/8, vmcnt(10) before the phase 2/6 barrier (one more K-tile of latency budget for the A-half-1 stage); bit-identical
# speedup vs baseline: 1.0153x; 1.0035x over previous
; #define PG8_WAIT_V(n) asm volatile("s_waitcnt vmcnt(" #n ")" ::: "memory")
; #define PG8_WAIT_L(n) asm volatile("s_waitcnt lgkmcnt(" #n ")" ::: "memory")
; #define PG8_BAR __builtin_amdgcn_s_barrier()
; #define PG8_SCHED __builtin_amdgcn_sched_barrier(0)
; template <class Epi, class AddrA, class AddrB>
; __device__ __forceinline__ void gemm_phase(const Sched S, const int lda, const int ldb, const int K, const AddrA addrA,
;                                            const AddrB addrB, const Epi E) {
;     ...
;     const bool has_next = S.next(ui + 1, nxt);
;     const char* nA = has_next ? addrA(nxt) : cA;
;     const char* nB = has_next ? addrB(nxt) : cB;
;     for (int t = 0; t < nt; t += 2) {
;       const bool last = (t == nt - 2);
;       const char* a1 = cA + (size_t)(t + 1) * kstep;
;       const char* a2 = last ? nA : cA + (size_t)(t + 2) * kstep;
;       const char* b2 = last ? nB : cB + (size_t)(t + 2) * kstep;
;       const char* a3 = a2 + kstep;
;       const char* b3 = b2 + kstep;
;       PG8_LDB(B0, 0, 0); PG8_SCHED; PG8_LDA(At, 0, 0); PG8_STAGE(PG8_SA(1, 1), a1 + hstepA, voffA);
;       PG8_WAIT_L(8); PG8_BAR; PG8_WAIT_L(0); PG8_MMA(0, 0, At, B0); PG8_BAR; PG8_SCHED;
;       PG8_LDB(B1, 0, 1); PG8_STAGE(PG8_SB(0, 0), b2, voffB);
;       PG8_BAR; PG8_WAIT_L(0); PG8_MMA(0, 1, At, B1); PG8_BAR;
;       PG8_LDA(At, 0, 1); PG8_STAGE(PG8_SA(0, 0), a2, voffA);
;       PG8_BAR; PG8_WAIT_L(0); PG8_MMA(1, 0, At, B0); PG8_BAR; PG8_SCHED;
;       PG8_STAGE(PG8_SB(0, 1), b2 + hstepB, voffB);
;       PG8_WAIT_V(6); PG8_BAR; PG8_MMA(1, 1, At, B1); PG8_BAR;
;       PG8_LDB(B0, 1, 0); PG8_SCHED; PG8_LDA(At, 1, 0); PG8_STAGE(PG8_SA(0, 1), a2 + hstepA, voffA);
;       PG8_WAIT_L(8); PG8_BAR; PG8_WAIT_L(0); PG8_MMA(0, 0, At, B0); PG8_BAR; PG8_SCHED;
;       PG8_LDB(B1, 1, 1); PG8_STAGE(PG8_SB(1, 0), b3, voffB);
;       PG8_BAR; PG8_WAIT_L(0); PG8_MMA(0, 1, At, B1); PG8_BAR;
;       PG8_LDA(At, 1, 1); PG8_STAGE(PG8_SA(1, 0), a3, voffA);
;       PG8_BAR; PG8_WAIT_L(0); PG8_MMA(1, 0, At, B0); PG8_BAR; PG8_SCHED;
;       PG8_STAGE(PG8_SB(1, 1), b3 + hstepB, voffB);
;       PG8_WAIT_V(6); PG8_BAR; PG8_MMA(1, 1, At, B1); PG8_BAR;
.LBB0_108:
	s_ashr_i32 s1, s0, 31
	s_lshl_b64 s[6:7], s[0:1], 20
	s_add_u32 s6, s20, s6
	s_addc_u32 s7, s21, s7
	s_and_b64 s[8:9], s[16:17], exec
	s_cselect_b32 s1, s7, s15
	s_cselect_b32 s11, s6, s14
	s_ashr_i32 s3, s2, 31
	s_lshl_b64 s[8:9], s[2:3], 20
	s_add_u32 s8, s22, s8
	s_addc_u32 s9, s23, s9
	s_and_b64 s[16:17], s[16:17], exec
	s_cselect_b32 s3, s9, s13
	s_cselect_b32 s36, s8, s12
	s_add_u32 s37, s12, 0x100
	s_addc_u32 s38, s13, 0
	s_add_u32 s12, s14, 0x80080
	s_addc_u32 s13, s15, 0
	s_mov_b32 s39, -2
	s_add_i32 s40, 0, 0x10000
	v_add_u32_e32 v246, s40, v145
	ds_read_b128 v[148:151], v246
	ds_read_b128 v[152:155], v246 offset:1024
	ds_read_b128 v[156:159], v246 offset:2048
	ds_read_b128 v[160:163], v246 offset:3072
	s_add_i32 m0, s24, 0xc000
	ds_read_b128 v[168:171], v146
	ds_read_b128 v[172:175], v146 offset:1024
	ds_read_b128 v[176:179], v146 offset:2048
	ds_read_b128 v[180:183], v146 offset:3072
	ds_read_b128 v[184:187], v146 offset:4096
	ds_read_b128 v[188:191], v146 offset:5120
	ds_read_b128 v[192:195], v146 offset:6144
	ds_read_b128 v[212:215], v146 offset:7168
	global_load_lds_dwordx4 v140, s[12:13]
	s_add_i32 m0, s24, 0xe000
	s_nop 0
	global_load_lds_dwordx4 v138, s[12:13]
	s_waitcnt lgkmcnt(6)
	s_setprio 1
	s_barrier
	v_mfma_f32_16x16x32_bf16 v[128:131], v[148:151], v[168:171], 0
	v_mfma_f32_16x16x32_bf16 v[128:131], v[152:155], v[172:175], v[128:131]
	s_waitcnt lgkmcnt(0)
	v_mfma_f32_16x16x32_bf16 v[120:123], v[148:151], v[176:179], 0
	v_mfma_f32_16x16x32_bf16 v[120:123], v[152:155], v[180:183], v[120:123]
	v_mfma_f32_16x16x32_bf16 v[104:107], v[148:151], v[184:187], 0
	v_mfma_f32_16x16x32_bf16 v[104:107], v[152:155], v[188:191], v[104:107]
	v_mfma_f32_16x16x32_bf16 v[88:91], v[148:151], v[192:195], 0
	v_mfma_f32_16x16x32_bf16 v[88:91], v[152:155], v[212:215], v[88:91]
	v_mfma_f32_16x16x32_bf16 v[124:127], v[156:159], v[168:171], 0
	v_mfma_f32_16x16x32_bf16 v[124:127], v[160:163], v[172:175], v[124:127]
	v_mfma_f32_16x16x32_bf16 v[112:115], v[156:159], v[176:179], 0
	v_mfma_f32_16x16x32_bf16 v[112:115], v[160:163], v[180:183], v[112:115]
	v_mfma_f32_16x16x32_bf16 v[96:99], v[156:159], v[184:187], 0
	v_mfma_f32_16x16x32_bf16 v[96:99], v[160:163], v[188:191], v[96:99]
	v_mfma_f32_16x16x32_bf16 v[80:83], v[156:159], v[192:195], 0
	v_mfma_f32_16x16x32_bf16 v[80:83], v[160:163], v[212:215], v[80:83]
	s_barrier
	s_setprio 0
	s_add_u32 s14, s12, 0xfff80080
	s_addc_u32 s15, s13, -1
	s_cmp_eq_u32 s39, 28
	s_cselect_b32 s17, s1, s15
	s_cselect_b32 s16, s11, s14
	s_cselect_b32 s15, s3, s38
	s_cselect_b32 s14, s36, s37
	s_add_i32 s42, 0, 0x14000
	s_add_i32 s40, s40, s19
	ds_read_b128 v[216:219], v246 offset:16384
	ds_read_b128 v[220:223], v246 offset:17408
	ds_read_b128 v[224:227], v246 offset:18432
	ds_read_b128 v[228:231], v246 offset:19456
	s_add_u32 s98, s14, 0x80
	s_addc_u32 s99, s15, 0
	s_mov_b32 m0, s40
	s_nop 0
	global_load_lds_dwordx4 v134, s[14:15]
	s_add_i32 m0, s40, 0x2000
	s_nop 0
	global_load_lds_dwordx4 v0, s[14:15]
	s_mov_b32 m0, s24
	s_add_u32 s100, s16, 0x80
	s_addc_u32 s101, s17, 0
	s_waitcnt vmcnt(10)
	s_waitcnt lgkmcnt(2)
	s_setprio 1
	s_barrier
	v_mfma_f32_16x16x32_bf16 v[116:119], v[216:219], v[168:171], 0
	v_mfma_f32_16x16x32_bf16 v[116:119], v[220:223], v[172:175], v[116:119]
	s_waitcnt lgkmcnt(0)
	v_mfma_f32_16x16x32_bf16 v[100:103], v[216:219], v[176:179], 0
	v_mfma_f32_16x16x32_bf16 v[100:103], v[220:223], v[180:183], v[100:103]
	v_mfma_f32_16x16x32_bf16 v[84:87], v[216:219], v[184:187], 0
	v_mfma_f32_16x16x32_bf16 v[84:87], v[220:223], v[188:191], v[84:87]
	v_mfma_f32_16x16x32_bf16 v[72:75], v[216:219], v[192:195], 0
	v_mfma_f32_16x16x32_bf16 v[72:75], v[220:223], v[212:215], v[72:75]
	v_mfma_f32_16x16x32_bf16 v[108:111], v[224:227], v[168:171], 0
	v_mfma_f32_16x16x32_bf16 v[108:111], v[228:231], v[172:175], v[108:111]
	v_mfma_f32_16x16x32_bf16 v[92:95], v[224:227], v[176:179], 0
	v_mfma_f32_16x16x32_bf16 v[92:95], v[228:231], v[180:183], v[92:95]
	v_mfma_f32_16x16x32_bf16 v[76:79], v[224:227], v[184:187], 0
	v_mfma_f32_16x16x32_bf16 v[76:79], v[228:231], v[188:191], v[76:79]
	v_mfma_f32_16x16x32_bf16 v[68:71], v[224:227], v[192:195], 0
	v_mfma_f32_16x16x32_bf16 v[68:71], v[228:231], v[212:215], v[68:71]
	s_barrier
	s_setprio 0
	ds_read_b128 v[168:171], v146 offset:16384
	ds_read_b128 v[172:175], v146 offset:17408
	ds_read_b128 v[176:179], v146 offset:18432
	ds_read_b128 v[180:183], v146 offset:19456
	ds_read_b128 v[184:187], v146 offset:20480
	ds_read_b128 v[188:191], v146 offset:21504
	ds_read_b128 v[192:195], v146 offset:22528
	ds_read_b128 v[212:215], v146 offset:23552
	global_load_lds_dwordx4 v136, s[16:17]
	s_mov_b32 m0, s25
	s_nop 0
	global_load_lds_dwordx4 v132, s[16:17]
	s_waitcnt lgkmcnt(6)
	s_setprio 1
	s_barrier
	v_mfma_f32_16x16x32_bf16 v[64:67], v[148:151], v[168:171], 0
	v_mfma_f32_16x16x32_bf16 v[64:67], v[152:155], v[172:175], v[64:67]
	s_waitcnt lgkmcnt(0)
	v_mfma_f32_16x16x32_bf16 v[56:59], v[148:151], v[176:179], 0
	v_mfma_f32_16x16x32_bf16 v[56:59], v[152:155], v[180:183], v[56:59]
	v_mfma_f32_16x16x32_bf16 v[40:43], v[148:151], v[184:187], 0
	v_mfma_f32_16x16x32_bf16 v[40:43], v[152:155], v[188:191], v[40:43]
	v_mfma_f32_16x16x32_bf16 v[24:27], v[148:151], v[192:195], 0
	v_mfma_f32_16x16x32_bf16 v[24:27], v[152:155], v[212:215], v[24:27]
	v_mfma_f32_16x16x32_bf16 v[60:63], v[156:159], v[168:171], 0
	v_mfma_f32_16x16x32_bf16 v[60:63], v[160:163], v[172:175], v[60:63]
	v_mfma_f32_16x16x32_bf16 v[48:51], v[156:159], v[176:179], 0
	v_mfma_f32_16x16x32_bf16 v[48:51], v[160:163], v[180:183], v[48:51]
	v_mfma_f32_16x16x32_bf16 v[32:35], v[156:159], v[184:187], 0
	v_mfma_f32_16x16x32_bf16 v[32:35], v[160:163], v[188:191], v[32:35]
	v_mfma_f32_16x16x32_bf16 v[16:19], v[156:159], v[192:195], 0
	v_mfma_f32_16x16x32_bf16 v[16:19], v[160:163], v[212:215], v[16:19]
	s_barrier
; #define PG8_WAIT_V(n) asm volatile("s_waitcnt vmcnt(" #n ")" ::: "memory")
; #define PG8_WAIT_L(n) asm volatile("s_waitcnt lgkmcnt(" #n ")" ::: "memory")
; #define PG8_BAR __builtin_amdgcn_s_barrier()
; #define PG8_SCHED __builtin_amdgcn_sched_barrier(0)
; template <class Epi, class AddrA, class AddrB>
; __device__ __forceinline__ void gemm_phase(const Sched S, const int lda, const int ldb, const int K, const AddrA addrA,
;                                            const AddrB addrB, const Epi E) {
;     ...
;       PG8_LDB(B0, 0, 0); PG8_SCHED; PG8_LDA(At, 0, 0); PG8_STAGE(PG8_SA(1, 1), a1 + hstepA, voffA);
;       PG8_WAIT_L(8); PG8_BAR; PG8_WAIT_L(0); PG8_MMA(0, 0, At, B0); PG8_BAR; PG8_SCHED;
;       PG8_LDB(B1, 0, 1); PG8_STAGE(PG8_SB(0, 0), b2, voffB);
;       PG8_BAR; PG8_WAIT_L(0); PG8_MMA(0, 1, At, B1); PG8_BAR;
;       PG8_LDA(At, 0, 1); PG8_STAGE(PG8_SA(0, 0), a2, voffA);
;       PG8_BAR; PG8_WAIT_L(0); PG8_MMA(1, 0, At, B0); PG8_BAR; PG8_SCHED;
;       PG8_STAGE(PG8_SB(0, 1), b2 + hstepB, voffB);
;       PG8_WAIT_V(6); PG8_BAR; PG8_MMA(1, 1, At, B1); PG8_BAR;
;       PG8_LDB(B0, 1, 0); PG8_SCHED; PG8_LDA(At, 1, 0); PG8_STAGE(PG8_SA(0, 1), a2 + hstepA, voffA);
;       PG8_WAIT_L(8); PG8_BAR; PG8_WAIT_L(0); PG8_MMA(0, 0, At, B0); PG8_BAR; PG8_SCHED;
;       PG8_LDB(B1, 1, 1); PG8_STAGE(PG8_SB(1, 0), b3, voffB);
;       PG8_BAR; PG8_WAIT_L(0); PG8_MMA(0, 1, At, B1); PG8_BAR;
;       PG8_LDA(At, 1, 1); PG8_STAGE(PG8_SA(1, 0), a3, voffA);
;       PG8_BAR; PG8_WAIT_L(0); PG8_MMA(1, 0, At, B0); PG8_BAR; PG8_SCHED;
;       PG8_STAGE(PG8_SB(1, 1), b3 + hstepB, voffB);
;       PG8_WAIT_V(6); PG8_BAR; PG8_MMA(1, 1, At, B1); PG8_BAR;
	s_setprio 0
	s_add_u32 s40, s14, 0x80000
	s_addc_u32 s41, s15, 0
	s_add_i32 s42, s42, s19
	s_mov_b32 m0, s42
	s_nop 0
	global_load_lds_dwordx4 v134, s[40:41]
	s_add_i32 m0, s42, 0x2000
	s_nop 0
	global_load_lds_dwordx4 v0, s[40:41]
	s_add_i32 s40, 0, 0x18000
	s_waitcnt vmcnt(8)
	s_setprio 1
	s_barrier
	v_mfma_f32_16x16x32_bf16 v[52:55], v[216:219], v[168:171], 0
	v_mfma_f32_16x16x32_bf16 v[52:55], v[220:223], v[172:175], v[52:55]
	v_mfma_f32_16x16x32_bf16 v[36:39], v[216:219], v[176:179], 0
	v_mfma_f32_16x16x32_bf16 v[36:39], v[220:223], v[180:183], v[36:39]
	v_mfma_f32_16x16x32_bf16 v[20:23], v[216:219], v[184:187], 0
	v_mfma_f32_16x16x32_bf16 v[20:23], v[220:223], v[188:191], v[20:23]
	v_mfma_f32_16x16x32_bf16 v[8:11], v[216:219], v[192:195], 0
	v_mfma_f32_16x16x32_bf16 v[8:11], v[220:223], v[212:215], v[8:11]
	v_mfma_f32_16x16x32_bf16 v[44:47], v[224:227], v[168:171], 0
	v_mfma_f32_16x16x32_bf16 v[44:47], v[228:231], v[172:175], v[44:47]
	v_mfma_f32_16x16x32_bf16 v[28:31], v[224:227], v[176:179], 0
	v_mfma_f32_16x16x32_bf16 v[28:31], v[228:231], v[180:183], v[28:31]
	v_mfma_f32_16x16x32_bf16 v[12:15], v[224:227], v[184:187], 0
	v_mfma_f32_16x16x32_bf16 v[12:15], v[228:231], v[188:191], v[12:15]
	v_mfma_f32_16x16x32_bf16 v[4:7], v[224:227], v[192:195], 0
	v_mfma_f32_16x16x32_bf16 v[4:7], v[228:231], v[212:215], v[4:7]
	s_barrier
	s_setprio 0
	ds_read_b128 v[148:151], v246 offset:32768
	ds_read_b128 v[152:155], v246 offset:33792
	ds_read_b128 v[156:159], v246 offset:34816
	ds_read_b128 v[160:163], v246 offset:35840
	s_add_u32 s16, s16, 0x80000
	s_addc_u32 s17, s17, 0
	s_mov_b32 m0, s26
	ds_read_b128 v[168:171], v146 offset:32768
	ds_read_b128 v[172:175], v146 offset:33792
	ds_read_b128 v[176:179], v146 offset:34816
	ds_read_b128 v[180:183], v146 offset:35840
	ds_read_b128 v[184:187], v146 offset:36864
	ds_read_b128 v[188:191], v146 offset:37888
	ds_read_b128 v[192:195], v146 offset:38912
	ds_read_b128 v[212:215], v146 offset:39936
	global_load_lds_dwordx4 v136, s[16:17]
	s_mov_b32 m0, s27
	s_nop 0
	global_load_lds_dwordx4 v132, s[16:17]
	s_waitcnt lgkmcnt(6)
	s_setprio 1
	s_barrier
	v_mfma_f32_16x16x32_bf16 v[128:131], v[148:151], v[168:171], v[128:131]
	v_mfma_f32_16x16x32_bf16 v[128:131], v[152:155], v[172:175], v[128:131]
	s_waitcnt lgkmcnt(0)
	v_mfma_f32_16x16x32_bf16 v[120:123], v[148:151], v[176:179], v[120:123]
	v_mfma_f32_16x16x32_bf16 v[120:123], v[152:155], v[180:183], v[120:123]
	v_mfma_f32_16x16x32_bf16 v[104:107], v[148:151], v[184:187], v[104:107]
	v_mfma_f32_16x16x32_bf16 v[104:107], v[152:155], v[188:191], v[104:107]
	v_mfma_f32_16x16x32_bf16 v[88:91], v[148:151], v[192:195], v[88:91]
	v_mfma_f32_16x16x32_bf16 v[88:91], v[152:155], v[212:215], v[88:91]
	v_mfma_f32_16x16x32_bf16 v[124:127], v[156:159], v[168:171], v[124:127]
	v_mfma_f32_16x16x32_bf16 v[124:127], v[160:163], v[172:175], v[124:127]
	v_mfma_f32_16x16x32_bf16 v[112:115], v[156:159], v[176:179], v[112:115]
	v_mfma_f32_16x16x32_bf16 v[112:115], v[160:163], v[180:183], v[112:115]
	v_mfma_f32_16x16x32_bf16 v[96:99], v[156:159], v[184:187], v[96:99]
	v_mfma_f32_16x16x32_bf16 v[96:99], v[160:163], v[188:191], v[96:99]
	v_mfma_f32_16x16x32_bf16 v[80:83], v[156:159], v[192:195], v[80:83]
	v_mfma_f32_16x16x32_bf16 v[80:83], v[160:163], v[212:215], v[80:83]
	s_barrier
	s_setprio 0
	s_add_i32 s16, 0, 0x1c000
	s_add_i32 s17, s40, s19
	s_mov_b32 m0, s17
	ds_read_b128 v[216:219], v246 offset:49152
	ds_read_b128 v[220:223], v246 offset:50176
	ds_read_b128 v[224:227], v246 offset:51200
	ds_read_b128 v[228:231], v246 offset:52224
	global_load_lds_dwordx4 v134, s[98:99]
	s_add_i32 m0, s17, 0x2000
	s_nop 0
	global_load_lds_dwordx4 v0, s[98:99]
	s_mov_b32 m0, s30
	s_waitcnt vmcnt(10)
	s_waitcnt lgkmcnt(2)
	s_setprio 1
	s_barrier
	v_mfma_f32_16x16x32_bf16 v[116:119], v[216:219], v[168:171], v[116:119]
	v_mfma_f32_16x16x32_bf16 v[116:119], v[220:223], v[172:175], v[116:119]
	s_waitcnt lgkmcnt(0)
	v_mfma_f32_16x16x32_bf16 v[100:103], v[216:219], v[176:179], v[100:103]
	v_mfma_f32_16x16x32_bf16 v[100:103], v[220:223], v[180:183], v[100:103]
	v_mfma_f32_16x16x32_bf16 v[84:87], v[216:219], v[184:187], v[84:87]
	v_mfma_f32_16x16x32_bf16 v[84:87], v[220:223], v[188:191], v[84:87]
	v_mfma_f32_16x16x32_bf16 v[72:75], v[216:219], v[192:195], v[72:75]
	v_mfma_f32_16x16x32_bf16 v[72:75], v[220:223], v[212:215], v[72:75]
	v_mfma_f32_16x16x32_bf16 v[108:111], v[224:227], v[168:171], v[108:111]
	v_mfma_f32_16x16x32_bf16 v[108:111], v[228:231], v[172:175], v[108:111]
	v_mfma_f32_16x16x32_bf16 v[92:95], v[224:227], v[176:179], v[92:95]
	v_mfma_f32_16x16x32_bf16 v[92:95], v[228:231], v[180:183], v[92:95]
	v_mfma_f32_16x16x32_bf16 v[76:79], v[224:227], v[184:187], v[76:79]
	v_mfma_f32_16x16x32_bf16 v[76:79], v[228:231], v[188:191], v[76:79]
	v_mfma_f32_16x16x32_bf16 v[68:71], v[224:227], v[192:195], v[68:71]
	v_mfma_f32_16x16x32_bf16 v[68:71], v[228:231], v[212:215], v[68:71]
	s_barrier
	s_setprio 0
	ds_read_b128 v[168:171], v146 offset:49152
	ds_read_b128 v[172:175], v146 offset:50176
	ds_read_b128 v[176:179], v146 offset:51200
	ds_read_b128 v[180:183], v146 offset:52224
	ds_read_b128 v[184:187], v146 offset:53248
	ds_read_b128 v[188:191], v146 offset:54272
	ds_read_b128 v[192:195], v146 offset:55296
	ds_read_b128 v[212:215], v146 offset:56320
	global_load_lds_dwordx4 v136, s[100:101]
	s_mov_b32 m0, s31
	s_nop 0
	global_load_lds_dwordx4 v132, s[100:101]
	s_waitcnt lgkmcnt(6)
	s_setprio 1
	s_barrier
; #define PG8_WAIT_V(n) asm volatile("s_waitcnt vmcnt(" #n ")" ::: "memory")
; #define PG8_WAIT_L(n) asm volatile("s_waitcnt lgkmcnt(" #n ")" ::: "memory")
; #define PG8_BAR __builtin_amdgcn_s_barrier()
; #define PG8_SCHED __builtin_amdgcn_sched_barrier(0)
; template <class Epi, class AddrA, class AddrB>
; __device__ __forceinline__ void gemm_phase(const Sched S, const int lda, const int ldb, const int K, const AddrA addrA,
;                                            const AddrB addrB, const Epi E) {
;     ...
;     for (int t = 0; t < nt; t += 2) {
;       const bool last = (t == nt - 2);
;       const char* a1 = cA + (size_t)(t + 1) * kstep;
;       const char* a2 = last ? nA : cA + (size_t)(t + 2) * kstep;
;       const char* b2 = last ? nB : cB + (size_t)(t + 2) * kstep;
;       const char* a3 = a2 + kstep;
;       const char* b3 = b2 + kstep;
;       PG8_LDB(B0, 0, 0); PG8_SCHED; PG8_LDA(At, 0, 0); PG8_STAGE(PG8_SA(1, 1), a1 + hstepA, voffA);
;       PG8_WAIT_L(8); PG8_BAR; PG8_WAIT_L(0); PG8_MMA(0, 0, At, B0); PG8_BAR; PG8_SCHED;
;       PG8_LDB(B1, 0, 1); PG8_STAGE(PG8_SB(0, 0), b2, voffB);
;       PG8_BAR; PG8_WAIT_L(0); PG8_MMA(0, 1, At, B1); PG8_BAR;
;       PG8_LDA(At, 0, 1); PG8_STAGE(PG8_SA(0, 0), a2, voffA);
;       PG8_BAR; PG8_WAIT_L(0); PG8_MMA(1, 0, At, B0); PG8_BAR; PG8_SCHED;
;       PG8_STAGE(PG8_SB(0, 1), b2 + hstepB, voffB);
;       PG8_WAIT_V(6); PG8_BAR; PG8_MMA(1, 1, At, B1); PG8_BAR;
;       PG8_LDB(B0, 1, 0); PG8_SCHED; PG8_LDA(At, 1, 0); PG8_STAGE(PG8_SA(0, 1), a2 + hstepA, voffA);
;       PG8_WAIT_L(8); PG8_BAR; PG8_WAIT_L(0); PG8_MMA(0, 0, At, B0); PG8_BAR; PG8_SCHED;
;       PG8_LDB(B1, 1, 1); PG8_STAGE(PG8_SB(1, 0), b3, voffB);
;       PG8_BAR; PG8_WAIT_L(0); PG8_MMA(0, 1, At, B1); PG8_BAR;
;       PG8_LDA(At, 1, 1); PG8_STAGE(PG8_SA(1, 0), a3, voffA);
;       PG8_BAR; PG8_WAIT_L(0); PG8_MMA(1, 0, At, B0); PG8_BAR; PG8_SCHED;
;       PG8_STAGE(PG8_SB(1, 1), b3 + hstepB, voffB);
;       PG8_WAIT_V(6); PG8_BAR; PG8_MMA(1, 1, At, B1); PG8_BAR;
	v_mfma_f32_16x16x32_bf16 v[64:67], v[148:151], v[168:171], v[64:67]
	v_mfma_f32_16x16x32_bf16 v[64:67], v[152:155], v[172:175], v[64:67]
	s_waitcnt lgkmcnt(0)
	v_mfma_f32_16x16x32_bf16 v[56:59], v[148:151], v[176:179], v[56:59]
	v_mfma_f32_16x16x32_bf16 v[56:59], v[152:155], v[180:183], v[56:59]
	v_mfma_f32_16x16x32_bf16 v[40:43], v[148:151], v[184:187], v[40:43]
	v_mfma_f32_16x16x32_bf16 v[40:43], v[152:155], v[188:191], v[40:43]
	v_mfma_f32_16x16x32_bf16 v[24:27], v[148:151], v[192:195], v[24:27]
	v_mfma_f32_16x16x32_bf16 v[24:27], v[152:155], v[212:215], v[24:27]
	v_mfma_f32_16x16x32_bf16 v[60:63], v[156:159], v[168:171], v[60:63]
	v_mfma_f32_16x16x32_bf16 v[60:63], v[160:163], v[172:175], v[60:63]
	v_mfma_f32_16x16x32_bf16 v[48:51], v[156:159], v[176:179], v[48:51]
	v_mfma_f32_16x16x32_bf16 v[48:51], v[160:163], v[180:183], v[48:51]
	v_mfma_f32_16x16x32_bf16 v[32:35], v[156:159], v[184:187], v[32:35]
	v_mfma_f32_16x16x32_bf16 v[32:35], v[160:163], v[188:191], v[32:35]
	v_mfma_f32_16x16x32_bf16 v[16:19], v[156:159], v[192:195], v[16:19]
	v_mfma_f32_16x16x32_bf16 v[16:19], v[160:163], v[212:215], v[16:19]
	s_barrier
	s_setprio 0
	s_add_u32 s14, s14, 0x80080
	s_addc_u32 s15, s15, 0
	s_add_i32 s16, s16, s19
	s_mov_b32 m0, s16
	s_nop 0
	global_load_lds_dwordx4 v134, s[14:15]
	s_add_i32 m0, s16, 0x2000
	s_nop 0
	global_load_lds_dwordx4 v0, s[14:15]
	s_add_i32 s39, s39, 2
	s_add_u32 s37, s37, 0x100
	s_addc_u32 s38, s38, 0
	s_add_u32 s12, s12, 0x100
	s_addc_u32 s13, s13, 0
	s_waitcnt vmcnt(8)
	s_setprio 1
	s_barrier
	v_mfma_f32_16x16x32_bf16 v[52:55], v[216:219], v[168:171], v[52:55]
	v_mfma_f32_16x16x32_bf16 v[52:55], v[220:223], v[172:175], v[52:55]
	v_mfma_f32_16x16x32_bf16 v[36:39], v[216:219], v[176:179], v[36:39]
	v_mfma_f32_16x16x32_bf16 v[36:39], v[220:223], v[180:183], v[36:39]
	v_mfma_f32_16x16x32_bf16 v[20:23], v[216:219], v[184:187], v[20:23]
	v_mfma_f32_16x16x32_bf16 v[20:23], v[220:223], v[188:191], v[20:23]
	v_mfma_f32_16x16x32_bf16 v[8:11], v[216:219], v[192:195], v[8:11]
	v_mfma_f32_16x16x32_bf16 v[8:11], v[220:223], v[212:215], v[8:11]
	v_mfma_f32_16x16x32_bf16 v[44:47], v[224:227], v[168:171], v[44:47]
	v_mfma_f32_16x16x32_bf16 v[44:47], v[228:231], v[172:175], v[44:47]
	v_mfma_f32_16x16x32_bf16 v[28:31], v[224:227], v[176:179], v[28:31]
	v_mfma_f32_16x16x32_bf16 v[28:31], v[228:231], v[180:183], v[28:31]
	v_mfma_f32_16x16x32_bf16 v[12:15], v[224:227], v[184:187], v[12:15]
	v_mfma_f32_16x16x32_bf16 v[12:15], v[228:231], v[188:191], v[12:15]
	v_mfma_f32_16x16x32_bf16 v[4:7], v[224:227], v[192:195], v[4:7]
	v_mfma_f32_16x16x32_bf16 v[4:7], v[228:231], v[212:215], v[4:7]
	s_barrier
	s_setprio 0
	s_cmp_gt_u32 s39, 29
.LBB0_109:
	s_add_i32 s40, 0, 0x10000
	v_add_u32_e32 v246, s40, v145
	ds_read_b128 v[148:151], v246
	ds_read_b128 v[152:155], v246 offset:1024
	ds_read_b128 v[156:159], v246 offset:2048
	ds_read_b128 v[160:163], v246 offset:3072
	s_add_i32 m0, s24, 0xc000
	ds_read_b128 v[168:171], v146
	ds_read_b128 v[172:175], v146 offset:1024
	ds_read_b128 v[176:179], v146 offset:2048
	ds_read_b128 v[180:183], v146 offset:3072
	ds_read_b128 v[184:187], v146 offset:4096
	ds_read_b128 v[188:191], v146 offset:5120
	ds_read_b128 v[192:195], v146 offset:6144
	ds_read_b128 v[212:215], v146 offset:7168
	global_load_lds_dwordx4 v140, s[12:13]
	s_add_i32 m0, s24, 0xe000
	s_nop 0
	global_load_lds_dwordx4 v138, s[12:13]
	s_waitcnt lgkmcnt(6)
	s_setprio 1
	s_barrier
	v_mfma_f32_16x16x32_bf16 v[128:131], v[148:151], v[168:171], v[128:131]
	v_mfma_f32_16x16x32_bf16 v[128:131], v[152:155], v[172:175], v[128:131]
	s_waitcnt lgkmcnt(0)
	v_mfma_f32_16x16x32_bf16 v[120:123], v[148:151], v[176:179], v[120:123]
	v_mfma_f32_16x16x32_bf16 v[120:123], v[152:155], v[180:183], v[120:123]
	v_mfma_f32_16x16x32_bf16 v[104:107], v[148:151], v[184:187], v[104:107]
	v_mfma_f32_16x16x32_bf16 v[104:107], v[152:155], v[188:191], v[104:107]
	v_mfma_f32_16x16x32_bf16 v[88:91], v[148:151], v[192:195], v[88:91]
	v_mfma_f32_16x16x32_bf16 v[88:91], v[152:155], v[212:215], v[88:91]
	v_mfma_f32_16x16x32_bf16 v[124:127], v[156:159], v[168:171], v[124:127]
	v_mfma_f32_16x16x32_bf16 v[124:127], v[160:163], v[172:175], v[124:127]
	v_mfma_f32_16x16x32_bf16 v[112:115], v[156:159], v[176:179], v[112:115]
	v_mfma_f32_16x16x32_bf16 v[112:115], v[160:163], v[180:183], v[112:115]
	v_mfma_f32_16x16x32_bf16 v[96:99], v[156:159], v[184:187], v[96:99]
	v_mfma_f32_16x16x32_bf16 v[96:99], v[160:163], v[188:191], v[96:99]
	v_mfma_f32_16x16x32_bf16 v[80:83], v[156:159], v[192:195], v[80:83]
	v_mfma_f32_16x16x32_bf16 v[80:83], v[160:163], v[212:215], v[80:83]
	s_barrier
	s_setprio 0
	s_add_u32 s14, s12, 0xfff80080
	s_addc_u32 s15, s13, -1
	s_cmp_eq_u32 s39, 28
	s_cselect_b32 s17, s1, s15
	s_cselect_b32 s16, s11, s14
	s_cselect_b32 s15, s3, s38
	s_cselect_b32 s14, s36, s37
	s_add_i32 s42, 0, 0x14000
	s_add_i32 s40, s40, s19
	ds_read_b128 v[216:219], v246 offset:16384
	ds_read_b128 v[220:223], v246 offset:17408
	ds_read_b128 v[224:227], v246 offset:18432
	ds_read_b128 v[228:231], v246 offset:19456
	s_add_u32 s98, s14, 0x80
	s_addc_u32 s99, s15, 0
	s_mov_b32 m0, s40
	s_nop 0
	global_load_lds_dwordx4 v134, s[14:15]
	s_add_i32 m0, s40, 0x2000
	s_nop 0
	global_load_lds_dwordx4 v0, s[14:15]
	s_mov_b32 m0, s24
	s_add_u32 s100, s16, 0x80
	s_addc_u32 s101, s17, 0
	s_waitcnt vmcnt(10)
	s_waitcnt lgkmcnt(2)
	s_setprio 1
	s_barrier
; #define PG8_WAIT_V(n) asm volatile("s_waitcnt vmcnt(" #n ")" ::: "memory")
; #define PG8_WAIT_L(n) asm volatile("s_waitcnt lgkmcnt(" #n ")" ::: "memory")
; #define PG8_BAR __builtin_amdgcn_s_barrier()
; #define PG8_SCHED __builtin_amdgcn_sched_barrier(0)
; template <class Epi, class AddrA, class AddrB>
; __device__ __forceinline__ void gemm_phase(const Sched S, const int lda, const int ldb, const int K, const AddrA addrA,
;                                            const AddrB addrB, const Epi E) {
;     ...
;       PG8_LDB(B0, 0, 0); PG8_SCHED; PG8_LDA(At, 0, 0); PG8_STAGE(PG8_SA(1, 1), a1 + hstepA, voffA);
;       PG8_WAIT_L(8); PG8_BAR; PG8_WAIT_L(0); PG8_MMA(0, 0, At, B0); PG8_BAR; PG8_SCHED;
;       PG8_LDB(B1, 0, 1); PG8_STAGE(PG8_SB(0, 0), b2, voffB);
;       PG8_BAR; PG8_WAIT_L(0); PG8_MMA(0, 1, At, B1); PG8_BAR;
;       PG8_LDA(At, 0, 1); PG8_STAGE(PG8_SA(0, 0), a2, voffA);
;       PG8_BAR; PG8_WAIT_L(0); PG8_MMA(1, 0, At, B0); PG8_BAR; PG8_SCHED;
;       PG8_STAGE(PG8_SB(0, 1), b2 + hstepB, voffB);
;       PG8_WAIT_V(6); PG8_BAR; PG8_MMA(1, 1, At, B1); PG8_BAR;
;       PG8_LDB(B0, 1, 0); PG8_SCHED; PG8_LDA(At, 1, 0); PG8_STAGE(PG8_SA(0, 1), a2 + hstepA, voffA);
;       PG8_WAIT_L(8); PG8_BAR; PG8_WAIT_L(0); PG8_MMA(0, 0, At, B0); PG8_BAR; PG8_SCHED;
;       PG8_LDB(B1, 1, 1); PG8_STAGE(PG8_SB(1, 0), b3, voffB);
;       PG8_BAR; PG8_WAIT_L(0); PG8_MMA(0, 1, At, B1); PG8_BAR;
;       PG8_LDA(At, 1, 1); PG8_STAGE(PG8_SA(1, 0), a3, voffA);
;       PG8_BAR; PG8_WAIT_L(0); PG8_MMA(1, 0, At, B0); PG8_BAR; PG8_SCHED;
;       PG8_STAGE(PG8_SB(1, 1), b3 + hstepB, voffB);
;       PG8_WAIT_V(6); PG8_BAR; PG8_MMA(1, 1, At, B1); PG8_BAR;
	v_mfma_f32_16x16x32_bf16 v[116:119], v[216:219], v[168:171], v[116:119]
	v_mfma_f32_16x16x32_bf16 v[116:119], v[220:223], v[172:175], v[116:119]
	s_waitcnt lgkmcnt(0)
	v_mfma_f32_16x16x32_bf16 v[100:103], v[216:219], v[176:179], v[100:103]
	v_mfma_f32_16x16x32_bf16 v[100:103], v[220:223], v[180:183], v[100:103]
	v_mfma_f32_16x16x32_bf16 v[84:87], v[216:219], v[184:187], v[84:87]
	v_mfma_f32_16x16x32_bf16 v[84:87], v[220:223], v[188:191], v[84:87]
	v_mfma_f32_16x16x32_bf16 v[72:75], v[216:219], v[192:195], v[72:75]
	v_mfma_f32_16x16x32_bf16 v[72:75], v[220:223], v[212:215], v[72:75]
	v_mfma_f32_16x16x32_bf16 v[108:111], v[224:227], v[168:171], v[108:111]
	v_mfma_f32_16x16x32_bf16 v[108:111], v[228:231], v[172:175], v[108:111]
	v_mfma_f32_16x16x32_bf16 v[92:95], v[224:227], v[176:179], v[92:95]
	v_mfma_f32_16x16x32_bf16 v[92:95], v[228:231], v[180:183], v[92:95]
	v_mfma_f32_16x16x32_bf16 v[76:79], v[224:227], v[184:187], v[76:79]
	v_mfma_f32_16x16x32_bf16 v[76:79], v[228:231], v[188:191], v[76:79]
	v_mfma_f32_16x16x32_bf16 v[68:71], v[224:227], v[192:195], v[68:71]
	v_mfma_f32_16x16x32_bf16 v[68:71], v[228:231], v[212:215], v[68:71]
	s_barrier
	s_setprio 0
	ds_read_b128 v[168:171], v146 offset:16384
	ds_read_b128 v[172:175], v146 offset:17408
	ds_read_b128 v[176:179], v146 offset:18432
	ds_read_b128 v[180:183], v146 offset:19456
	ds_read_b128 v[184:187], v146 offset:20480
	ds_read_b128 v[188:191], v146 offset:21504
	ds_read_b128 v[192:195], v146 offset:22528
	ds_read_b128 v[212:215], v146 offset:23552
	global_load_lds_dwordx4 v136, s[16:17]
	s_mov_b32 m0, s25
	s_nop 0
	global_load_lds_dwordx4 v132, s[16:17]
	s_waitcnt lgkmcnt(6)
	s_setprio 1
	s_barrier
	v_mfma_f32_16x16x32_bf16 v[64:67], v[148:151], v[168:171], v[64:67]
	v_mfma_f32_16x16x32_bf16 v[64:67], v[152:155], v[172:175], v[64:67]
	s_waitcnt lgkmcnt(0)
	v_mfma_f32_16x16x32_bf16 v[56:59], v[148:151], v[176:179], v[56:59]
	v_mfma_f32_16x16x32_bf16 v[56:59], v[152:155], v[180:183], v[56:59]
	v_mfma_f32_16x16x32_bf16 v[40:43], v[148:151], v[184:187], v[40:43]
	v_mfma_f32_16x16x32_bf16 v[40:43], v[152:155], v[188:191], v[40:43]
	v_mfma_f32_16x16x32_bf16 v[24:27], v[148:151], v[192:195], v[24:27]
	v_mfma_f32_16x16x32_bf16 v[24:27], v[152:155], v[212:215], v[24:27]
	v_mfma_f32_16x16x32_bf16 v[60:63], v[156:159], v[168:171], v[60:63]
	v_mfma_f32_16x16x32_bf16 v[60:63], v[160:163], v[172:175], v[60:63]
	v_mfma_f32_16x16x32_bf16 v[48:51], v[156:159], v[176:179], v[48:51]
	v_mfma_f32_16x16x32_bf16 v[48:51], v[160:163], v[180:183], v[48:51]
	v_mfma_f32_16x16x32_bf16 v[32:35], v[156:159], v[184:187], v[32:35]
	v_mfma_f32_16x16x32_bf16 v[32:35], v[160:163], v[188:191], v[32:35]
	v_mfma_f32_16x16x32_bf16 v[16:19], v[156:159], v[192:195], v[16:19]
	v_mfma_f32_16x16x32_bf16 v[16:19], v[160:163], v[212:215], v[16:19]
	s_barrier
	s_setprio 0
	s_add_u32 s40, s14, 0x80000
	s_addc_u32 s41, s15, 0
	s_add_i32 s42, s42, s19
	s_mov_b32 m0, s42
	s_nop 0
	global_load_lds_dwordx4 v134, s[40:41]
	s_add_i32 m0, s42, 0x2000
	s_nop 0
	global_load_lds_dwordx4 v0, s[40:41]
	s_add_i32 s40, 0, 0x18000
	s_waitcnt vmcnt(8)
	s_setprio 1
	s_barrier
	v_mfma_f32_16x16x32_bf16 v[52:55], v[216:219], v[168:171], v[52:55]
	v_mfma_f32_16x16x32_bf16 v[52:55], v[220:223], v[172:175], v[52:55]
	v_mfma_f32_16x16x32_bf16 v[36:39], v[216:219], v[176:179], v[36:39]
	v_mfma_f32_16x16x32_bf16 v[36:39], v[220:223], v[180:183], v[36:39]
	v_mfma_f32_16x16x32_bf16 v[20:23], v[216:219], v[184:187], v[20:23]
	v_mfma_f32_16x16x32_bf16 v[20:23], v[220:223], v[188:191], v[20:23]
	v_mfma_f32_16x16x32_bf16 v[8:11], v[216:219], v[192:195], v[8:11]
	v_mfma_f32_16x16x32_bf16 v[8:11], v[220:223], v[212:215], v[8:11]
	v_mfma_f32_16x16x32_bf16 v[44:47], v[224:227], v[168:171], v[44:47]
	v_mfma_f32_16x16x32_bf16 v[44:47], v[228:231], v[172:175], v[44:47]
	v_mfma_f32_16x16x32_bf16 v[28:31], v[224:227], v[176:179], v[28:31]
	v_mfma_f32_16x16x32_bf16 v[28:31], v[228:231], v[180:183], v[28:31]
	v_mfma_f32_16x16x32_bf16 v[12:15], v[224:227], v[184:187], v[12:15]
	v_mfma_f32_16x16x32_bf16 v[12:15], v[228:231], v[188:191], v[12:15]
	v_mfma_f32_16x16x32_bf16 v[4:7], v[224:227], v[192:195], v[4:7]
	v_mfma_f32_16x16x32_bf16 v[4:7], v[228:231], v[212:215], v[4:7]
	s_barrier
	s_setprio 0
	ds_read_b128 v[148:151], v246 offset:32768
	ds_read_b128 v[152:155], v246 offset:33792
	ds_read_b128 v[156:159], v246 offset:34816
	ds_read_b128 v[160:163], v246 offset:35840
	s_add_u32 s16, s16, 0x80000
	s_addc_u32 s17, s17, 0
	s_mov_b32 m0, s26
	ds_read_b128 v[168:171], v146 offset:32768
	ds_read_b128 v[172:175], v146 offset:33792
	ds_read_b128 v[176:179], v146 offset:34816
	ds_read_b128 v[180:183], v146 offset:35840
	ds_read_b128 v[184:187], v146 offset:36864
	ds_read_b128 v[188:191], v146 offset:37888
	ds_read_b128 v[192:195], v146 offset:38912
	ds_read_b128 v[212:215], v146 offset:39936
	global_load_lds_dwordx4 v136, s[16:17]
	s_mov_b32 m0, s27
	s_nop 0
	global_load_lds_dwordx4 v132, s[16:17]
	s_waitcnt lgkmcnt(6)
	s_setprio 1
	s_barrier
	v_mfma_f32_16x16x32_bf16 v[128:131], v[148:151], v[168:171], v[128:131]
	v_mfma_f32_16x16x32_bf16 v[128:131], v[152:155], v[172:175], v[128:131]
	s_waitcnt lgkmcnt(0)
	v_mfma_f32_16x16x32_bf16 v[120:123], v[148:151], v[176:179], v[120:123]
	v_mfma_f32_16x16x32_bf16 v[120:123], v[152:155], v[180:183], v[120:123]
	v_mfma_f32_16x16x32_bf16 v[104:107], v[148:151], v[184:187], v[104:107]
	v_mfma_f32_16x16x32_bf16 v[104:107], v[152:155], v[188:191], v[104:107]
	v_mfma_f32_16x16x32_bf16 v[88:91], v[148:151], v[192:195], v[88:91]
	v_mfma_f32_16x16x32_bf16 v[88:91], v[152:155], v[212:215], v[88:91]
	v_mfma_f32_16x16x32_bf16 v[124:127], v[156:159], v[168:171], v[124:127]
	v_mfma_f32_16x16x32_bf16 v[124:127], v[160:163], v[172:175], v[124:127]
	v_mfma_f32_16x16x32_bf16 v[112:115], v[156:159], v[176:179], v[112:115]
	v_mfma_f32_16x16x32_bf16 v[112:115], v[160:163], v[180:183], v[112:115]
	v_mfma_f32_16x16x32_bf16 v[96:99], v[156:159], v[184:187], v[96:99]
	v_mfma_f32_16x16x32_bf16 v[96:99], v[160:163], v[188:191], v[96:99]
	v_mfma_f32_16x16x32_bf16 v[80:83], v[156:159], v[192:195], v[80:83]
	v_mfma_f32_16x16x32_bf16 v[80:83], v[160:163], v[212:215], v[80:83]
	s_barrier
; #define PG8_WAIT_V(n) asm volatile("s_waitcnt vmcnt(" #n ")" ::: "memory")
; #define PG8_WAIT_L(n) asm volatile("s_waitcnt lgkmcnt(" #n ")" ::: "memory")
; #define PG8_BAR __builtin_amdgcn_s_barrier()
; #define PG8_SCHED __builtin_amdgcn_sched_barrier(0)
; template <class Epi, class AddrA, class AddrB>
; __device__ __forceinline__ void gemm_phase(const Sched S, const int lda, const int ldb, const int K, const AddrA addrA,
;                                            const AddrB addrB, const Epi E) {
;     ...
;       PG8_LDB(B0, 0, 0); PG8_SCHED; PG8_LDA(At, 0, 0); PG8_STAGE(PG8_SA(1, 1), a1 + hstepA, voffA);
;       PG8_WAIT_L(8); PG8_BAR; PG8_WAIT_L(0); PG8_MMA(0, 0, At, B0); PG8_BAR; PG8_SCHED;
;       PG8_LDB(B1, 0, 1); PG8_STAGE(PG8_SB(0, 0), b2, voffB);
;       PG8_BAR; PG8_WAIT_L(0); PG8_MMA(0, 1, At, B1); PG8_BAR;
;       PG8_LDA(At, 0, 1); PG8_STAGE(PG8_SA(0, 0), a2, voffA);
;       PG8_BAR; PG8_WAIT_L(0); PG8_MMA(1, 0, At, B0); PG8_BAR; PG8_SCHED;
;       PG8_STAGE(PG8_SB(0, 1), b2 + hstepB, voffB);
;       PG8_WAIT_V(6); PG8_BAR; PG8_MMA(1, 1, At, B1); PG8_BAR;
;       PG8_LDB(B0, 1, 0); PG8_SCHED; PG8_LDA(At, 1, 0); PG8_STAGE(PG8_SA(0, 1), a2 + hstepA, voffA);
;       PG8_WAIT_L(8); PG8_BAR; PG8_WAIT_L(0); PG8_MMA(0, 0, At, B0); PG8_BAR; PG8_SCHED;
;       PG8_LDB(B1, 1, 1); PG8_STAGE(PG8_SB(1, 0), b3, voffB);
;       PG8_BAR; PG8_WAIT_L(0); PG8_MMA(0, 1, At, B1); PG8_BAR;
;       PG8_LDA(At, 1, 1); PG8_STAGE(PG8_SA(1, 0), a3, voffA);
;       PG8_BAR; PG8_WAIT_L(0); PG8_MMA(1, 0, At, B0); PG8_BAR; PG8_SCHED;
;       PG8_STAGE(PG8_SB(1, 1), b3 + hstepB, voffB);
;       PG8_WAIT_V(6); PG8_BAR; PG8_MMA(1, 1, At, B1); PG8_BAR;
	s_setprio 0
	s_add_i32 s16, 0, 0x1c000
	s_add_i32 s17, s40, s19
	s_mov_b32 m0, s17
	ds_read_b128 v[216:219], v246 offset:49152
	ds_read_b128 v[220:223], v246 offset:50176
	ds_read_b128 v[224:227], v246 offset:51200
	ds_read_b128 v[228:231], v246 offset:52224
	global_load_lds_dwordx4 v134, s[98:99]
	s_add_i32 m0, s17, 0x2000
	s_nop 0
	global_load_lds_dwordx4 v0, s[98:99]
	s_mov_b32 m0, s30
	s_waitcnt vmcnt(10)
	s_waitcnt lgkmcnt(2)
	s_setprio 1
	s_barrier
	v_mfma_f32_16x16x32_bf16 v[116:119], v[216:219], v[168:171], v[116:119]
	v_mfma_f32_16x16x32_bf16 v[116:119], v[220:223], v[172:175], v[116:119]
	s_waitcnt lgkmcnt(0)
	v_mfma_f32_16x16x32_bf16 v[100:103], v[216:219], v[176:179], v[100:103]
	v_mfma_f32_16x16x32_bf16 v[100:103], v[220:223], v[180:183], v[100:103]
	v_mfma_f32_16x16x32_bf16 v[84:87], v[216:219], v[184:187], v[84:87]
	v_mfma_f32_16x16x32_bf16 v[84:87], v[220:223], v[188:191], v[84:87]
	v_mfma_f32_16x16x32_bf16 v[72:75], v[216:219], v[192:195], v[72:75]
	v_mfma_f32_16x16x32_bf16 v[72:75], v[220:223], v[212:215], v[72:75]
	v_mfma_f32_16x16x32_bf16 v[108:111], v[224:227], v[168:171], v[108:111]
	v_mfma_f32_16x16x32_bf16 v[108:111], v[228:231], v[172:175], v[108:111]
	v_mfma_f32_16x16x32_bf16 v[92:95], v[224:227], v[176:179], v[92:95]
	v_mfma_f32_16x16x32_bf16 v[92:95], v[228:231], v[180:183], v[92:95]
	v_mfma_f32_16x16x32_bf16 v[76:79], v[224:227], v[184:187], v[76:79]
	v_mfma_f32_16x16x32_bf16 v[76:79], v[228:231], v[188:191], v[76:79]
	v_mfma_f32_16x16x32_bf16 v[68:71], v[224:227], v[192:195], v[68:71]
	v_mfma_f32_16x16x32_bf16 v[68:71], v[228:231], v[212:215], v[68:71]
	s_barrier
	s_setprio 0
	ds_read_b128 v[168:171], v146 offset:49152
	ds_read_b128 v[172:175], v146 offset:50176
	ds_read_b128 v[176:179], v146 offset:51200
	ds_read_b128 v[180:183], v146 offset:52224
	ds_read_b128 v[184:187], v146 offset:53248
	ds_read_b128 v[188:191], v146 offset:54272
	ds_read_b128 v[192:195], v146 offset:55296
	ds_read_b128 v[212:215], v146 offset:56320
	global_load_lds_dwordx4 v136, s[100:101]
	s_mov_b32 m0, s31
	s_nop 0
	global_load_lds_dwordx4 v132, s[100:101]
	s_waitcnt lgkmcnt(6)
	s_setprio 1
	s_barrier
	v_mfma_f32_16x16x32_bf16 v[64:67], v[148:151], v[168:171], v[64:67]
	v_mfma_f32_16x16x32_bf16 v[64:67], v[152:155], v[172:175], v[64:67]
	s_waitcnt lgkmcnt(0)
	v_mfma_f32_16x16x32_bf16 v[56:59], v[148:151], v[176:179], v[56:59]
	v_mfma_f32_16x16x32_bf16 v[56:59], v[152:155], v[180:183], v[56:59]
	v_mfma_f32_16x16x32_bf16 v[40:43], v[148:151], v[184:187], v[40:43]
	v_mfma_f32_16x16x32_bf16 v[40:43], v[152:155], v[188:191], v[40:43]
	v_mfma_f32_16x16x32_bf16 v[24:27], v[148:151], v[192:195], v[24:27]
	v_mfma_f32_16x16x32_bf16 v[24:27], v[152:155], v[212:215], v[24:27]
	v_mfma_f32_16x16x32_bf16 v[60:63], v[156:159], v[168:171], v[60:63]
	v_mfma_f32_16x16x32_bf16 v[60:63], v[160:163], v[172:175], v[60:63]
	v_mfma_f32_16x16x32_bf16 v[48:51], v[156:159], v[176:179], v[48:51]
	v_mfma_f32_16x16x32_bf16 v[48:51], v[160:163], v[180:183], v[48:51]
	v_mfma_f32_16x16x32_bf16 v[32:35], v[156:159], v[184:187], v[32:35]
	v_mfma_f32_16x16x32_bf16 v[32:35], v[160:163], v[188:191], v[32:35]
	v_mfma_f32_16x16x32_bf16 v[16:19], v[156:159], v[192:195], v[16:19]
	v_mfma_f32_16x16x32_bf16 v[16:19], v[160:163], v[212:215], v[16:19]
	s_barrier
	s_setprio 0
	s_add_u32 s14, s14, 0x80080
	s_addc_u32 s15, s15, 0
	s_add_i32 s16, s16, s19
	s_mov_b32 m0, s16
	s_nop 0
	global_load_lds_dwordx4 v134, s[14:15]
	s_add_i32 m0, s16, 0x2000
	s_nop 0
	global_load_lds_dwordx4 v0, s[14:15]
	s_add_i32 s39, s39, 2
	s_add_u32 s37, s37, 0x100
	s_addc_u32 s38, s38, 0
	s_add_u32 s12, s12, 0x100
	s_addc_u32 s13, s13, 0
	s_waitcnt vmcnt(8)
	s_setprio 1
	s_barrier
	v_mfma_f32_16x16x32_bf16 v[52:55], v[216:219], v[168:171], v[52:55]
	v_mfma_f32_16x16x32_bf16 v[52:55], v[220:223], v[172:175], v[52:55]
	v_mfma_f32_16x16x32_bf16 v[36:39], v[216:219], v[176:179], v[36:39]
	v_mfma_f32_16x16x32_bf16 v[36:39], v[220:223], v[180:183], v[36:39]
	v_mfma_f32_16x16x32_bf16 v[20:23], v[216:219], v[184:187], v[20:23]
	v_mfma_f32_16x16x32_bf16 v[20:23], v[220:223], v[188:191], v[20:23]
	v_mfma_f32_16x16x32_bf16 v[8:11], v[216:219], v[192:195], v[8:11]
	v_mfma_f32_16x16x32_bf16 v[8:11], v[220:223], v[212:215], v[8:11]
	v_mfma_f32_16x16x32_bf16 v[44:47], v[224:227], v[168:171], v[44:47]
	v_mfma_f32_16x16x32_bf16 v[44:47], v[228:231], v[172:175], v[44:47]
	v_mfma_f32_16x16x32_bf16 v[28:31], v[224:227], v[176:179], v[28:31]
	v_mfma_f32_16x16x32_bf16 v[28:31], v[228:231], v[180:183], v[28:31]
	v_mfma_f32_16x16x32_bf16 v[12:15], v[224:227], v[184:187], v[12:15]
	v_mfma_f32_16x16x32_bf16 v[12:15], v[228:231], v[188:191], v[12:15]
	v_mfma_f32_16x16x32_bf16 v[4:7], v[224:227], v[192:195], v[4:7]
	v_mfma_f32_16x16x32_bf16 v[4:7], v[228:231], v[212:215], v[4:7]
	s_barrier
;   __device__ __forceinline__ void operator()(EPI_ARGS) const {
;     bf16_t* base = proj + ((size_t)u.pn * MTOK + (size_t)(u.pm * 256 + wr * 64 + fr)) * PLD + wc * 32 + 8 * fq;
; #pragma unroll
;     for (int ai = 0; ai < 2; ++ai)
; #pragma unroll
;       for (int m = 0; m < 4; ++m) {
;         bf16_t* rowp = base + (size_t)(ai * HALF + m * 16) * PLD;
; #pragma unroll
;         for (int bj = 0; bj < 2; ++bj) {
;           const f32x4 v0 = acc[ai][bj][m][0], v1 = acc[ai][bj][m][1];
;           u32x4 o;
;           o.x = pack2(v0[0], v0[1]); o.y = pack2(v0[2], v0[3]); o.z = pack2(v1[0], v1[1]); o.w = pack2(v1[2], v1[3]);
;           *(u32x4*)(rowp + bj * HALF) = o;
;         }
;       }
;   }
	s_setprio 0
	s_cmp_gt_u32 s39, 29
	s_cbranch_scc0 .LBB0_109
	s_ashr_i32 s11, s10, 31
	v_lshl_add_u32 v142, s35, 8, v144
	s_lshl_b64 s[10:11], s[10:11], 23
	v_ashrrev_i32_e32 v143, 31, v142
	s_add_u32 s10, s28, s10
	s_addc_u32 s11, s29, s11
	v_lshlrev_b64 v[142:143], 9, v[142:143]
	v_lshl_add_u64 v[142:143], s[10:11], 0, v[142:143]
	v_lshl_add_u64 v[142:143], v[142:143], 0, s[72:73]
	v_lshl_add_u64 v[142:143], v[142:143], 0, v[2:3]
	v_cvt_pk_bf16_f32 v116, v116, v117
	v_cvt_pk_bf16_f32 v117, v118, v119
	v_cvt_pk_bf16_f32 v119, v110, v111
	v_cvt_pk_bf16_f32 v110, v112, v113
	v_add_co_u32_e32 v112, vcc, s96, v142
	s_movk_i32 s1, 0x4000
	s_nop 0
	v_addc_co_u32_e32 v113, vcc, 0, v143, vcc
	v_cvt_pk_bf16_f32 v100, v100, v101
	v_cvt_pk_bf16_f32 v101, v102, v103
	v_cvt_pk_bf16_f32 v103, v94, v95
	v_cvt_pk_bf16_f32 v94, v96, v97
	v_add_co_u32_e32 v96, vcc, s1, v142
	s_movk_i32 s1, 0x6000
	s_nop 0
	v_addc_co_u32_e32 v97, vcc, 0, v143, vcc
	v_cvt_pk_bf16_f32 v84, v84, v85
	v_cvt_pk_bf16_f32 v85, v86, v87
	v_cvt_pk_bf16_f32 v87, v78, v79
	v_cvt_pk_bf16_f32 v78, v80, v81
	v_add_co_u32_e32 v80, vcc, s1, v142
	v_cvt_pk_bf16_f32 v64, v64, v65
	v_cvt_pk_bf16_f32 v65, v66, v67
	v_cvt_pk_bf16_f32 v66, v60, v61
	s_mov_b32 s1, 0x12000
	s_nop 0
	v_addc_co_u32_e32 v81, vcc, 0, v143, vcc
	v_add_co_u32_e32 v60, vcc, s67, v142
	v_cvt_pk_bf16_f32 v52, v52, v53
	v_cvt_pk_bf16_f32 v53, v54, v55
	v_cvt_pk_bf16_f32 v55, v46, v47
	v_cvt_pk_bf16_f32 v46, v48, v49
	s_nop 1
	v_addc_co_u32_e32 v61, vcc, 0, v143, vcc
	v_add_co_u32_e32 v48, vcc, s1, v142
	s_mov_b32 s1, 0x14000
	s_nop 0
	v_addc_co_u32_e32 v49, vcc, 0, v143, vcc
	v_cvt_pk_bf16_f32 v36, v36, v37
	v_cvt_pk_bf16_f32 v37, v38, v39
	v_cvt_pk_bf16_f32 v39, v30, v31
	v_cvt_pk_bf16_f32 v30, v32, v33
	v_add_co_u32_e32 v32, vcc, s1, v142
	s_mov_b32 s1, 0x16000
	s_nop 0
	v_addc_co_u32_e32 v33, vcc, 0, v143, vcc
	v_cvt_pk_bf16_f32 v20, v20, v21
	v_cvt_pk_bf16_f32 v21, v22, v23
	v_cvt_pk_bf16_f32 v23, v14, v15
	v_cvt_pk_bf16_f32 v14, v16, v17
	v_add_co_u32_e32 v16, vcc, s1, v142
	s_mov_b32 s10, s2
	s_nop 0
	v_addc_co_u32_e32 v17, vcc, 0, v143, vcc
	s_and_b64 vcc, exec, s[4:5]
	s_mov_b32 s35, s0
	s_mov_b64 s[12:13], s[8:9]
	s_mov_b64 s[14:15], s[6:7]
	v_cvt_pk_bf16_f32 v128, v128, v129
	v_cvt_pk_bf16_f32 v129, v130, v131
	v_cvt_pk_bf16_f32 v130, v124, v125
	v_cvt_pk_bf16_f32 v131, v126, v127
	flat_store_dwordx4 v[142:143], v[128:131]
	v_cvt_pk_bf16_f32 v118, v108, v109
	flat_store_dwordx4 v[142:143], v[116:119] offset:256
	v_cvt_pk_bf16_f32 v108, v120, v121
	v_cvt_pk_bf16_f32 v109, v122, v123
	v_cvt_pk_bf16_f32 v111, v114, v115
	flat_store_dwordx4 v[112:113], v[108:111]
	v_cvt_pk_bf16_f32 v102, v92, v93
	flat_store_dwordx4 v[112:113], v[100:103] offset:256
	v_cvt_pk_bf16_f32 v92, v104, v105
	v_cvt_pk_bf16_f32 v93, v106, v107
	v_cvt_pk_bf16_f32 v95, v98, v99
	flat_store_dwordx4 v[96:97], v[92:95]
	v_cvt_pk_bf16_f32 v86, v76, v77
	flat_store_dwordx4 v[96:97], v[84:87] offset:256
	v_cvt_pk_bf16_f32 v76, v88, v89
	v_cvt_pk_bf16_f32 v77, v90, v91
	v_cvt_pk_bf16_f32 v79, v82, v83
	flat_store_dwordx4 v[80:81], v[76:79]
	v_cvt_pk_bf16_f32 v72, v72, v73
	v_cvt_pk_bf16_f32 v73, v74, v75
	v_cvt_pk_bf16_f32 v74, v68, v69
	v_cvt_pk_bf16_f32 v75, v70, v71
	flat_store_dwordx4 v[80:81], v[72:75] offset:256
	v_cvt_pk_bf16_f32 v67, v62, v63
	flat_store_dwordx4 v[60:61], v[64:67]
	v_cvt_pk_bf16_f32 v54, v44, v45
	flat_store_dwordx4 v[60:61], v[52:55] offset:256
	v_cvt_pk_bf16_f32 v44, v56, v57
	v_cvt_pk_bf16_f32 v45, v58, v59
	v_cvt_pk_bf16_f32 v47, v50, v51
	flat_store_dwordx4 v[48:49], v[44:47]
	v_cvt_pk_bf16_f32 v38, v28, v29
	flat_store_dwordx4 v[48:49], v[36:39] offset:256
	v_cvt_pk_bf16_f32 v28, v40, v41
	v_cvt_pk_bf16_f32 v29, v42, v43
	v_cvt_pk_bf16_f32 v31, v34, v35
	flat_store_dwordx4 v[32:33], v[28:31]
	v_cvt_pk_bf16_f32 v22, v12, v13
	flat_store_dwordx4 v[32:33], v[20:23] offset:256
	v_cvt_pk_bf16_f32 v12, v24, v25
	v_cvt_pk_bf16_f32 v13, v26, v27
	v_cvt_pk_bf16_f32 v15, v18, v19
	flat_store_dwordx4 v[16:17], v[12:15]
	v_cvt_pk_bf16_f32 v8, v8, v9
	v_cvt_pk_bf16_f32 v9, v10, v11
	v_cvt_pk_bf16_f32 v10, v4, v5
	v_cvt_pk_bf16_f32 v11, v6, v7
	flat_store_dwordx4 v[16:17], v[8:11] offset:256
	s_cbranch_vccz .LBB0_106
	s_waitcnt vmcnt(0)
	s_cmpk_gt_u32 s18, 0xff
	s_cbranch_scc1 .LBB0_113
	s_barrier

; #define PG8_WAIT_V(n) asm volatile("s_waitcnt vmcnt(" #n ")" ::: "memory")
; #define PG8_WAIT_L(n) asm volatile("s_waitcnt lgkmcnt(" #n ")" ::: "memory")
; #define PG8_BAR __builtin_amdgcn_s_barrier()
; #define PG8_SCHED __builtin_amdgcn_sched_barrier(0)
; template <class Epi, class AddrA, class AddrB>
; __device__ __forceinline__ void gemm_phase(const Sched S, const int lda, const int ldb, const int K, const AddrA addrA,
;                                            const AddrB addrB, const Epi E) {
;     ...
;     const bool has_next = S.next(ui + 1, nxt);
;     const char* nA = has_next ? addrA(nxt) : cA;
;     const char* nB = has_next ? addrB(nxt) : cB;
;     for (int t = 0; t < nt; t += 2) {
;       const bool last = (t == nt - 2);
;       const char* a1 = cA + (size_t)(t + 1) * kstep;
;       const char* a2 = last ? nA : cA + (size_t)(t + 2) * kstep;
;       const char* b2 = last ? nB : cB + (size_t)(t + 2) * kstep;
;       const char* a3 = a2 + kstep;
;       const char* b3 = b2 + kstep;
;       PG8_LDB(B0, 0, 0); PG8_SCHED; PG8_LDA(At, 0, 0); PG8_STAGE(PG8_SA(1, 1), a1 + hstepA, voffA);
;       PG8_WAIT_L(8); PG8_BAR; PG8_WAIT_L(0); PG8_MMA(0, 0, At, B0); PG8_BAR; PG8_SCHED;
;       PG8_LDB(B1, 0, 1); PG8_STAGE(PG8_SB(0, 0), b2, voffB);
;       PG8_BAR; PG8_WAIT_L(0); PG8_MMA(0, 1, At, B1); PG8_BAR;
;       PG8_LDA(At, 0, 1); PG8_STAGE(PG8_SA(0, 0), a2, voffA);
;       PG8_BAR; PG8_WAIT_L(0); PG8_MMA(1, 0, At, B0); PG8_BAR; PG8_SCHED;
;       PG8_STAGE(PG8_SB(0, 1), b2 + hstepB, voffB);
;       PG8_WAIT_V(6); PG8_BAR; PG8_MMA(1, 1, At, B1); PG8_BAR;
;       PG8_LDB(B0, 1, 0); PG8_SCHED; PG8_LDA(At, 1, 0); PG8_STAGE(PG8_SA(0, 1), a2 + hstepA, voffA);
;       PG8_WAIT_L(8); PG8_BAR; PG8_WAIT_L(0); PG8_MMA(0, 0, At, B0); PG8_BAR; PG8_SCHED;
;       PG8_LDB(B1, 1, 1); PG8_STAGE(PG8_SB(1, 0), b3, voffB);
;       PG8_BAR; PG8_WAIT_L(0); PG8_MMA(0, 1, At, B1); PG8_BAR;
;       PG8_LDA(At, 1, 1); PG8_STAGE(PG8_SA(1, 0), a3, voffA);
;       PG8_BAR; PG8_WAIT_L(0); PG8_MMA(1, 0, At, B0); PG8_BAR; PG8_SCHED;
;       PG8_STAGE(PG8_SB(1, 1), b3 + hstepB, voffB);
;       PG8_WAIT_V(6); PG8_BAR; PG8_MMA(1, 1, At, B1); PG8_BAR;
.LBB0_484:
	s_ashr_i32 s15, s14, 31
	s_lshl_b64 s[20:21], s[14:15], 20
	s_add_u32 s3, s25, s20
	s_addc_u32 s15, s26, s21
	s_lshl_b32 s17, s16, 8
	s_and_b32 s20, s17, 0xfffffe00
	s_ashr_i32 s21, s20, 31
	s_lshl_b64 s[20:21], s[20:21], 1
	s_add_u32 s20, s3, s20
	s_addc_u32 s21, s15, s21
	s_and_b64 s[22:23], s[10:11], exec
	s_cselect_b32 s3, s21, s7
	s_cselect_b32 s15, s20, s6
	s_ashr_i32 s17, s16, 31
	s_lshl_b64 s[22:23], s[16:17], 18
	s_add_u32 s22, s27, s22
	s_addc_u32 s23, s28, s23
	s_and_b64 s[10:11], s[10:11], exec
	s_cselect_b32 s17, s23, s5
	s_cselect_b32 s40, s22, s4
	s_add_u32 s41, s4, 0x100
	s_addc_u32 s42, s5, 0
	s_add_u32 s4, s6, 0x80080
	s_addc_u32 s5, s7, 0
	s_mov_b32 s43, -2
	s_add_i32 s44, 0, 0x10000
	v_add_u32_e32 v246, s44, v167
	ds_read_b128 v[92:95], v246
	ds_read_b128 v[100:103], v246 offset:1024
	ds_read_b128 v[132:135], v246 offset:2048
	ds_read_b128 v[144:147], v246 offset:3072
	s_add_i32 m0, s30, 0xc000
	ds_read_b128 v[148:151], v169
	ds_read_b128 v[152:155], v169 offset:1024
	ds_read_b128 v[176:179], v169 offset:2048
	ds_read_b128 v[180:183], v169 offset:3072
	ds_read_b128 v[184:187], v169 offset:4096
	ds_read_b128 v[188:191], v169 offset:5120
	ds_read_b128 v[192:195], v169 offset:6144
	ds_read_b128 v[212:215], v169 offset:7168
	global_load_lds_dwordx4 v172, s[4:5]
	s_add_i32 m0, s30, 0xe000
	s_nop 0
	global_load_lds_dwordx4 v170, s[4:5]
	s_waitcnt lgkmcnt(6)
	s_setprio 1
	s_barrier
	v_mfma_f32_16x16x32_bf16 v[140:143], v[92:95], v[148:151], 0
	v_mfma_f32_16x16x32_bf16 v[140:143], v[100:103], v[152:155], v[140:143]
	s_waitcnt lgkmcnt(0)
	v_mfma_f32_16x16x32_bf16 v[128:131], v[92:95], v[176:179], 0
	v_mfma_f32_16x16x32_bf16 v[128:131], v[100:103], v[180:183], v[128:131]
	v_mfma_f32_16x16x32_bf16 v[120:123], v[92:95], v[184:187], 0
	v_mfma_f32_16x16x32_bf16 v[120:123], v[100:103], v[188:191], v[120:123]
	v_mfma_f32_16x16x32_bf16 v[112:115], v[92:95], v[192:195], 0
	v_mfma_f32_16x16x32_bf16 v[112:115], v[100:103], v[212:215], v[112:115]
	v_mfma_f32_16x16x32_bf16 v[136:139], v[132:135], v[148:151], 0
	v_mfma_f32_16x16x32_bf16 v[136:139], v[144:147], v[152:155], v[136:139]
	v_mfma_f32_16x16x32_bf16 v[124:127], v[132:135], v[176:179], 0
	v_mfma_f32_16x16x32_bf16 v[124:127], v[144:147], v[180:183], v[124:127]
	v_mfma_f32_16x16x32_bf16 v[116:119], v[132:135], v[184:187], 0
	v_mfma_f32_16x16x32_bf16 v[116:119], v[144:147], v[188:191], v[116:119]
	v_mfma_f32_16x16x32_bf16 v[108:111], v[132:135], v[192:195], 0
	v_mfma_f32_16x16x32_bf16 v[108:111], v[144:147], v[212:215], v[108:111]
	s_barrier
	s_setprio 0
	s_add_u32 s6, s4, 0xfff80080
	s_addc_u32 s7, s5, -1
	s_cmp_eq_u32 s43, 4
	s_cselect_b32 s11, s3, s7
	s_cselect_b32 s10, s15, s6
	s_cselect_b32 s7, s17, s42
	s_cselect_b32 s6, s40, s41
	s_add_i32 s46, 0, 0x14000
	s_add_i32 s44, s44, s29
	s_add_u32 s98, s6, 0x80
	s_addc_u32 s99, s7, 0
	s_mov_b32 m0, s44
	ds_read_b128 v[216:219], v246 offset:16384
	ds_read_b128 v[220:223], v246 offset:17408
	ds_read_b128 v[224:227], v246 offset:18432
	ds_read_b128 v[228:231], v246 offset:19456
	global_load_lds_dwordx4 v158, s[6:7]
	s_add_i32 m0, s44, 0x2000
	s_nop 0
	global_load_lds_dwordx4 v0, s[6:7]
	s_mov_b32 m0, s30
	s_add_u32 s100, s10, 0x80
	s_addc_u32 s101, s11, 0
	s_waitcnt vmcnt(10)
	s_waitcnt lgkmcnt(2)
	s_setprio 1
	s_barrier
	v_mfma_f32_16x16x32_bf16 v[64:67], v[216:219], v[148:151], 0
	v_mfma_f32_16x16x32_bf16 v[64:67], v[220:223], v[152:155], v[64:67]
	s_waitcnt lgkmcnt(0)
	v_mfma_f32_16x16x32_bf16 v[56:59], v[216:219], v[176:179], 0
	v_mfma_f32_16x16x32_bf16 v[56:59], v[220:223], v[180:183], v[56:59]
	v_mfma_f32_16x16x32_bf16 v[48:51], v[216:219], v[184:187], 0
	v_mfma_f32_16x16x32_bf16 v[48:51], v[220:223], v[188:191], v[48:51]
	v_mfma_f32_16x16x32_bf16 v[40:43], v[216:219], v[192:195], 0
	v_mfma_f32_16x16x32_bf16 v[40:43], v[220:223], v[212:215], v[40:43]
	v_mfma_f32_16x16x32_bf16 v[60:63], v[224:227], v[148:151], 0
	v_mfma_f32_16x16x32_bf16 v[60:63], v[228:231], v[152:155], v[60:63]
	v_mfma_f32_16x16x32_bf16 v[52:55], v[224:227], v[176:179], 0
	v_mfma_f32_16x16x32_bf16 v[52:55], v[228:231], v[180:183], v[52:55]
	v_mfma_f32_16x16x32_bf16 v[44:47], v[224:227], v[184:187], 0
	v_mfma_f32_16x16x32_bf16 v[44:47], v[228:231], v[188:191], v[44:47]
	v_mfma_f32_16x16x32_bf16 v[36:39], v[224:227], v[192:195], 0
	v_mfma_f32_16x16x32_bf16 v[36:39], v[228:231], v[212:215], v[36:39]
	s_barrier
	s_setprio 0
	ds_read_b128 v[148:151], v169 offset:16384
	ds_read_b128 v[152:155], v169 offset:17408
	ds_read_b128 v[176:179], v169 offset:18432
	ds_read_b128 v[180:183], v169 offset:19456
	ds_read_b128 v[184:187], v169 offset:20480
	ds_read_b128 v[188:191], v169 offset:21504
	ds_read_b128 v[192:195], v169 offset:22528
	ds_read_b128 v[212:215], v169 offset:23552
	global_load_lds_dwordx4 v160, s[10:11]
	s_mov_b32 m0, s31
	s_nop 0
	global_load_lds_dwordx4 v156, s[10:11]
	s_waitcnt lgkmcnt(6)
	s_setprio 1
	s_barrier
	v_mfma_f32_16x16x32_bf16 v[104:107], v[92:95], v[148:151], 0
	v_mfma_f32_16x16x32_bf16 v[104:107], v[100:103], v[152:155], v[104:107]
	s_waitcnt lgkmcnt(0)
	v_mfma_f32_16x16x32_bf16 v[88:91], v[92:95], v[176:179], 0
	v_mfma_f32_16x16x32_bf16 v[88:91], v[100:103], v[180:183], v[88:91]
	v_mfma_f32_16x16x32_bf16 v[80:83], v[92:95], v[184:187], 0
	v_mfma_f32_16x16x32_bf16 v[80:83], v[100:103], v[188:191], v[80:83]
	v_mfma_f32_16x16x32_bf16 v[72:75], v[92:95], v[192:195], 0
	v_mfma_f32_16x16x32_bf16 v[72:75], v[100:103], v[212:215], v[72:75]
	v_mfma_f32_16x16x32_bf16 v[96:99], v[132:135], v[148:151], 0
	v_mfma_f32_16x16x32_bf16 v[96:99], v[144:147], v[152:155], v[96:99]
	v_mfma_f32_16x16x32_bf16 v[84:87], v[132:135], v[176:179], 0
	v_mfma_f32_16x16x32_bf16 v[84:87], v[144:147], v[180:183], v[84:87]
	v_mfma_f32_16x16x32_bf16 v[76:79], v[132:135], v[184:187], 0
	v_mfma_f32_16x16x32_bf16 v[76:79], v[144:147], v[188:191], v[76:79]
	v_mfma_f32_16x16x32_bf16 v[68:71], v[132:135], v[192:195], 0
	v_mfma_f32_16x16x32_bf16 v[68:71], v[144:147], v[212:215], v[68:71]
	s_barrier
; #define PG8_WAIT_V(n) asm volatile("s_waitcnt vmcnt(" #n ")" ::: "memory")
; #define PG8_WAIT_L(n) asm volatile("s_waitcnt lgkmcnt(" #n ")" ::: "memory")
; #define PG8_BAR __builtin_amdgcn_s_barrier()
; #define PG8_SCHED __builtin_amdgcn_sched_barrier(0)
; template <class Epi, class AddrA, class AddrB>
; __device__ __forceinline__ void gemm_phase(const Sched S, const int lda, const int ldb, const int K, const AddrA addrA,
;                                            const AddrB addrB, const Epi E) {
;     ...
;       PG8_LDB(B0, 0, 0); PG8_SCHED; PG8_LDA(At, 0, 0); PG8_STAGE(PG8_SA(1, 1), a1 + hstepA, voffA);
;       PG8_WAIT_L(8); PG8_BAR; PG8_WAIT_L(0); PG8_MMA(0, 0, At, B0); PG8_BAR; PG8_SCHED;
;       PG8_LDB(B1, 0, 1); PG8_STAGE(PG8_SB(0, 0), b2, voffB);
;       PG8_BAR; PG8_WAIT_L(0); PG8_MMA(0, 1, At, B1); PG8_BAR;
;       PG8_LDA(At, 0, 1); PG8_STAGE(PG8_SA(0, 0), a2, voffA);
;       PG8_BAR; PG8_WAIT_L(0); PG8_MMA(1, 0, At, B0); PG8_BAR; PG8_SCHED;
;       PG8_STAGE(PG8_SB(0, 1), b2 + hstepB, voffB);
;       PG8_WAIT_V(6); PG8_BAR; PG8_MMA(1, 1, At, B1); PG8_BAR;
;       PG8_LDB(B0, 1, 0); PG8_SCHED; PG8_LDA(At, 1, 0); PG8_STAGE(PG8_SA(0, 1), a2 + hstepA, voffA);
;       PG8_WAIT_L(8); PG8_BAR; PG8_WAIT_L(0); PG8_MMA(0, 0, At, B0); PG8_BAR; PG8_SCHED;
;       PG8_LDB(B1, 1, 1); PG8_STAGE(PG8_SB(1, 0), b3, voffB);
;       PG8_BAR; PG8_WAIT_L(0); PG8_MMA(0, 1, At, B1); PG8_BAR;
;       PG8_LDA(At, 1, 1); PG8_STAGE(PG8_SA(1, 0), a3, voffA);
;       PG8_BAR; PG8_WAIT_L(0); PG8_MMA(1, 0, At, B0); PG8_BAR; PG8_SCHED;
;       PG8_STAGE(PG8_SB(1, 1), b3 + hstepB, voffB);
;       PG8_WAIT_V(6); PG8_BAR; PG8_MMA(1, 1, At, B1); PG8_BAR;
	s_setprio 0
	s_add_u32 s44, s6, 0x20000
	s_addc_u32 s45, s7, 0
	s_add_i32 s46, s46, s29
	s_mov_b32 m0, s46
	s_nop 0
	global_load_lds_dwordx4 v158, s[44:45]
	s_add_i32 m0, s46, 0x2000
	s_nop 0
	global_load_lds_dwordx4 v0, s[44:45]
	s_add_i32 s44, 0, 0x18000
	s_waitcnt vmcnt(8)
	s_setprio 1
	s_barrier
	v_mfma_f32_16x16x32_bf16 v[32:35], v[216:219], v[148:151], 0
	v_mfma_f32_16x16x32_bf16 v[32:35], v[220:223], v[152:155], v[32:35]
	v_mfma_f32_16x16x32_bf16 v[24:27], v[216:219], v[176:179], 0
	v_mfma_f32_16x16x32_bf16 v[24:27], v[220:223], v[180:183], v[24:27]
	v_mfma_f32_16x16x32_bf16 v[16:19], v[216:219], v[184:187], 0
	v_mfma_f32_16x16x32_bf16 v[16:19], v[220:223], v[188:191], v[16:19]
	v_mfma_f32_16x16x32_bf16 v[8:11], v[216:219], v[192:195], 0
	v_mfma_f32_16x16x32_bf16 v[8:11], v[220:223], v[212:215], v[8:11]
	v_mfma_f32_16x16x32_bf16 v[28:31], v[224:227], v[148:151], 0
	v_mfma_f32_16x16x32_bf16 v[28:31], v[228:231], v[152:155], v[28:31]
	v_mfma_f32_16x16x32_bf16 v[20:23], v[224:227], v[176:179], 0
	v_mfma_f32_16x16x32_bf16 v[20:23], v[228:231], v[180:183], v[20:23]
	v_mfma_f32_16x16x32_bf16 v[12:15], v[224:227], v[184:187], 0
	v_mfma_f32_16x16x32_bf16 v[12:15], v[228:231], v[188:191], v[12:15]
	v_mfma_f32_16x16x32_bf16 v[4:7], v[224:227], v[192:195], 0
	v_mfma_f32_16x16x32_bf16 v[4:7], v[228:231], v[212:215], v[4:7]
	s_barrier
	s_setprio 0
	ds_read_b128 v[92:95], v246 offset:32768
	ds_read_b128 v[100:103], v246 offset:33792
	ds_read_b128 v[132:135], v246 offset:34816
	ds_read_b128 v[144:147], v246 offset:35840
	s_add_u32 s10, s10, 0x80000
	s_addc_u32 s11, s11, 0
	s_mov_b32 m0, s34
	ds_read_b128 v[148:151], v169 offset:32768
	ds_read_b128 v[152:155], v169 offset:33792
	ds_read_b128 v[176:179], v169 offset:34816
	ds_read_b128 v[180:183], v169 offset:35840
	ds_read_b128 v[184:187], v169 offset:36864
	ds_read_b128 v[188:191], v169 offset:37888
	ds_read_b128 v[192:195], v169 offset:38912
	ds_read_b128 v[212:215], v169 offset:39936
	global_load_lds_dwordx4 v160, s[10:11]
	s_mov_b32 m0, s35
	s_nop 0
	global_load_lds_dwordx4 v156, s[10:11]
	s_waitcnt lgkmcnt(6)
	s_setprio 1
	s_barrier
	v_mfma_f32_16x16x32_bf16 v[140:143], v[92:95], v[148:151], v[140:143]
	v_mfma_f32_16x16x32_bf16 v[140:143], v[100:103], v[152:155], v[140:143]
	s_waitcnt lgkmcnt(0)
	v_mfma_f32_16x16x32_bf16 v[128:131], v[92:95], v[176:179], v[128:131]
	v_mfma_f32_16x16x32_bf16 v[128:131], v[100:103], v[180:183], v[128:131]
	v_mfma_f32_16x16x32_bf16 v[120:123], v[92:95], v[184:187], v[120:123]
	v_mfma_f32_16x16x32_bf16 v[120:123], v[100:103], v[188:191], v[120:123]
	v_mfma_f32_16x16x32_bf16 v[112:115], v[92:95], v[192:195], v[112:115]
	v_mfma_f32_16x16x32_bf16 v[112:115], v[100:103], v[212:215], v[112:115]
	v_mfma_f32_16x16x32_bf16 v[136:139], v[132:135], v[148:151], v[136:139]
	v_mfma_f32_16x16x32_bf16 v[136:139], v[144:147], v[152:155], v[136:139]
	v_mfma_f32_16x16x32_bf16 v[124:127], v[132:135], v[176:179], v[124:127]
	v_mfma_f32_16x16x32_bf16 v[124:127], v[144:147], v[180:183], v[124:127]
	v_mfma_f32_16x16x32_bf16 v[116:119], v[132:135], v[184:187], v[116:119]
	v_mfma_f32_16x16x32_bf16 v[116:119], v[144:147], v[188:191], v[116:119]
	v_mfma_f32_16x16x32_bf16 v[108:111], v[132:135], v[192:195], v[108:111]
	v_mfma_f32_16x16x32_bf16 v[108:111], v[144:147], v[212:215], v[108:111]
	s_barrier
	s_setprio 0
	s_add_i32 s10, 0, 0x1c000
	s_add_i32 s11, s44, s29
	s_mov_b32 m0, s11
	ds_read_b128 v[216:219], v246 offset:49152
	ds_read_b128 v[220:223], v246 offset:50176
	ds_read_b128 v[224:227], v246 offset:51200
	ds_read_b128 v[228:231], v246 offset:52224
	global_load_lds_dwordx4 v158, s[98:99]
	s_add_i32 m0, s11, 0x2000
	s_nop 0
	global_load_lds_dwordx4 v0, s[98:99]
	s_mov_b32 m0, s37
	s_waitcnt vmcnt(10)
	s_waitcnt lgkmcnt(2)
	s_setprio 1
	s_barrier
	v_mfma_f32_16x16x32_bf16 v[64:67], v[216:219], v[148:151], v[64:67]
	v_mfma_f32_16x16x32_bf16 v[64:67], v[220:223], v[152:155], v[64:67]
	s_waitcnt lgkmcnt(0)
	v_mfma_f32_16x16x32_bf16 v[56:59], v[216:219], v[176:179], v[56:59]
	v_mfma_f32_16x16x32_bf16 v[56:59], v[220:223], v[180:183], v[56:59]
	v_mfma_f32_16x16x32_bf16 v[48:51], v[216:219], v[184:187], v[48:51]
	v_mfma_f32_16x16x32_bf16 v[48:51], v[220:223], v[188:191], v[48:51]
	v_mfma_f32_16x16x32_bf16 v[40:43], v[216:219], v[192:195], v[40:43]
	v_mfma_f32_16x16x32_bf16 v[40:43], v[220:223], v[212:215], v[40:43]
	v_mfma_f32_16x16x32_bf16 v[60:63], v[224:227], v[148:151], v[60:63]
	v_mfma_f32_16x16x32_bf16 v[60:63], v[228:231], v[152:155], v[60:63]
	v_mfma_f32_16x16x32_bf16 v[52:55], v[224:227], v[176:179], v[52:55]
	v_mfma_f32_16x16x32_bf16 v[52:55], v[228:231], v[180:183], v[52:55]
	v_mfma_f32_16x16x32_bf16 v[44:47], v[224:227], v[184:187], v[44:47]
	v_mfma_f32_16x16x32_bf16 v[44:47], v[228:231], v[188:191], v[44:47]
	v_mfma_f32_16x16x32_bf16 v[36:39], v[224:227], v[192:195], v[36:39]
	v_mfma_f32_16x16x32_bf16 v[36:39], v[228:231], v[212:215], v[36:39]
	s_barrier
	s_setprio 0
	ds_read_b128 v[148:151], v169 offset:49152
	ds_read_b128 v[152:155], v169 offset:50176
	ds_read_b128 v[176:179], v169 offset:51200
	ds_read_b128 v[180:183], v169 offset:52224
	ds_read_b128 v[184:187], v169 offset:53248
	ds_read_b128 v[188:191], v169 offset:54272
	ds_read_b128 v[192:195], v169 offset:55296
	ds_read_b128 v[212:215], v169 offset:56320
	global_load_lds_dwordx4 v160, s[100:101]
	s_mov_b32 m0, s38
	s_nop 0
	global_load_lds_dwordx4 v156, s[100:101]
	s_waitcnt lgkmcnt(6)
	s_setprio 1
	s_barrier
; #define PG8_WAIT_V(n) asm volatile("s_waitcnt vmcnt(" #n ")" ::: "memory")
; #define PG8_WAIT_L(n) asm volatile("s_waitcnt lgkmcnt(" #n ")" ::: "memory")
; #define PG8_BAR __builtin_amdgcn_s_barrier()
; #define PG8_SCHED __builtin_amdgcn_sched_barrier(0)
; template <class Epi, class AddrA, class AddrB>
; __device__ __forceinline__ void gemm_phase(const Sched S, const int lda, const int ldb, const int K, const AddrA addrA,
;                                            const AddrB addrB, const Epi E) {
;     ...
;     for (int t = 0; t < nt; t += 2) {
;       const bool last = (t == nt - 2);
;       const char* a1 = cA + (size_t)(t + 1) * kstep;
;       const char* a2 = last ? nA : cA + (size_t)(t + 2) * kstep;
;       const char* b2 = last ? nB : cB + (size_t)(t + 2) * kstep;
;       const char* a3 = a2 + kstep;
;       const char* b3 = b2 + kstep;
;       PG8_LDB(B0, 0, 0); PG8_SCHED; PG8_LDA(At, 0, 0); PG8_STAGE(PG8_SA(1, 1), a1 + hstepA, voffA);
;       PG8_WAIT_L(8); PG8_BAR; PG8_WAIT_L(0); PG8_MMA(0, 0, At, B0); PG8_BAR; PG8_SCHED;
;       PG8_LDB(B1, 0, 1); PG8_STAGE(PG8_SB(0, 0), b2, voffB);
;       PG8_BAR; PG8_WAIT_L(0); PG8_MMA(0, 1, At, B1); PG8_BAR;
;       PG8_LDA(At, 0, 1); PG8_STAGE(PG8_SA(0, 0), a2, voffA);
;       PG8_BAR; PG8_WAIT_L(0); PG8_MMA(1, 0, At, B0); PG8_BAR; PG8_SCHED;
;       PG8_STAGE(PG8_SB(0, 1), b2 + hstepB, voffB);
;       PG8_WAIT_V(6); PG8_BAR; PG8_MMA(1, 1, At, B1); PG8_BAR;
;       PG8_LDB(B0, 1, 0); PG8_SCHED; PG8_LDA(At, 1, 0); PG8_STAGE(PG8_SA(0, 1), a2 + hstepA, voffA);
;       PG8_WAIT_L(8); PG8_BAR; PG8_WAIT_L(0); PG8_MMA(0, 0, At, B0); PG8_BAR; PG8_SCHED;
;       PG8_LDB(B1, 1, 1); PG8_STAGE(PG8_SB(1, 0), b3, voffB);
;       PG8_BAR; PG8_WAIT_L(0); PG8_MMA(0, 1, At, B1); PG8_BAR;
;       PG8_LDA(At, 1, 1); PG8_STAGE(PG8_SA(1, 0), a3, voffA);
;       PG8_BAR; PG8_WAIT_L(0); PG8_MMA(1, 0, At, B0); PG8_BAR; PG8_SCHED;
;       PG8_STAGE(PG8_SB(1, 1), b3 + hstepB, voffB);
;       PG8_WAIT_V(6); PG8_BAR; PG8_MMA(1, 1, At, B1); PG8_BAR;
	v_mfma_f32_16x16x32_bf16 v[104:107], v[92:95], v[148:151], v[104:107]
	v_mfma_f32_16x16x32_bf16 v[104:107], v[100:103], v[152:155], v[104:107]
	s_waitcnt lgkmcnt(0)
	v_mfma_f32_16x16x32_bf16 v[88:91], v[92:95], v[176:179], v[88:91]
	v_mfma_f32_16x16x32_bf16 v[88:91], v[100:103], v[180:183], v[88:91]
	v_mfma_f32_16x16x32_bf16 v[80:83], v[92:95], v[184:187], v[80:83]
	v_mfma_f32_16x16x32_bf16 v[80:83], v[100:103], v[188:191], v[80:83]
	v_mfma_f32_16x16x32_bf16 v[72:75], v[92:95], v[192:195], v[72:75]
	v_mfma_f32_16x16x32_bf16 v[72:75], v[100:103], v[212:215], v[72:75]
	v_mfma_f32_16x16x32_bf16 v[96:99], v[132:135], v[148:151], v[96:99]
	v_mfma_f32_16x16x32_bf16 v[96:99], v[144:147], v[152:155], v[96:99]
	v_mfma_f32_16x16x32_bf16 v[84:87], v[132:135], v[176:179], v[84:87]
	v_mfma_f32_16x16x32_bf16 v[84:87], v[144:147], v[180:183], v[84:87]
	v_mfma_f32_16x16x32_bf16 v[76:79], v[132:135], v[184:187], v[76:79]
	v_mfma_f32_16x16x32_bf16 v[76:79], v[144:147], v[188:191], v[76:79]
	v_mfma_f32_16x16x32_bf16 v[68:71], v[132:135], v[192:195], v[68:71]
	v_mfma_f32_16x16x32_bf16 v[68:71], v[144:147], v[212:215], v[68:71]
	s_barrier
	s_setprio 0
	s_add_u32 s6, s6, 0x20080
	s_addc_u32 s7, s7, 0
	s_add_i32 s10, s10, s29
	s_mov_b32 m0, s10
	s_nop 0
	global_load_lds_dwordx4 v158, s[6:7]
	s_add_i32 m0, s10, 0x2000
	s_nop 0
	global_load_lds_dwordx4 v0, s[6:7]
	s_add_i32 s43, s43, 2
	s_add_u32 s41, s41, 0x100
	s_addc_u32 s42, s42, 0
	s_add_u32 s4, s4, 0x100
	s_addc_u32 s5, s5, 0
	s_waitcnt vmcnt(8)
	s_setprio 1
	s_barrier
	v_mfma_f32_16x16x32_bf16 v[32:35], v[216:219], v[148:151], v[32:35]
	v_mfma_f32_16x16x32_bf16 v[32:35], v[220:223], v[152:155], v[32:35]
	v_mfma_f32_16x16x32_bf16 v[24:27], v[216:219], v[176:179], v[24:27]
	v_mfma_f32_16x16x32_bf16 v[24:27], v[220:223], v[180:183], v[24:27]
	v_mfma_f32_16x16x32_bf16 v[16:19], v[216:219], v[184:187], v[16:19]
	v_mfma_f32_16x16x32_bf16 v[16:19], v[220:223], v[188:191], v[16:19]
	v_mfma_f32_16x16x32_bf16 v[8:11], v[216:219], v[192:195], v[8:11]
	v_mfma_f32_16x16x32_bf16 v[8:11], v[220:223], v[212:215], v[8:11]
	v_mfma_f32_16x16x32_bf16 v[28:31], v[224:227], v[148:151], v[28:31]
	v_mfma_f32_16x16x32_bf16 v[28:31], v[228:231], v[152:155], v[28:31]
	v_mfma_f32_16x16x32_bf16 v[20:23], v[224:227], v[176:179], v[20:23]
	v_mfma_f32_16x16x32_bf16 v[20:23], v[228:231], v[180:183], v[20:23]
	v_mfma_f32_16x16x32_bf16 v[12:15], v[224:227], v[184:187], v[12:15]
	v_mfma_f32_16x16x32_bf16 v[12:15], v[228:231], v[188:191], v[12:15]
	v_mfma_f32_16x16x32_bf16 v[4:7], v[224:227], v[192:195], v[4:7]
	v_mfma_f32_16x16x32_bf16 v[4:7], v[228:231], v[212:215], v[4:7]
	s_barrier
	s_setprio 0
	s_cmp_gt_u32 s43, 5
.LBB0_485:
	s_add_i32 s44, 0, 0x10000
	v_add_u32_e32 v246, s44, v167
	ds_read_b128 v[92:95], v246
	ds_read_b128 v[100:103], v246 offset:1024
	ds_read_b128 v[132:135], v246 offset:2048
	ds_read_b128 v[144:147], v246 offset:3072
	s_add_i32 m0, s30, 0xc000
	ds_read_b128 v[148:151], v169
	ds_read_b128 v[152:155], v169 offset:1024
	ds_read_b128 v[176:179], v169 offset:2048
	ds_read_b128 v[180:183], v169 offset:3072
	ds_read_b128 v[184:187], v169 offset:4096
	ds_read_b128 v[188:191], v169 offset:5120
	ds_read_b128 v[192:195], v169 offset:6144
	ds_read_b128 v[212:215], v169 offset:7168
	global_load_lds_dwordx4 v172, s[4:5]
	s_add_i32 m0, s30, 0xe000
	s_nop 0
	global_load_lds_dwordx4 v170, s[4:5]
	s_waitcnt lgkmcnt(6)
	s_setprio 1
	s_barrier
	v_mfma_f32_16x16x32_bf16 v[140:143], v[92:95], v[148:151], v[140:143]
	v_mfma_f32_16x16x32_bf16 v[140:143], v[100:103], v[152:155], v[140:143]
	s_waitcnt lgkmcnt(0)
	v_mfma_f32_16x16x32_bf16 v[128:131], v[92:95], v[176:179], v[128:131]
	v_mfma_f32_16x16x32_bf16 v[128:131], v[100:103], v[180:183], v[128:131]
	v_mfma_f32_16x16x32_bf16 v[120:123], v[92:95], v[184:187], v[120:123]
	v_mfma_f32_16x16x32_bf16 v[120:123], v[100:103], v[188:191], v[120:123]
	v_mfma_f32_16x16x32_bf16 v[112:115], v[92:95], v[192:195], v[112:115]
	v_mfma_f32_16x16x32_bf16 v[112:115], v[100:103], v[212:215], v[112:115]
	v_mfma_f32_16x16x32_bf16 v[136:139], v[132:135], v[148:151], v[136:139]
	v_mfma_f32_16x16x32_bf16 v[136:139], v[144:147], v[152:155], v[136:139]
	v_mfma_f32_16x16x32_bf16 v[124:127], v[132:135], v[176:179], v[124:127]
	v_mfma_f32_16x16x32_bf16 v[124:127], v[144:147], v[180:183], v[124:127]
	v_mfma_f32_16x16x32_bf16 v[116:119], v[132:135], v[184:187], v[116:119]
	v_mfma_f32_16x16x32_bf16 v[116:119], v[144:147], v[188:191], v[116:119]
	v_mfma_f32_16x16x32_bf16 v[108:111], v[132:135], v[192:195], v[108:111]
	v_mfma_f32_16x16x32_bf16 v[108:111], v[144:147], v[212:215], v[108:111]
	s_barrier
	s_setprio 0
	s_add_u32 s6, s4, 0xfff80080
	s_addc_u32 s7, s5, -1
	s_cmp_eq_u32 s43, 4
	s_cselect_b32 s11, s3, s7
	s_cselect_b32 s10, s15, s6
	s_cselect_b32 s7, s17, s42
	s_cselect_b32 s6, s40, s41
	s_add_i32 s46, 0, 0x14000
	s_add_i32 s44, s44, s29
	s_add_u32 s98, s6, 0x80
	s_addc_u32 s99, s7, 0
	s_mov_b32 m0, s44
	ds_read_b128 v[216:219], v246 offset:16384
	ds_read_b128 v[220:223], v246 offset:17408
	ds_read_b128 v[224:227], v246 offset:18432
	ds_read_b128 v[228:231], v246 offset:19456
	global_load_lds_dwordx4 v158, s[6:7]
	s_add_i32 m0, s44, 0x2000
	s_nop 0
	global_load_lds_dwordx4 v0, s[6:7]
	s_mov_b32 m0, s30
	s_add_u32 s100, s10, 0x80
	s_addc_u32 s101, s11, 0
	s_waitcnt vmcnt(10)
	s_waitcnt lgkmcnt(2)
	s_setprio 1
	s_barrier
; #define PG8_WAIT_V(n) asm volatile("s_waitcnt vmcnt(" #n ")" ::: "memory")
; #define PG8_WAIT_L(n) asm volatile("s_waitcnt lgkmcnt(" #n ")" ::: "memory")
; #define PG8_BAR __builtin_amdgcn_s_barrier()
; #define PG8_SCHED __builtin_amdgcn_sched_barrier(0)
; template <class Epi, class AddrA, class AddrB>
; __device__ __forceinline__ void gemm_phase(const Sched S, const int lda, const int ldb, const int K, const AddrA addrA,
;                                            const AddrB addrB, const Epi E) {
;     ...
;       PG8_LDB(B0, 0, 0); PG8_SCHED; PG8_LDA(At, 0, 0); PG8_STAGE(PG8_SA(1, 1), a1 + hstepA, voffA);
;       PG8_WAIT_L(8); PG8_BAR; PG8_WAIT_L(0); PG8_MMA(0, 0, At, B0); PG8_BAR; PG8_SCHED;
;       PG8_LDB(B1, 0, 1); PG8_STAGE(PG8_SB(0, 0), b2, voffB);
;       PG8_BAR; PG8_WAIT_L(0); PG8_MMA(0, 1, At, B1); PG8_BAR;
;       PG8_LDA(At, 0, 1); PG8_STAGE(PG8_SA(0, 0), a2, voffA);
;       PG8_BAR; PG8_WAIT_L(0); PG8_MMA(1, 0, At, B0); PG8_BAR; PG8_SCHED;
;       PG8_STAGE(PG8_SB(0, 1), b2 + hstepB, voffB);
;       PG8_WAIT_V(6); PG8_BAR; PG8_MMA(1, 1, At, B1); PG8_BAR;
;       PG8_LDB(B0, 1, 0); PG8_SCHED; PG8_LDA(At, 1, 0); PG8_STAGE(PG8_SA(0, 1), a2 + hstepA, voffA);
;       PG8_WAIT_L(8); PG8_BAR; PG8_WAIT_L(0); PG8_MMA(0, 0, At, B0); PG8_BAR; PG8_SCHED;
;       PG8_LDB(B1, 1, 1); PG8_STAGE(PG8_SB(1, 0), b3, voffB);
;       PG8_BAR; PG8_WAIT_L(0); PG8_MMA(0, 1, At, B1); PG8_BAR;
;       PG8_LDA(At, 1, 1); PG8_STAGE(PG8_SA(1, 0), a3, voffA);
;       PG8_BAR; PG8_WAIT_L(0); PG8_MMA(1, 0, At, B0); PG8_BAR; PG8_SCHED;
;       PG8_STAGE(PG8_SB(1, 1), b3 + hstepB, voffB);
;       PG8_WAIT_V(6); PG8_BAR; PG8_MMA(1, 1, At, B1); PG8_BAR;
	v_mfma_f32_16x16x32_bf16 v[64:67], v[216:219], v[148:151], v[64:67]
	v_mfma_f32_16x16x32_bf16 v[64:67], v[220:223], v[152:155], v[64:67]
	s_waitcnt lgkmcnt(0)
	v_mfma_f32_16x16x32_bf16 v[56:59], v[216:219], v[176:179], v[56:59]
	v_mfma_f32_16x16x32_bf16 v[56:59], v[220:223], v[180:183], v[56:59]
	v_mfma_f32_16x16x32_bf16 v[48:51], v[216:219], v[184:187], v[48:51]
	v_mfma_f32_16x16x32_bf16 v[48:51], v[220:223], v[188:191], v[48:51]
	v_mfma_f32_16x16x32_bf16 v[40:43], v[216:219], v[192:195], v[40:43]
	v_mfma_f32_16x16x32_bf16 v[40:43], v[220:223], v[212:215], v[40:43]
	v_mfma_f32_16x16x32_bf16 v[60:63], v[224:227], v[148:151], v[60:63]
	v_mfma_f32_16x16x32_bf16 v[60:63], v[228:231], v[152:155], v[60:63]
	v_mfma_f32_16x16x32_bf16 v[52:55], v[224:227], v[176:179], v[52:55]
	v_mfma_f32_16x16x32_bf16 v[52:55], v[228:231], v[180:183], v[52:55]
	v_mfma_f32_16x16x32_bf16 v[44:47], v[224:227], v[184:187], v[44:47]
	v_mfma_f32_16x16x32_bf16 v[44:47], v[228:231], v[188:191], v[44:47]
	v_mfma_f32_16x16x32_bf16 v[36:39], v[224:227], v[192:195], v[36:39]
	v_mfma_f32_16x16x32_bf16 v[36:39], v[228:231], v[212:215], v[36:39]
	s_barrier
	s_setprio 0
	ds_read_b128 v[148:151], v169 offset:16384
	ds_read_b128 v[152:155], v169 offset:17408
	ds_read_b128 v[176:179], v169 offset:18432
	ds_read_b128 v[180:183], v169 offset:19456
	ds_read_b128 v[184:187], v169 offset:20480
	ds_read_b128 v[188:191], v169 offset:21504
	ds_read_b128 v[192:195], v169 offset:22528
	ds_read_b128 v[212:215], v169 offset:23552
	global_load_lds_dwordx4 v160, s[10:11]
	s_mov_b32 m0, s31
	s_nop 0
	global_load_lds_dwordx4 v156, s[10:11]
	s_waitcnt lgkmcnt(6)
	s_setprio 1
	s_barrier
	v_mfma_f32_16x16x32_bf16 v[104:107], v[92:95], v[148:151], v[104:107]
	v_mfma_f32_16x16x32_bf16 v[104:107], v[100:103], v[152:155], v[104:107]
	s_waitcnt lgkmcnt(0)
	v_mfma_f32_16x16x32_bf16 v[88:91], v[92:95], v[176:179], v[88:91]
	v_mfma_f32_16x16x32_bf16 v[88:91], v[100:103], v[180:183], v[88:91]
	v_mfma_f32_16x16x32_bf16 v[80:83], v[92:95], v[184:187], v[80:83]
	v_mfma_f32_16x16x32_bf16 v[80:83], v[100:103], v[188:191], v[80:83]
	v_mfma_f32_16x16x32_bf16 v[72:75], v[92:95], v[192:195], v[72:75]
	v_mfma_f32_16x16x32_bf16 v[72:75], v[100:103], v[212:215], v[72:75]
	v_mfma_f32_16x16x32_bf16 v[96:99], v[132:135], v[148:151], v[96:99]
	v_mfma_f32_16x16x32_bf16 v[96:99], v[144:147], v[152:155], v[96:99]
	v_mfma_f32_16x16x32_bf16 v[84:87], v[132:135], v[176:179], v[84:87]
	v_mfma_f32_16x16x32_bf16 v[84:87], v[144:147], v[180:183], v[84:87]
	v_mfma_f32_16x16x32_bf16 v[76:79], v[132:135], v[184:187], v[76:79]
	v_mfma_f32_16x16x32_bf16 v[76:79], v[144:147], v[188:191], v[76:79]
	v_mfma_f32_16x16x32_bf16 v[68:71], v[132:135], v[192:195], v[68:71]
	v_mfma_f32_16x16x32_bf16 v[68:71], v[144:147], v[212:215], v[68:71]
	s_barrier
	s_setprio 0
	s_add_u32 s44, s6, 0x20000
	s_addc_u32 s45, s7, 0
	s_add_i32 s46, s46, s29
	s_mov_b32 m0, s46
	s_nop 0
	global_load_lds_dwordx4 v158, s[44:45]
	s_add_i32 m0, s46, 0x2000
	s_nop 0
	global_load_lds_dwordx4 v0, s[44:45]
	s_add_i32 s44, 0, 0x18000
	s_waitcnt vmcnt(8)
	s_setprio 1
	s_barrier
	v_mfma_f32_16x16x32_bf16 v[32:35], v[216:219], v[148:151], v[32:35]
	v_mfma_f32_16x16x32_bf16 v[32:35], v[220:223], v[152:155], v[32:35]
	v_mfma_f32_16x16x32_bf16 v[24:27], v[216:219], v[176:179], v[24:27]
	v_mfma_f32_16x16x32_bf16 v[24:27], v[220:223], v[180:183], v[24:27]
	v_mfma_f32_16x16x32_bf16 v[16:19], v[216:219], v[184:187], v[16:19]
	v_mfma_f32_16x16x32_bf16 v[16:19], v[220:223], v[188:191], v[16:19]
	v_mfma_f32_16x16x32_bf16 v[8:11], v[216:219], v[192:195], v[8:11]
	v_mfma_f32_16x16x32_bf16 v[8:11], v[220:223], v[212:215], v[8:11]
	v_mfma_f32_16x16x32_bf16 v[28:31], v[224:227], v[148:151], v[28:31]
	v_mfma_f32_16x16x32_bf16 v[28:31], v[228:231], v[152:155], v[28:31]
	v_mfma_f32_16x16x32_bf16 v[20:23], v[224:227], v[176:179], v[20:23]
	v_mfma_f32_16x16x32_bf16 v[20:23], v[228:231], v[180:183], v[20:23]
	v_mfma_f32_16x16x32_bf16 v[12:15], v[224:227], v[184:187], v[12:15]
	v_mfma_f32_16x16x32_bf16 v[12:15], v[228:231], v[188:191], v[12:15]
	v_mfma_f32_16x16x32_bf16 v[4:7], v[224:227], v[192:195], v[4:7]
	v_mfma_f32_16x16x32_bf16 v[4:7], v[228:231], v[212:215], v[4:7]
	s_barrier
	s_setprio 0
	ds_read_b128 v[92:95], v246 offset:32768
	ds_read_b128 v[100:103], v246 offset:33792
	ds_read_b128 v[132:135], v246 offset:34816
	ds_read_b128 v[144:147], v246 offset:35840
	s_add_u32 s10, s10, 0x80000
	s_addc_u32 s11, s11, 0
	s_mov_b32 m0, s34
	ds_read_b128 v[148:151], v169 offset:32768
	ds_read_b128 v[152:155], v169 offset:33792
	ds_read_b128 v[176:179], v169 offset:34816
	ds_read_b128 v[180:183], v169 offset:35840
	ds_read_b128 v[184:187], v169 offset:36864
	ds_read_b128 v[188:191], v169 offset:37888
	ds_read_b128 v[192:195], v169 offset:38912
	ds_read_b128 v[212:215], v169 offset:39936
	global_load_lds_dwordx4 v160, s[10:11]
	s_mov_b32 m0, s35
	s_nop 0
	global_load_lds_dwordx4 v156, s[10:11]
	s_waitcnt lgkmcnt(6)
	s_setprio 1
	s_barrier
	v_mfma_f32_16x16x32_bf16 v[140:143], v[92:95], v[148:151], v[140:143]
	v_mfma_f32_16x16x32_bf16 v[140:143], v[100:103], v[152:155], v[140:143]
	s_waitcnt lgkmcnt(0)
	v_mfma_f32_16x16x32_bf16 v[128:131], v[92:95], v[176:179], v[128:131]
	v_mfma_f32_16x16x32_bf16 v[128:131], v[100:103], v[180:183], v[128:131]
	v_mfma_f32_16x16x32_bf16 v[120:123], v[92:95], v[184:187], v[120:123]
	v_mfma_f32_16x16x32_bf16 v[120:123], v[100:103], v[188:191], v[120:123]
	v_mfma_f32_16x16x32_bf16 v[112:115], v[92:95], v[192:195], v[112:115]
	v_mfma_f32_16x16x32_bf16 v[112:115], v[100:103], v[212:215], v[112:115]
	v_mfma_f32_16x16x32_bf16 v[136:139], v[132:135], v[148:151], v[136:139]
	v_mfma_f32_16x16x32_bf16 v[136:139], v[144:147], v[152:155], v[136:139]
	v_mfma_f32_16x16x32_bf16 v[124:127], v[132:135], v[176:179], v[124:127]
	v_mfma_f32_16x16x32_bf16 v[124:127], v[144:147], v[180:183], v[124:127]
	v_mfma_f32_16x16x32_bf16 v[116:119], v[132:135], v[184:187], v[116:119]
	v_mfma_f32_16x16x32_bf16 v[116:119], v[144:147], v[188:191], v[116:119]
	v_mfma_f32_16x16x32_bf16 v[108:111], v[132:135], v[192:195], v[108:111]
	v_mfma_f32_16x16x32_bf16 v[108:111], v[144:147], v[212:215], v[108:111]
	s_barrier
; #define PG8_WAIT_V(n) asm volatile("s_waitcnt vmcnt(" #n ")" ::: "memory")
; #define PG8_WAIT_L(n) asm volatile("s_waitcnt lgkmcnt(" #n ")" ::: "memory")
; #define PG8_BAR __builtin_amdgcn_s_barrier()
; #define PG8_SCHED __builtin_amdgcn_sched_barrier(0)
; template <class Epi, class AddrA, class AddrB>
; __device__ __forceinline__ void gemm_phase(const Sched S, const int lda, const int ldb, const int K, const AddrA addrA,
;                                            const AddrB addrB, const Epi E) {
;     ...
;       PG8_LDB(B0, 0, 0); PG8_SCHED; PG8_LDA(At, 0, 0); PG8_STAGE(PG8_SA(1, 1), a1 + hstepA, voffA);
;       PG8_WAIT_L(8); PG8_BAR; PG8_WAIT_L(0); PG8_MMA(0, 0, At, B0); PG8_BAR; PG8_SCHED;
;       PG8_LDB(B1, 0, 1); PG8_STAGE(PG8_SB(0, 0), b2, voffB);
;       PG8_BAR; PG8_WAIT_L(0); PG8_MMA(0, 1, At, B1); PG8_BAR;
;       PG8_LDA(At, 0, 1); PG8_STAGE(PG8_SA(0, 0), a2, voffA);
;       PG8_BAR; PG8_WAIT_L(0); PG8_MMA(1, 0, At, B0); PG8_BAR; PG8_SCHED;
;       PG8_STAGE(PG8_SB(0, 1), b2 + hstepB, voffB);
;       PG8_WAIT_V(6); PG8_BAR; PG8_MMA(1, 1, At, B1); PG8_BAR;
;       PG8_LDB(B0, 1, 0); PG8_SCHED; PG8_LDA(At, 1, 0); PG8_STAGE(PG8_SA(0, 1), a2 + hstepA, voffA);
;       PG8_WAIT_L(8); PG8_BAR; PG8_WAIT_L(0); PG8_MMA(0, 0, At, B0); PG8_BAR; PG8_SCHED;
;       PG8_LDB(B1, 1, 1); PG8_STAGE(PG8_SB(1, 0), b3, voffB);
;       PG8_BAR; PG8_WAIT_L(0); PG8_MMA(0, 1, At, B1); PG8_BAR;
;       PG8_LDA(At, 1, 1); PG8_STAGE(PG8_SA(1, 0), a3, voffA);
;       PG8_BAR; PG8_WAIT_L(0); PG8_MMA(1, 0, At, B0); PG8_BAR; PG8_SCHED;
;       PG8_STAGE(PG8_SB(1, 1), b3 + hstepB, voffB);
;       PG8_WAIT_V(6); PG8_BAR; PG8_MMA(1, 1, At, B1); PG8_BAR;
	s_setprio 0
	s_add_i32 s10, 0, 0x1c000
	s_add_i32 s11, s44, s29
	s_mov_b32 m0, s11
	ds_read_b128 v[216:219], v246 offset:49152
	ds_read_b128 v[220:223], v246 offset:50176
	ds_read_b128 v[224:227], v246 offset:51200
	ds_read_b128 v[228:231], v246 offset:52224
	global_load_lds_dwordx4 v158, s[98:99]
	s_add_i32 m0, s11, 0x2000
	s_nop 0
	global_load_lds_dwordx4 v0, s[98:99]
	s_mov_b32 m0, s37
	s_waitcnt vmcnt(10)
	s_waitcnt lgkmcnt(2)
	s_setprio 1
	s_barrier
	v_mfma_f32_16x16x32_bf16 v[64:67], v[216:219], v[148:151], v[64:67]
	v_mfma_f32_16x16x32_bf16 v[64:67], v[220:223], v[152:155], v[64:67]
	s_waitcnt lgkmcnt(0)
	v_mfma_f32_16x16x32_bf16 v[56:59], v[216:219], v[176:179], v[56:59]
	v_mfma_f32_16x16x32_bf16 v[56:59], v[220:223], v[180:183], v[56:59]
	v_mfma_f32_16x16x32_bf16 v[48:51], v[216:219], v[184:187], v[48:51]
	v_mfma_f32_16x16x32_bf16 v[48:51], v[220:223], v[188:191], v[48:51]
	v_mfma_f32_16x16x32_bf16 v[40:43], v[216:219], v[192:195], v[40:43]
	v_mfma_f32_16x16x32_bf16 v[40:43], v[220:223], v[212:215], v[40:43]
	v_mfma_f32_16x16x32_bf16 v[60:63], v[224:227], v[148:151], v[60:63]
	v_mfma_f32_16x16x32_bf16 v[60:63], v[228:231], v[152:155], v[60:63]
	v_mfma_f32_16x16x32_bf16 v[52:55], v[224:227], v[176:179], v[52:55]
	v_mfma_f32_16x16x32_bf16 v[52:55], v[228:231], v[180:183], v[52:55]
	v_mfma_f32_16x16x32_bf16 v[44:47], v[224:227], v[184:187], v[44:47]
	v_mfma_f32_16x16x32_bf16 v[44:47], v[228:231], v[188:191], v[44:47]
	v_mfma_f32_16x16x32_bf16 v[36:39], v[224:227], v[192:195], v[36:39]
	v_mfma_f32_16x16x32_bf16 v[36:39], v[228:231], v[212:215], v[36:39]
	s_barrier
	s_setprio 0
	ds_read_b128 v[148:151], v169 offset:49152
	ds_read_b128 v[152:155], v169 offset:50176
	ds_read_b128 v[176:179], v169 offset:51200
	ds_read_b128 v[180:183], v169 offset:52224
	ds_read_b128 v[184:187], v169 offset:53248
	ds_read_b128 v[188:191], v169 offset:54272
	ds_read_b128 v[192:195], v169 offset:55296
	ds_read_b128 v[212:215], v169 offset:56320
	global_load_lds_dwordx4 v160, s[100:101]
	s_mov_b32 m0, s38
	s_nop 0
	global_load_lds_dwordx4 v156, s[100:101]
	s_waitcnt lgkmcnt(6)
	s_setprio 1
	s_barrier
	v_mfma_f32_16x16x32_bf16 v[104:107], v[92:95], v[148:151], v[104:107]
	v_mfma_f32_16x16x32_bf16 v[104:107], v[100:103], v[152:155], v[104:107]
	s_waitcnt lgkmcnt(0)
	v_mfma_f32_16x16x32_bf16 v[88:91], v[92:95], v[176:179], v[88:91]
	v_mfma_f32_16x16x32_bf16 v[88:91], v[100:103], v[180:183], v[88:91]
	v_mfma_f32_16x16x32_bf16 v[80:83], v[92:95], v[184:187], v[80:83]
	v_mfma_f32_16x16x32_bf16 v[80:83], v[100:103], v[188:191], v[80:83]
	v_mfma_f32_16x16x32_bf16 v[72:75], v[92:95], v[192:195], v[72:75]
	v_mfma_f32_16x16x32_bf16 v[72:75], v[100:103], v[212:215], v[72:75]
	v_mfma_f32_16x16x32_bf16 v[96:99], v[132:135], v[148:151], v[96:99]
	v_mfma_f32_16x16x32_bf16 v[96:99], v[144:147], v[152:155], v[96:99]
	v_mfma_f32_16x16x32_bf16 v[84:87], v[132:135], v[176:179], v[84:87]
	v_mfma_f32_16x16x32_bf16 v[84:87], v[144:147], v[180:183], v[84:87]
	v_mfma_f32_16x16x32_bf16 v[76:79], v[132:135], v[184:187], v[76:79]
	v_mfma_f32_16x16x32_bf16 v[76:79], v[144:147], v[188:191], v[76:79]
	v_mfma_f32_16x16x32_bf16 v[68:71], v[132:135], v[192:195], v[68:71]
	v_mfma_f32_16x16x32_bf16 v[68:71], v[144:147], v[212:215], v[68:71]
	s_barrier
	s_setprio 0
	s_add_u32 s6, s6, 0x20080
	s_addc_u32 s7, s7, 0
	s_add_i32 s10, s10, s29
	s_mov_b32 m0, s10
	s_nop 0
	global_load_lds_dwordx4 v158, s[6:7]
	s_add_i32 m0, s10, 0x2000
	s_nop 0
	global_load_lds_dwordx4 v0, s[6:7]
	s_add_i32 s43, s43, 2
	s_add_u32 s41, s41, 0x100
	s_addc_u32 s42, s42, 0
	s_add_u32 s4, s4, 0x100
	s_addc_u32 s5, s5, 0
	s_waitcnt vmcnt(8)
	s_setprio 1
	s_barrier
	v_mfma_f32_16x16x32_bf16 v[32:35], v[216:219], v[148:151], v[32:35]
	v_mfma_f32_16x16x32_bf16 v[32:35], v[220:223], v[152:155], v[32:35]
	v_mfma_f32_16x16x32_bf16 v[24:27], v[216:219], v[176:179], v[24:27]
	v_mfma_f32_16x16x32_bf16 v[24:27], v[220:223], v[180:183], v[24:27]
	v_mfma_f32_16x16x32_bf16 v[16:19], v[216:219], v[184:187], v[16:19]
	v_mfma_f32_16x16x32_bf16 v[16:19], v[220:223], v[188:191], v[16:19]
	v_mfma_f32_16x16x32_bf16 v[8:11], v[216:219], v[192:195], v[8:11]
	v_mfma_f32_16x16x32_bf16 v[8:11], v[220:223], v[212:215], v[8:11]
	v_mfma_f32_16x16x32_bf16 v[28:31], v[224:227], v[148:151], v[28:31]
	v_mfma_f32_16x16x32_bf16 v[28:31], v[228:231], v[152:155], v[28:31]
	v_mfma_f32_16x16x32_bf16 v[20:23], v[224:227], v[176:179], v[20:23]
	v_mfma_f32_16x16x32_bf16 v[20:23], v[228:231], v[180:183], v[20:23]
	v_mfma_f32_16x16x32_bf16 v[12:15], v[224:227], v[184:187], v[12:15]
	v_mfma_f32_16x16x32_bf16 v[12:15], v[228:231], v[188:191], v[12:15]
	v_mfma_f32_16x16x32_bf16 v[4:7], v[224:227], v[192:195], v[4:7]
	v_mfma_f32_16x16x32_bf16 v[4:7], v[228:231], v[212:215], v[4:7]
	s_barrier
	s_setprio 0
	s_cmp_gt_u32 s43, 5
	s_cbranch_scc0 .LBB0_485
; __device__ __forceinline__ size_t pidx(size_t row, int col) { return ((size_t)(col >> 8) * MTOK + row) * PLD + (col & 255); }
; __device__ __forceinline__ float bflo(unsigned v) { return __uint_as_float(v << 16); }
; __device__ __forceinline__ float bfhi(unsigned v) { return __uint_as_float(v & 0xffff0000u); }
; __device__ __forceinline__ float siluf_(float x) { return x * __builtin_amdgcn_rcpf(1.0f + __expf(-x)); }
;   __device__ __forceinline__ void operator()(EPI_ARGS) const {
;     const size_t row0 = (size_t)u.pm * 256 + wr * 64 + fr;
;     const int col0 = u.pn * 256 + wc * 32 + 8 * fq;
; #pragma unroll
;     for (int bj = 0; bj < 2; ++bj) {
;       const int c = col0 + bj * HALF;
;       const f32x4 s0 = *(const f32x4*)(psc + c), s1 = *(const f32x4*)(psc + c + 4);
; #pragma unroll
;       for (int ai = 0; ai < 2; ++ai) {
;         u32x4 z[4];
; #pragma unroll
;         for (int m = 0; m < 4; ++m) z[m] = *(const u32x4*)(proj + pidx(row0 + ai * HALF + m * 16, PZ + c));
;         __builtin_amdgcn_sched_barrier(0);
; #pragma unroll
;         for (int m = 0; m < 4; ++m) {
;           const size_t row = row0 + ai * HALF + m * 16;
;           const f32x4 v0 = acc[ai][bj][m][0], v1 = acc[ai][bj][m][1];
;           u32x4 o;
;           o.x = pack2(v0[0] * s0[0] * siluf_(bflo(z[m].x)), v0[1] * s0[1] * siluf_(bfhi(z[m].x)));
;           o.y = pack2(v0[2] * s0[2] * siluf_(bflo(z[m].y)), v0[3] * s0[3] * siluf_(bfhi(z[m].y)));
;           o.z = pack2(v1[0] * s1[0] * siluf_(bflo(z[m].z)), v1[1] * s1[1] * siluf_(bfhi(z[m].z)));
;           o.w = pack2(v1[2] * s1[2] * siluf_(bflo(z[m].w)), v1[3] * s1[3] * siluf_(bfhi(z[m].w)));
;           *(u32x4*)(y0 + row * DM + c) = o;
	s_ashr_i32 s3, s2, 31
	s_lshl_b64 s[2:3], s[2:3], 8
	v_lshl_add_u64 v[186:187], s[2:3], 0, v[162:163]
	s_lshl_b32 s2, s33, 8
	v_or_b32_e32 v196, s2, v168
	s_addk_i32 s2, 0x800
	s_ashr_i32 s2, s2, 8
	s_ashr_i32 s3, s2, 31
	s_lshl_b64 s[2:3], s[2:3], 23
	s_add_u32 s2, s0, s2
	s_addc_u32 s3, s1, s3
	v_lshlrev_b32_e32 v2, 1, v168
	v_or_b32_e32 v194, 16, v186
	v_mov_b32_e32 v195, v187
	v_ashrrev_i32_e32 v197, 31, v196
	v_lshl_add_u64 v[188:189], s[2:3], 0, v[2:3]
	v_lshlrev_b64 v[178:179], 9, v[186:187]
	v_lshlrev_b64 v[180:181], 9, v[194:195]
	v_or_b32_e32 v192, 32, v186
	v_mov_b32_e32 v193, v187
	v_or_b32_e32 v190, 48, v186
	v_mov_b32_e32 v191, v187
	v_lshl_add_u64 v[176:177], v[196:197], 2, s[12:13]
	v_lshl_add_u64 v[132:133], v[188:189], 0, v[178:179]
	v_lshl_add_u64 v[134:135], v[188:189], 0, v[180:181]
	v_lshlrev_b64 v[182:183], 9, v[192:193]
	v_lshlrev_b64 v[184:185], 9, v[190:191]
	global_load_dwordx4 v[92:95], v[176:177], off offset:16
	global_load_dwordx4 v[100:103], v[176:177], off
	flat_load_dwordx4 v[152:155], v[132:133]
	flat_load_dwordx4 v[148:151], v[134:135]
	v_lshl_add_u64 v[132:133], v[188:189], 0, v[182:183]
	v_lshl_add_u64 v[134:135], v[188:189], 0, v[184:185]
	flat_load_dwordx4 v[144:147], v[132:133]
	s_nop 0
	flat_load_dwordx4 v[132:135], v[134:135]
	s_waitcnt vmcnt(0) lgkmcnt(0)
	v_lshlrev_b32_e32 v213, 16, v152
	v_mul_f32_e32 v2, 0xbfb8aa3b, v213
	v_exp_f32_e32 v2, v2
	v_mov_b32_e32 v214, v140
	v_mov_b32_e32 v212, v100
	s_mov_b64 s[4:5], 0x90
	v_add_f32_e32 v2, 1.0, v2
	v_rcp_f32_e32 v215, v2
	s_nop 0
	v_pk_mul_f32 v[212:213], v[214:215], v[212:213]
	s_nop 0
	v_mul_f32_e32 v2, v212, v213
	v_and_b32_e32 v213, 0xffff0000, v152
	v_mul_f32_e32 v140, 0xbfb8aa3b, v213
	v_exp_f32_e32 v140, v140
	v_mov_b32_e32 v214, v141
	v_mov_b32_e32 v212, v101
	v_add_f32_e32 v140, 1.0, v140
	v_rcp_f32_e32 v215, v140
	s_nop 0
	v_pk_mul_f32 v[140:141], v[214:215], v[212:213]
	s_nop 0
	v_mul_f32_e32 v140, v140, v141
	v_lshlrev_b32_e32 v141, 16, v153
	v_cvt_pk_bf16_f32 v152, v2, v140
	v_mul_f32_e32 v2, 0xbfb8aa3b, v141
	v_exp_f32_e32 v2, v2
	v_mov_b32_e32 v212, v142
	v_mov_b32_e32 v140, v102
	v_mov_b32_e32 v142, v136
	v_add_f32_e32 v2, 1.0, v2
	v_rcp_f32_e32 v213, v2
	s_nop 0
	v_pk_mul_f32 v[140:141], v[212:213], v[140:141]
	s_nop 0
	v_mul_f32_e32 v2, v140, v141
	v_and_b32_e32 v141, 0xffff0000, v153
	v_mul_f32_e32 v140, 0xbfb8aa3b, v141
	v_exp_f32_e32 v140, v140
	v_mov_b32_e32 v212, v143
	v_add_f32_e32 v140, 1.0, v140
	v_rcp_f32_e32 v213, v140
	v_mov_b32_e32 v140, v103
	v_pk_mul_f32 v[140:141], v[212:213], v[140:141]
	s_nop 0
	v_mul_f32_e32 v140, v140, v141
	v_lshlrev_b32_e32 v141, 16, v154
	v_cvt_pk_bf16_f32 v153, v2, v140
	v_mul_f32_e32 v2, 0xbfb8aa3b, v141
	v_exp_f32_e32 v2, v2
	v_mov_b32_e32 v140, v92
	v_add_f32_e32 v2, 1.0, v2
	v_rcp_f32_e32 v143, v2
	s_nop 0
	v_pk_mul_f32 v[140:141], v[142:143], v[140:141]
	s_nop 0
	v_mul_f32_e32 v2, v140, v141
	v_and_b32_e32 v141, 0xffff0000, v154
	v_mul_f32_e32 v136, 0xbfb8aa3b, v141
	v_exp_f32_e32 v136, v136
	v_mov_b32_e32 v142, v137
	v_mov_b32_e32 v140, v93
	v_add_f32_e32 v136, 1.0, v136
	v_rcp_f32_e32 v143, v136
	s_nop 0
	v_pk_mul_f32 v[136:137], v[142:143], v[140:141]
	s_nop 0
	v_mul_f32_e32 v136, v136, v137
	v_lshlrev_b32_e32 v137, 16, v155
	v_cvt_pk_bf16_f32 v154, v2, v136
	v_mul_f32_e32 v2, 0xbfb8aa3b, v137
	v_exp_f32_e32 v2, v2
	v_mov_b32_e32 v140, v138
	v_mov_b32_e32 v136, v94
	v_mov_b32_e32 v142, v128
	v_add_f32_e32 v2, 1.0, v2
	v_rcp_f32_e32 v141, v2
	v_mov_b32_e32 v138, v100
	v_pk_mul_f32 v[136:137], v[140:141], v[136:137]
	s_nop 0
	v_mul_f32_e32 v2, v136, v137
	v_and_b32_e32 v137, 0xffff0000, v155
	v_mul_f32_e32 v136, 0xbfb8aa3b, v137
	v_exp_f32_e32 v136, v136
	v_mov_b32_e32 v140, v139
	v_lshlrev_b32_e32 v139, 16, v148
	v_add_f32_e32 v136, 1.0, v136
	v_rcp_f32_e32 v141, v136
	v_mov_b32_e32 v136, v95
	v_pk_mul_f32 v[136:137], v[140:141], v[136:137]
	s_nop 0
	v_mul_f32_e32 v136, v136, v137
	v_cvt_pk_bf16_f32 v155, v2, v136
	v_mul_f32_e32 v2, 0xbfb8aa3b, v139
	v_exp_f32_e32 v2, v2
	v_lshlrev_b64 v[140:141], 1, v[196:197]
	v_lshlrev_b64 v[136:137], 12, v[186:187]
	v_lshl_add_u64 v[136:137], s[8:9], 0, v[136:137]
	v_add_f32_e32 v2, 1.0, v2
	v_rcp_f32_e32 v143, v2
	v_lshl_add_u64 v[136:137], v[136:137], 0, v[140:141]
	flat_store_dwordx4 v[136:137], v[152:155]
	v_pk_mul_f32 v[138:139], v[142:143], v[138:139]
	s_nop 0
	v_mul_f32_e32 v2, v138, v139
	v_and_b32_e32 v139, 0xffff0000, v148
	v_mul_f32_e32 v128, 0xbfb8aa3b, v139
	v_exp_f32_e32 v128, v128
	v_mov_b32_e32 v142, v129
	v_mov_b32_e32 v138, v101
	v_add_f32_e32 v128, 1.0, v128
	v_rcp_f32_e32 v143, v128
	s_nop 0
	v_pk_mul_f32 v[128:129], v[142:143], v[138:139]
	s_nop 0
	v_mul_f32_e32 v128, v128, v129
	v_lshlrev_b32_e32 v139, 16, v149
	v_cvt_pk_bf16_f32 v128, v2, v128
	v_mul_f32_e32 v2, 0xbfb8aa3b, v139
	v_exp_f32_e32 v2, v2
	v_mov_b32_e32 v142, v130
	v_mov_b32_e32 v138, v102
	v_add_f32_e32 v2, 1.0, v2
	v_rcp_f32_e32 v143, v2
	s_nop 0
	v_pk_mul_f32 v[138:139], v[142:143], v[138:139]
	s_nop 0
	v_mul_f32_e32 v2, v138, v139
	v_and_b32_e32 v139, 0xffff0000, v149
	v_mul_f32_e32 v129, 0xbfb8aa3b, v139
	v_exp_f32_e32 v129, v129
	v_mov_b32_e32 v142, v131
	v_mov_b32_e32 v138, v103
	v_lshl_add_u64 v[148:149], v[186:187], 0, s[52:53]
	v_add_f32_e32 v129, 1.0, v129
	v_rcp_f32_e32 v143, v129
	s_nop 0
	v_pk_mul_f32 v[130:131], v[142:143], v[138:139]
	s_nop 0
	v_mul_f32_e32 v129, v130, v131
	v_lshlrev_b32_e32 v131, 16, v150
	v_cvt_pk_bf16_f32 v129, v2, v129
	v_mul_f32_e32 v2, 0xbfb8aa3b, v131
	v_exp_f32_e32 v2, v2
	v_mov_b32_e32 v138, v124
	v_mov_b32_e32 v130, v92
	v_add_f32_e32 v2, 1.0, v2
	v_rcp_f32_e32 v139, v2
	s_nop 0
	v_pk_mul_f32 v[130:131], v[138:139], v[130:131]
; __device__ __forceinline__ float bflo(unsigned v) { return __uint_as_float(v << 16); }
; __device__ __forceinline__ float bfhi(unsigned v) { return __uint_as_float(v & 0xffff0000u); }
; __device__ __forceinline__ float siluf_(float x) { return x * __builtin_amdgcn_rcpf(1.0f + __expf(-x)); }
;   __device__ __forceinline__ void operator()(EPI_ARGS) const {
;     ...
;         for (int m = 0; m < 4; ++m) {
;           const size_t row = row0 + ai * HALF + m * 16;
;           const f32x4 v0 = acc[ai][bj][m][0], v1 = acc[ai][bj][m][1];
;           u32x4 o;
;           o.x = pack2(v0[0] * s0[0] * siluf_(bflo(z[m].x)), v0[1] * s0[1] * siluf_(bfhi(z[m].x)));
;           o.y = pack2(v0[2] * s0[2] * siluf_(bflo(z[m].y)), v0[3] * s0[3] * siluf_(bfhi(z[m].y)));
;           o.z = pack2(v1[0] * s1[0] * siluf_(bflo(z[m].z)), v1[1] * s1[1] * siluf_(bfhi(z[m].z)));
;           o.w = pack2(v1[2] * s1[2] * siluf_(bflo(z[m].w)), v1[3] * s1[3] * siluf_(bfhi(z[m].w)));
;           *(u32x4*)(y0 + row * DM + c) = o;
	s_nop 0
	v_mul_f32_e32 v2, v130, v131
	v_and_b32_e32 v131, 0xffff0000, v150
	v_mul_f32_e32 v124, 0xbfb8aa3b, v131
	v_exp_f32_e32 v124, v124
	v_mov_b32_e32 v138, v125
	v_mov_b32_e32 v130, v93
	v_add_f32_e32 v124, 1.0, v124
	v_rcp_f32_e32 v139, v124
	s_nop 0
	v_pk_mul_f32 v[124:125], v[138:139], v[130:131]
	s_nop 0
	v_mul_f32_e32 v124, v124, v125
	v_lshlrev_b32_e32 v125, 16, v151
	v_cvt_pk_bf16_f32 v130, v2, v124
	v_mul_f32_e32 v2, 0xbfb8aa3b, v125
	v_exp_f32_e32 v2, v2
	v_mov_b32_e32 v138, v126
	v_mov_b32_e32 v124, v94
	v_mov_b32_e32 v126, v100
	v_add_f32_e32 v2, 1.0, v2
	v_rcp_f32_e32 v139, v2
	s_nop 0
	v_pk_mul_f32 v[124:125], v[138:139], v[124:125]
	s_nop 0
	v_mul_f32_e32 v2, v124, v125
	v_and_b32_e32 v125, 0xffff0000, v151
	v_mul_f32_e32 v124, 0xbfb8aa3b, v125
	v_exp_f32_e32 v124, v124
	v_mov_b32_e32 v138, v127
	v_lshlrev_b32_e32 v127, 16, v144
	v_add_f32_e32 v124, 1.0, v124
	v_rcp_f32_e32 v139, v124
	v_mov_b32_e32 v124, v95
	v_pk_mul_f32 v[124:125], v[138:139], v[124:125]
	s_nop 0
	v_mul_f32_e32 v124, v124, v125
	v_cvt_pk_bf16_f32 v131, v2, v124
	v_mul_f32_e32 v2, 0xbfb8aa3b, v127
	v_exp_f32_e32 v2, v2
	v_lshlrev_b64 v[124:125], 12, v[194:195]
	v_lshl_add_u64 v[124:125], s[8:9], 0, v[124:125]
	v_lshl_add_u64 v[124:125], v[124:125], 0, v[140:141]
	v_add_f32_e32 v2, 1.0, v2
	flat_store_dwordx4 v[124:125], v[128:131]
	s_nop 1
	v_rcp_f32_e32 v129, v2
	v_mov_b32_e32 v128, v120
	v_lshlrev_b64 v[130:131], 9, v[148:149]
	v_pk_mul_f32 v[126:127], v[128:129], v[126:127]
	s_nop 0
	v_mul_f32_e32 v2, v126, v127
	v_and_b32_e32 v127, 0xffff0000, v144
	v_mul_f32_e32 v120, 0xbfb8aa3b, v127
	v_exp_f32_e32 v120, v120
	v_mov_b32_e32 v128, v121
	v_mov_b32_e32 v126, v101
	v_add_f32_e32 v120, 1.0, v120
	v_rcp_f32_e32 v129, v120
	s_nop 0
	v_pk_mul_f32 v[120:121], v[128:129], v[126:127]
	s_nop 0
	v_mul_f32_e32 v120, v120, v121
	v_lshlrev_b32_e32 v127, 16, v145
	v_cvt_pk_bf16_f32 v120, v2, v120
	v_mul_f32_e32 v2, 0xbfb8aa3b, v127
	v_exp_f32_e32 v2, v2
	v_mov_b32_e32 v128, v122
	v_mov_b32_e32 v126, v102
	v_add_f32_e32 v2, 1.0, v2
	v_rcp_f32_e32 v129, v2
	s_nop 0
	v_pk_mul_f32 v[126:127], v[128:129], v[126:127]
	s_nop 0
	v_mul_f32_e32 v2, v126, v127
	v_and_b32_e32 v127, 0xffff0000, v145
	v_mul_f32_e32 v121, 0xbfb8aa3b, v127
	v_exp_f32_e32 v121, v121
	v_mov_b32_e32 v128, v123
	v_mov_b32_e32 v126, v103
	v_add_f32_e32 v121, 1.0, v121
	v_rcp_f32_e32 v129, v121
	s_nop 0
	v_pk_mul_f32 v[122:123], v[128:129], v[126:127]
	s_nop 0
	v_mul_f32_e32 v121, v122, v123
	v_lshlrev_b32_e32 v123, 16, v146
	v_cvt_pk_bf16_f32 v121, v2, v121
	v_mul_f32_e32 v2, 0xbfb8aa3b, v123
	v_exp_f32_e32 v2, v2
	v_mov_b32_e32 v126, v116
	v_mov_b32_e32 v122, v92
	v_add_f32_e32 v2, 1.0, v2
	v_rcp_f32_e32 v127, v2
	s_nop 0
	v_pk_mul_f32 v[122:123], v[126:127], v[122:123]
	s_nop 0
	v_mul_f32_e32 v2, v122, v123
	v_and_b32_e32 v123, 0xffff0000, v146
	v_mul_f32_e32 v116, 0xbfb8aa3b, v123
	v_exp_f32_e32 v116, v116
	v_mov_b32_e32 v126, v117
	v_mov_b32_e32 v122, v93
	v_add_f32_e32 v116, 1.0, v116
	v_rcp_f32_e32 v127, v116
	s_nop 0
	v_pk_mul_f32 v[116:117], v[126:127], v[122:123]
	s_nop 0
	v_mul_f32_e32 v116, v116, v117
	v_lshlrev_b32_e32 v117, 16, v147
	v_cvt_pk_bf16_f32 v122, v2, v116
	v_mul_f32_e32 v2, 0xbfb8aa3b, v117
	v_exp_f32_e32 v2, v2
	v_mov_b32_e32 v126, v118
	v_mov_b32_e32 v116, v94
	v_mov_b32_e32 v118, v112
	v_add_f32_e32 v2, 1.0, v2
	v_rcp_f32_e32 v127, v2
	s_nop 0
	v_pk_mul_f32 v[116:117], v[126:127], v[116:117]
	s_nop 0
	v_mul_f32_e32 v2, v116, v117
	v_and_b32_e32 v117, 0xffff0000, v147
	v_mul_f32_e32 v116, 0xbfb8aa3b, v117
	v_exp_f32_e32 v116, v116
	v_mov_b32_e32 v126, v119
	v_lshl_add_u64 v[146:147], v[186:187], 0, s[4:5]
	s_mov_b64 s[4:5], 0xa0
	v_add_f32_e32 v116, 1.0, v116
	v_rcp_f32_e32 v127, v116
	v_mov_b32_e32 v116, v95
	v_lshl_add_u64 v[144:145], v[186:187], 0, s[4:5]
	s_mov_b64 s[4:5], 0xb0
	v_pk_mul_f32 v[116:117], v[126:127], v[116:117]
	v_lshl_add_u64 v[142:143], v[186:187], 0, s[4:5]
	v_mul_f32_e32 v116, v116, v117
	v_cvt_pk_bf16_f32 v123, v2, v116
	v_lshlrev_b64 v[116:117], 12, v[192:193]
	v_lshl_add_u64 v[116:117], s[8:9], 0, v[116:117]
	v_lshl_add_u64 v[128:129], v[116:117], 0, v[140:141]
	v_lshlrev_b32_e32 v117, 16, v132
	v_mul_f32_e32 v2, 0xbfb8aa3b, v117
	v_exp_f32_e32 v2, v2
	v_mov_b32_e32 v116, v100
	flat_store_dwordx4 v[128:129], v[120:123]
	v_lshlrev_b64 v[138:139], 9, v[142:143]
	v_add_f32_e32 v2, 1.0, v2
	v_rcp_f32_e32 v119, v2
	s_nop 0
	v_pk_mul_f32 v[116:117], v[118:119], v[116:117]
	s_nop 0
	v_mul_f32_e32 v2, v116, v117
	v_and_b32_e32 v117, 0xffff0000, v132
	v_mul_f32_e32 v112, 0xbfb8aa3b, v117
	v_exp_f32_e32 v112, v112
	v_mov_b32_e32 v118, v113
	v_mov_b32_e32 v116, v101
	v_add_f32_e32 v112, 1.0, v112
	v_rcp_f32_e32 v119, v112
	s_nop 0
	v_pk_mul_f32 v[112:113], v[118:119], v[116:117]
	s_nop 0
	v_mul_f32_e32 v112, v112, v113
	v_lshlrev_b32_e32 v117, 16, v133
	v_cvt_pk_bf16_f32 v112, v2, v112
	v_mul_f32_e32 v2, 0xbfb8aa3b, v117
	v_exp_f32_e32 v2, v2
	v_mov_b32_e32 v118, v114
	v_mov_b32_e32 v116, v102
	v_add_f32_e32 v2, 1.0, v2
	v_rcp_f32_e32 v119, v2
	s_nop 0
	v_pk_mul_f32 v[116:117], v[118:119], v[116:117]
	s_nop 0
	v_mul_f32_e32 v2, v116, v117
	v_and_b32_e32 v117, 0xffff0000, v133
	v_mul_f32_e32 v113, 0xbfb8aa3b, v117
	v_exp_f32_e32 v113, v113
	v_mov_b32_e32 v118, v115
	v_mov_b32_e32 v116, v103
	v_lshlrev_b64 v[132:133], 9, v[146:147]
	v_add_f32_e32 v113, 1.0, v113
	v_rcp_f32_e32 v119, v113
	s_nop 0
	v_pk_mul_f32 v[114:115], v[118:119], v[116:117]
	s_nop 0
	v_mul_f32_e32 v113, v114, v115
	v_lshlrev_b32_e32 v115, 16, v134
	v_cvt_pk_bf16_f32 v113, v2, v113
	v_mul_f32_e32 v2, 0xbfb8aa3b, v115
	v_exp_f32_e32 v2, v2
	v_mov_b32_e32 v116, v108
	v_mov_b32_e32 v114, v92
; __device__ __forceinline__ size_t pidx(size_t row, int col) { return ((size_t)(col >> 8) * MTOK + row) * PLD + (col & 255); }
; __device__ __forceinline__ float bflo(unsigned v) { return __uint_as_float(v << 16); }
; __device__ __forceinline__ float bfhi(unsigned v) { return __uint_as_float(v & 0xffff0000u); }
; __device__ __forceinline__ float siluf_(float x) { return x * __builtin_amdgcn_rcpf(1.0f + __expf(-x)); }
;   __device__ __forceinline__ void operator()(EPI_ARGS) const {
;     ...
;         u32x4 z[4];
; #pragma unroll
;         for (int m = 0; m < 4; ++m) z[m] = *(const u32x4*)(proj + pidx(row0 + ai * HALF + m * 16, PZ + c));
;         __builtin_amdgcn_sched_barrier(0);
; #pragma unroll
;         for (int m = 0; m < 4; ++m) {
;           const size_t row = row0 + ai * HALF + m * 16;
;           const f32x4 v0 = acc[ai][bj][m][0], v1 = acc[ai][bj][m][1];
;           u32x4 o;
;           o.x = pack2(v0[0] * s0[0] * siluf_(bflo(z[m].x)), v0[1] * s0[1] * siluf_(bfhi(z[m].x)));
;           o.y = pack2(v0[2] * s0[2] * siluf_(bflo(z[m].y)), v0[3] * s0[3] * siluf_(bfhi(z[m].y)));
;           o.z = pack2(v1[0] * s1[0] * siluf_(bflo(z[m].z)), v1[1] * s1[1] * siluf_(bfhi(z[m].z)));
;           o.w = pack2(v1[2] * s1[2] * siluf_(bflo(z[m].w)), v1[3] * s1[3] * siluf_(bfhi(z[m].w)));
;           *(u32x4*)(y0 + row * DM + c) = o;
	v_add_f32_e32 v2, 1.0, v2
	v_rcp_f32_e32 v117, v2
	s_nop 0
	v_pk_mul_f32 v[114:115], v[116:117], v[114:115]
	s_nop 0
	v_mul_f32_e32 v2, v114, v115
	v_and_b32_e32 v115, 0xffff0000, v134
	v_mul_f32_e32 v108, 0xbfb8aa3b, v115
	v_exp_f32_e32 v108, v108
	v_mov_b32_e32 v116, v109
	v_mov_b32_e32 v114, v93
	v_add_f32_e32 v108, 1.0, v108
	v_rcp_f32_e32 v117, v108
	s_nop 0
	v_pk_mul_f32 v[108:109], v[116:117], v[114:115]
	s_nop 0
	v_mul_f32_e32 v108, v108, v109
	v_lshlrev_b32_e32 v109, 16, v135
	v_cvt_pk_bf16_f32 v114, v2, v108
	v_mul_f32_e32 v2, 0xbfb8aa3b, v109
	v_exp_f32_e32 v2, v2
	v_mov_b32_e32 v116, v110
	v_mov_b32_e32 v108, v94
	v_add_f32_e32 v2, 1.0, v2
	v_rcp_f32_e32 v117, v2
	s_nop 0
	v_pk_mul_f32 v[108:109], v[116:117], v[108:109]
	s_nop 0
	v_mul_f32_e32 v2, v108, v109
	v_and_b32_e32 v109, 0xffff0000, v135
	v_mul_f32_e32 v108, 0xbfb8aa3b, v109
	v_exp_f32_e32 v108, v108
	v_mov_b32_e32 v116, v111
	v_lshlrev_b64 v[134:135], 9, v[144:145]
	v_add_f32_e32 v108, 1.0, v108
	v_rcp_f32_e32 v117, v108
	v_mov_b32_e32 v108, v95
	v_pk_mul_f32 v[108:109], v[116:117], v[108:109]
	s_nop 0
	v_mul_f32_e32 v108, v108, v109
	v_cvt_pk_bf16_f32 v115, v2, v108
	v_lshlrev_b64 v[108:109], 12, v[190:191]
	v_lshl_add_u64 v[108:109], s[8:9], 0, v[108:109]
	v_lshl_add_u64 v[126:127], v[108:109], 0, v[140:141]
	flat_store_dwordx4 v[126:127], v[112:115]
	v_lshl_add_u64 v[108:109], v[188:189], 0, v[130:131]
	flat_load_dwordx4 v[120:123], v[108:109]
	v_lshl_add_u64 v[108:109], v[188:189], 0, v[132:133]
	flat_load_dwordx4 v[116:119], v[108:109]
	v_lshl_add_u64 v[108:109], v[188:189], 0, v[134:135]
	flat_load_dwordx4 v[112:115], v[108:109]
	v_lshl_add_u64 v[108:109], v[188:189], 0, v[138:139]
	flat_load_dwordx4 v[108:111], v[108:109]
	s_waitcnt vmcnt(0) lgkmcnt(0)
	v_lshlrev_b32_e32 v151, 16, v120
	v_mul_f32_e32 v2, 0xbfb8aa3b, v151
	v_exp_f32_e32 v2, v2
	v_mov_b32_e32 v152, v104
	v_mov_b32_e32 v150, v100
	v_mov_b32_e32 v175, v3
	v_add_f32_e32 v2, 1.0, v2
	v_rcp_f32_e32 v153, v2
	s_nop 0
	v_pk_mul_f32 v[150:151], v[152:153], v[150:151]
	s_nop 0
	v_mul_f32_e32 v2, v150, v151
	v_and_b32_e32 v151, 0xffff0000, v120
	v_mul_f32_e32 v104, 0xbfb8aa3b, v151
	v_exp_f32_e32 v104, v104
	v_mov_b32_e32 v152, v105
	v_mov_b32_e32 v150, v101
	v_mov_b32_e32 v120, v103
	v_add_f32_e32 v104, 1.0, v104
	v_rcp_f32_e32 v153, v104
	s_nop 0
	v_pk_mul_f32 v[104:105], v[152:153], v[150:151]
	s_nop 0
	v_mul_f32_e32 v104, v104, v105
	v_lshlrev_b32_e32 v151, 16, v121
	v_cvt_pk_bf16_f32 v104, v2, v104
	v_mul_f32_e32 v2, 0xbfb8aa3b, v151
	v_exp_f32_e32 v2, v2
	v_and_b32_e32 v121, 0xffff0000, v121
	v_mul_f32_e32 v105, 0xbfb8aa3b, v121
	v_exp_f32_e32 v105, v105
	v_add_f32_e32 v2, 1.0, v2
	v_rcp_f32_e32 v153, v2
	v_mov_b32_e32 v152, v106
	v_mov_b32_e32 v150, v102
	v_add_f32_e32 v105, 1.0, v105
	v_pk_mul_f32 v[150:151], v[152:153], v[150:151]
	s_nop 0
	v_mul_f32_e32 v2, v150, v151
	v_rcp_f32_e32 v151, v105
	v_mov_b32_e32 v150, v107
	v_pk_mul_f32 v[106:107], v[150:151], v[120:121]
	s_nop 0
	v_mul_f32_e32 v105, v106, v107
	v_lshlrev_b32_e32 v107, 16, v122
	v_cvt_pk_bf16_f32 v105, v2, v105
	v_mul_f32_e32 v2, 0xbfb8aa3b, v107
	v_exp_f32_e32 v2, v2
	v_mov_b32_e32 v120, v96
	v_mov_b32_e32 v106, v92
	v_add_f32_e32 v2, 1.0, v2
	v_rcp_f32_e32 v121, v2
	s_nop 0
	v_pk_mul_f32 v[106:107], v[120:121], v[106:107]
	s_nop 0
	v_mul_f32_e32 v2, v106, v107
	v_and_b32_e32 v107, 0xffff0000, v122
	v_mul_f32_e32 v96, 0xbfb8aa3b, v107
	v_exp_f32_e32 v96, v96
	v_mov_b32_e32 v120, v97
	v_mov_b32_e32 v106, v93
	v_add_f32_e32 v96, 1.0, v96
	v_rcp_f32_e32 v121, v96
	s_nop 0
	v_pk_mul_f32 v[96:97], v[120:121], v[106:107]
	s_nop 0
	v_mul_f32_e32 v96, v96, v97
	v_lshlrev_b32_e32 v97, 16, v123
	v_cvt_pk_bf16_f32 v106, v2, v96
	v_mul_f32_e32 v2, 0xbfb8aa3b, v97
	v_exp_f32_e32 v2, v2
	v_mov_b32_e32 v120, v98
	v_mov_b32_e32 v96, v94
	v_mov_b32_e32 v98, v100
	v_add_f32_e32 v2, 1.0, v2
	v_rcp_f32_e32 v121, v2
	s_nop 0
	v_pk_mul_f32 v[96:97], v[120:121], v[96:97]
	s_nop 0
	v_mul_f32_e32 v2, v96, v97
	v_and_b32_e32 v97, 0xffff0000, v123
	v_mul_f32_e32 v96, 0xbfb8aa3b, v97
	v_exp_f32_e32 v96, v96
	v_mov_b32_e32 v120, v99
	v_lshlrev_b32_e32 v99, 16, v116
	v_add_f32_e32 v96, 1.0, v96
	v_rcp_f32_e32 v121, v96
	v_mov_b32_e32 v96, v95
	v_pk_mul_f32 v[96:97], v[120:121], v[96:97]
	s_nop 0
	v_mul_f32_e32 v96, v96, v97
	v_cvt_pk_bf16_f32 v107, v2, v96
	v_mul_f32_e32 v2, 0xbfb8aa3b, v99
	v_exp_f32_e32 v2, v2
	v_lshlrev_b64 v[96:97], 12, v[148:149]
	v_lshl_add_u64 v[96:97], s[8:9], 0, v[96:97]
	v_lshl_add_u64 v[96:97], v[96:97], 0, v[140:141]
	v_add_f32_e32 v2, 1.0, v2
	flat_store_dwordx4 v[96:97], v[104:107]
	s_nop 1
	v_rcp_f32_e32 v105, v2
	v_mov_b32_e32 v104, v88
	v_pk_mul_f32 v[98:99], v[104:105], v[98:99]
	s_nop 0
	v_mul_f32_e32 v2, v98, v99
	v_and_b32_e32 v99, 0xffff0000, v116
	v_mul_f32_e32 v88, 0xbfb8aa3b, v99
	v_exp_f32_e32 v88, v88
	v_mov_b32_e32 v104, v89
	v_mov_b32_e32 v98, v101
	v_add_f32_e32 v88, 1.0, v88
	v_rcp_f32_e32 v105, v88
	s_nop 0
	v_pk_mul_f32 v[88:89], v[104:105], v[98:99]
	s_nop 0
	v_mul_f32_e32 v88, v88, v89
	v_lshlrev_b32_e32 v99, 16, v117
	v_cvt_pk_bf16_f32 v88, v2, v88
	v_mul_f32_e32 v2, 0xbfb8aa3b, v99
	v_exp_f32_e32 v2, v2
	v_mov_b32_e32 v104, v90
	v_mov_b32_e32 v98, v102
	v_add_f32_e32 v2, 1.0, v2
	v_rcp_f32_e32 v105, v2
	s_nop 0
	v_pk_mul_f32 v[98:99], v[104:105], v[98:99]
	s_nop 0
	v_mul_f32_e32 v2, v98, v99
	v_and_b32_e32 v99, 0xffff0000, v117
	v_mul_f32_e32 v89, 0xbfb8aa3b, v99
	v_exp_f32_e32 v89, v89
	v_mov_b32_e32 v104, v91
	v_mov_b32_e32 v98, v103
	v_add_f32_e32 v89, 1.0, v89
	v_rcp_f32_e32 v105, v89
	s_nop 0
	v_pk_mul_f32 v[90:91], v[104:105], v[98:99]
	s_nop 0
	v_mul_f32_e32 v89, v90, v91
	v_lshlrev_b32_e32 v91, 16, v118
; __device__ __forceinline__ size_t pidx(size_t row, int col) { return ((size_t)(col >> 8) * MTOK + row) * PLD + (col & 255); }
; __device__ __forceinline__ float bflo(unsigned v) { return __uint_as_float(v << 16); }
; __device__ __forceinline__ float bfhi(unsigned v) { return __uint_as_float(v & 0xffff0000u); }
; __device__ __forceinline__ float siluf_(float x) { return x * __builtin_amdgcn_rcpf(1.0f + __expf(-x)); }
;   __device__ __forceinline__ void operator()(EPI_ARGS) const {
;     ...
;     for (int bj = 0; bj < 2; ++bj) {
;       const int c = col0 + bj * HALF;
;       const f32x4 s0 = *(const f32x4*)(psc + c), s1 = *(const f32x4*)(psc + c + 4);
; #pragma unroll
;       for (int ai = 0; ai < 2; ++ai) {
;         u32x4 z[4];
; #pragma unroll
;         for (int m = 0; m < 4; ++m) z[m] = *(const u32x4*)(proj + pidx(row0 + ai * HALF + m * 16, PZ + c));
;         __builtin_amdgcn_sched_barrier(0);
; #pragma unroll
;         for (int m = 0; m < 4; ++m) {
;           const size_t row = row0 + ai * HALF + m * 16;
;           const f32x4 v0 = acc[ai][bj][m][0], v1 = acc[ai][bj][m][1];
;           u32x4 o;
;           o.x = pack2(v0[0] * s0[0] * siluf_(bflo(z[m].x)), v0[1] * s0[1] * siluf_(bfhi(z[m].x)));
;           o.y = pack2(v0[2] * s0[2] * siluf_(bflo(z[m].y)), v0[3] * s0[3] * siluf_(bfhi(z[m].y)));
;           o.z = pack2(v1[0] * s1[0] * siluf_(bflo(z[m].z)), v1[1] * s1[1] * siluf_(bfhi(z[m].z)));
;           o.w = pack2(v1[2] * s1[2] * siluf_(bflo(z[m].w)), v1[3] * s1[3] * siluf_(bfhi(z[m].w)));
;           *(u32x4*)(y0 + row * DM + c) = o;
	v_cvt_pk_bf16_f32 v89, v2, v89
	v_mul_f32_e32 v2, 0xbfb8aa3b, v91
	v_exp_f32_e32 v2, v2
	v_mov_b32_e32 v98, v84
	v_mov_b32_e32 v90, v92
	v_add_f32_e32 v2, 1.0, v2
	v_rcp_f32_e32 v99, v2
	s_nop 0
	v_pk_mul_f32 v[90:91], v[98:99], v[90:91]
	s_nop 0
	v_mul_f32_e32 v2, v90, v91
	v_and_b32_e32 v91, 0xffff0000, v118
	v_mul_f32_e32 v84, 0xbfb8aa3b, v91
	v_exp_f32_e32 v84, v84
	v_mov_b32_e32 v98, v85
	v_mov_b32_e32 v90, v93
	v_add_f32_e32 v84, 1.0, v84
	v_rcp_f32_e32 v99, v84
	s_nop 0
	v_pk_mul_f32 v[84:85], v[98:99], v[90:91]
	s_nop 0
	v_mul_f32_e32 v84, v84, v85
	v_lshlrev_b32_e32 v85, 16, v119
	v_cvt_pk_bf16_f32 v90, v2, v84
	v_mul_f32_e32 v2, 0xbfb8aa3b, v85
	v_exp_f32_e32 v2, v2
	v_mov_b32_e32 v98, v86
	v_mov_b32_e32 v84, v94
	v_mov_b32_e32 v86, v80
	v_add_f32_e32 v2, 1.0, v2
	v_rcp_f32_e32 v99, v2
	s_nop 0
	v_pk_mul_f32 v[84:85], v[98:99], v[84:85]
	s_nop 0
	v_mul_f32_e32 v2, v84, v85
	v_and_b32_e32 v85, 0xffff0000, v119
	v_mul_f32_e32 v84, 0xbfb8aa3b, v85
	v_exp_f32_e32 v84, v84
	v_mov_b32_e32 v98, v87
	v_add_f32_e32 v84, 1.0, v84
	v_rcp_f32_e32 v99, v84
	v_mov_b32_e32 v84, v95
	v_pk_mul_f32 v[84:85], v[98:99], v[84:85]
	s_nop 0
	v_mul_f32_e32 v84, v84, v85
	v_cvt_pk_bf16_f32 v91, v2, v84
	v_lshlrev_b64 v[84:85], 12, v[146:147]
	v_lshl_add_u64 v[84:85], s[8:9], 0, v[84:85]
	v_lshl_add_u64 v[98:99], v[84:85], 0, v[140:141]
	v_lshlrev_b32_e32 v85, 16, v112
	v_mul_f32_e32 v2, 0xbfb8aa3b, v85
	v_exp_f32_e32 v2, v2
	v_mov_b32_e32 v84, v100
	flat_store_dwordx4 v[98:99], v[88:91]
	v_add_f32_e32 v2, 1.0, v2
	v_rcp_f32_e32 v87, v2
	s_nop 0
	v_pk_mul_f32 v[84:85], v[86:87], v[84:85]
	s_nop 0
	v_mul_f32_e32 v2, v84, v85
	v_and_b32_e32 v85, 0xffff0000, v112
	v_mul_f32_e32 v80, 0xbfb8aa3b, v85
	v_exp_f32_e32 v80, v80
	v_mov_b32_e32 v86, v81
	v_mov_b32_e32 v84, v101
	v_add_f32_e32 v80, 1.0, v80
	v_rcp_f32_e32 v87, v80
	s_nop 0
	v_pk_mul_f32 v[80:81], v[86:87], v[84:85]
	s_nop 0
	v_mul_f32_e32 v80, v80, v81
	v_lshlrev_b32_e32 v85, 16, v113
	v_cvt_pk_bf16_f32 v80, v2, v80
	v_mul_f32_e32 v2, 0xbfb8aa3b, v85
	v_exp_f32_e32 v2, v2
	v_mov_b32_e32 v86, v82
	v_mov_b32_e32 v84, v102
	v_add_f32_e32 v2, 1.0, v2
	v_rcp_f32_e32 v87, v2
	s_nop 0
	v_pk_mul_f32 v[84:85], v[86:87], v[84:85]
	s_nop 0
	v_mul_f32_e32 v2, v84, v85
	v_and_b32_e32 v85, 0xffff0000, v113
	v_mul_f32_e32 v81, 0xbfb8aa3b, v85
	v_exp_f32_e32 v81, v81
	v_mov_b32_e32 v86, v83
	v_mov_b32_e32 v84, v103
	v_add_f32_e32 v81, 1.0, v81
	v_rcp_f32_e32 v87, v81
	s_nop 0
	v_pk_mul_f32 v[82:83], v[86:87], v[84:85]
	s_nop 0
	v_mul_f32_e32 v81, v82, v83
	v_lshlrev_b32_e32 v83, 16, v114
	v_cvt_pk_bf16_f32 v81, v2, v81
	v_mul_f32_e32 v2, 0xbfb8aa3b, v83
	v_exp_f32_e32 v2, v2
	v_mov_b32_e32 v84, v76
	v_mov_b32_e32 v82, v92
	v_add_f32_e32 v2, 1.0, v2
	v_rcp_f32_e32 v85, v2
	s_nop 0
	v_pk_mul_f32 v[82:83], v[84:85], v[82:83]
	s_nop 0
	v_mul_f32_e32 v2, v82, v83
	v_and_b32_e32 v83, 0xffff0000, v114
	v_mul_f32_e32 v76, 0xbfb8aa3b, v83
	v_exp_f32_e32 v76, v76
	v_mov_b32_e32 v84, v77
	v_mov_b32_e32 v82, v93
	v_add_f32_e32 v76, 1.0, v76
	v_rcp_f32_e32 v85, v76
	s_nop 0
	v_pk_mul_f32 v[76:77], v[84:85], v[82:83]
	s_nop 0
	v_mul_f32_e32 v76, v76, v77
	v_lshlrev_b32_e32 v77, 16, v115
	v_cvt_pk_bf16_f32 v82, v2, v76
	v_mul_f32_e32 v2, 0xbfb8aa3b, v77
	v_exp_f32_e32 v2, v2
	v_mov_b32_e32 v84, v78
	v_mov_b32_e32 v76, v94
	v_mov_b32_e32 v78, v72
	v_add_f32_e32 v2, 1.0, v2
	v_rcp_f32_e32 v85, v2
	s_nop 0
	v_pk_mul_f32 v[76:77], v[84:85], v[76:77]
	s_nop 0
	v_mul_f32_e32 v2, v76, v77
	v_and_b32_e32 v77, 0xffff0000, v115
	v_mul_f32_e32 v76, 0xbfb8aa3b, v77
	v_exp_f32_e32 v76, v76
	v_mov_b32_e32 v84, v79
	v_add_f32_e32 v76, 1.0, v76
	v_rcp_f32_e32 v85, v76
	v_mov_b32_e32 v76, v95
	v_pk_mul_f32 v[76:77], v[84:85], v[76:77]
	s_nop 0
	v_mul_f32_e32 v76, v76, v77
	v_cvt_pk_bf16_f32 v83, v2, v76
	v_lshlrev_b64 v[76:77], 12, v[144:145]
	v_lshl_add_u64 v[76:77], s[8:9], 0, v[76:77]
	v_lshl_add_u64 v[104:105], v[76:77], 0, v[140:141]
	v_lshlrev_b32_e32 v77, 16, v108
	v_mul_f32_e32 v2, 0xbfb8aa3b, v77
	v_exp_f32_e32 v2, v2
	v_mov_b32_e32 v76, v100
	flat_store_dwordx4 v[104:105], v[80:83]
	v_add_f32_e32 v2, 1.0, v2
	v_rcp_f32_e32 v79, v2
	s_nop 0
	v_pk_mul_f32 v[76:77], v[78:79], v[76:77]
	s_nop 0
	v_mul_f32_e32 v2, v76, v77
	v_and_b32_e32 v77, 0xffff0000, v108
	v_mul_f32_e32 v72, 0xbfb8aa3b, v77
	v_exp_f32_e32 v72, v72
	v_mov_b32_e32 v78, v73
	v_mov_b32_e32 v76, v101
	v_add_f32_e32 v72, 1.0, v72
	v_rcp_f32_e32 v79, v72
	s_nop 0
	v_pk_mul_f32 v[72:73], v[78:79], v[76:77]
	s_nop 0
	v_mul_f32_e32 v72, v72, v73
	v_lshlrev_b32_e32 v77, 16, v109
	v_cvt_pk_bf16_f32 v72, v2, v72
	v_mul_f32_e32 v2, 0xbfb8aa3b, v77
	v_exp_f32_e32 v2, v2
	v_mov_b32_e32 v78, v74
	v_mov_b32_e32 v76, v102
	v_add_f32_e32 v2, 1.0, v2
	v_rcp_f32_e32 v79, v2
	s_nop 0
	v_pk_mul_f32 v[76:77], v[78:79], v[76:77]
	s_nop 0
	v_mul_f32_e32 v2, v76, v77
	v_and_b32_e32 v77, 0xffff0000, v109
	v_mul_f32_e32 v73, 0xbfb8aa3b, v77
	v_exp_f32_e32 v73, v73
	v_mov_b32_e32 v78, v75
	v_mov_b32_e32 v76, v103
	v_add_f32_e32 v73, 1.0, v73
	v_rcp_f32_e32 v79, v73
	s_nop 0
	v_pk_mul_f32 v[74:75], v[78:79], v[76:77]
	s_nop 0
	v_mul_f32_e32 v73, v74, v75
	v_lshlrev_b32_e32 v75, 16, v110
	v_cvt_pk_bf16_f32 v73, v2, v73
	v_mul_f32_e32 v2, 0xbfb8aa3b, v75
	v_exp_f32_e32 v2, v2
	v_mov_b32_e32 v76, v68
	v_mov_b32_e32 v74, v92
	v_add_f32_e32 v2, 1.0, v2
	v_rcp_f32_e32 v77, v2
	s_nop 0
	v_pk_mul_f32 v[74:75], v[76:77], v[74:75]
	s_nop 0
	v_mul_f32_e32 v2, v74, v75
	v_and_b32_e32 v75, 0xffff0000, v110
	v_mul_f32_e32 v68, 0xbfb8aa3b, v75
	v_exp_f32_e32 v68, v68
	v_mov_b32_e32 v76, v69
	v_mov_b32_e32 v74, v93
	v_add_f32_e32 v68, 1.0, v68
	v_rcp_f32_e32 v77, v68
	s_nop 0
	v_pk_mul_f32 v[68:69], v[76:77], v[74:75]
	s_nop 0
	v_mul_f32_e32 v68, v68, v69
	v_lshlrev_b32_e32 v69, 16, v111
	v_cvt_pk_bf16_f32 v74, v2, v68
	v_mul_f32_e32 v2, 0xbfb8aa3b, v69
	v_exp_f32_e32 v2, v2
	v_mov_b32_e32 v76, v70
	v_mov_b32_e32 v68, v94
	v_add_f32_e32 v2, 1.0, v2
	v_rcp_f32_e32 v77, v2
	s_nop 0
	v_pk_mul_f32 v[68:69], v[76:77], v[68:69]
	s_nop 0
	v_mul_f32_e32 v2, v68, v69
	v_and_b32_e32 v69, 0xffff0000, v111
	v_mul_f32_e32 v68, 0xbfb8aa3b, v69
	v_exp_f32_e32 v68, v68
	v_mov_b32_e32 v76, v71
	v_add_f32_e32 v68, 1.0, v68
	v_rcp_f32_e32 v77, v68
	v_mov_b32_e32 v68, v95
	v_lshl_add_u64 v[94:95], s[2:3], 0, v[174:175]
	v_pk_mul_f32 v[68:69], v[76:77], v[68:69]
	s_nop 0
	v_mul_f32_e32 v68, v68, v69
	v_cvt_pk_bf16_f32 v75, v2, v68
	v_lshlrev_b64 v[68:69], 12, v[142:143]
	v_lshl_add_u64 v[68:69], s[8:9], 0, v[68:69]
	v_lshl_add_u64 v[92:93], v[68:69], 0, v[140:141]
	flat_store_dwordx4 v[92:93], v[72:75]
	v_lshl_add_u64 v[76:77], v[94:95], 0, v[178:179]
	global_load_dwordx4 v[68:71], v[176:177], off offset:528
	global_load_dwordx4 v[72:75], v[176:177], off offset:512
	flat_load_dwordx4 v[88:91], v[76:77]
	v_lshl_add_u64 v[76:77], v[94:95], 0, v[180:181]
	flat_load_dwordx4 v[84:87], v[76:77]
	v_lshl_add_u64 v[76:77], v[94:95], 0, v[182:183]
	flat_load_dwordx4 v[80:83], v[76:77]
	v_lshl_add_u64 v[76:77], v[94:95], 0, v[184:185]
	flat_load_dwordx4 v[76:79], v[76:77]
	s_waitcnt vmcnt(0) lgkmcnt(0)
; __device__ __forceinline__ float bflo(unsigned v) { return __uint_as_float(v << 16); }
; __device__ __forceinline__ float bfhi(unsigned v) { return __uint_as_float(v & 0xffff0000u); }
; __device__ __forceinline__ float siluf_(float x) { return x * __builtin_amdgcn_rcpf(1.0f + __expf(-x)); }
;   __device__ __forceinline__ void operator()(EPI_ARGS) const {
;     ...
;         for (int m = 0; m < 4; ++m) {
;           const size_t row = row0 + ai * HALF + m * 16;
;           const f32x4 v0 = acc[ai][bj][m][0], v1 = acc[ai][bj][m][1];
;           u32x4 o;
;           o.x = pack2(v0[0] * s0[0] * siluf_(bflo(z[m].x)), v0[1] * s0[1] * siluf_(bfhi(z[m].x)));
;           o.y = pack2(v0[2] * s0[2] * siluf_(bflo(z[m].y)), v0[3] * s0[3] * siluf_(bfhi(z[m].y)));
;           o.z = pack2(v1[0] * s1[0] * siluf_(bflo(z[m].z)), v1[1] * s1[1] * siluf_(bfhi(z[m].z)));
;           o.w = pack2(v1[2] * s1[2] * siluf_(bflo(z[m].w)), v1[3] * s1[3] * siluf_(bfhi(z[m].w)));
;           *(u32x4*)(y0 + row * DM + c) = o;
;         }
	v_lshlrev_b32_e32 v101, 16, v88
	v_mul_f32_e32 v2, 0xbfb8aa3b, v101
	v_exp_f32_e32 v2, v2
	v_mov_b32_e32 v102, v64
	v_mov_b32_e32 v100, v72
	v_add_f32_e32 v2, 1.0, v2
	v_rcp_f32_e32 v103, v2
	s_nop 0
	v_pk_mul_f32 v[100:101], v[102:103], v[100:101]
	s_nop 0
	v_mul_f32_e32 v2, v100, v101
	v_and_b32_e32 v101, 0xffff0000, v88
	v_mul_f32_e32 v64, 0xbfb8aa3b, v101
	v_exp_f32_e32 v64, v64
	v_mov_b32_e32 v102, v65
	v_mov_b32_e32 v100, v73
	v_mov_b32_e32 v88, v75
	v_add_f32_e32 v64, 1.0, v64
	v_rcp_f32_e32 v103, v64
	s_nop 0
	v_pk_mul_f32 v[64:65], v[102:103], v[100:101]
	s_nop 0
	v_mul_f32_e32 v64, v64, v65
	v_lshlrev_b32_e32 v101, 16, v89
	v_cvt_pk_bf16_f32 v64, v2, v64
	v_mul_f32_e32 v2, 0xbfb8aa3b, v101
	v_exp_f32_e32 v2, v2
	v_and_b32_e32 v89, 0xffff0000, v89
	v_mul_f32_e32 v65, 0xbfb8aa3b, v89
	v_exp_f32_e32 v65, v65
	v_add_f32_e32 v2, 1.0, v2
	v_rcp_f32_e32 v103, v2
	v_mov_b32_e32 v102, v66
	v_mov_b32_e32 v100, v74
	v_add_f32_e32 v65, 1.0, v65
	v_pk_mul_f32 v[100:101], v[102:103], v[100:101]
	s_nop 0
	v_mul_f32_e32 v2, v100, v101
	v_rcp_f32_e32 v101, v65
	v_mov_b32_e32 v100, v67
	v_pk_mul_f32 v[66:67], v[100:101], v[88:89]
	s_nop 0
	v_mul_f32_e32 v65, v66, v67
	v_lshlrev_b32_e32 v67, 16, v90
	v_cvt_pk_bf16_f32 v65, v2, v65
	v_mul_f32_e32 v2, 0xbfb8aa3b, v67
	v_exp_f32_e32 v2, v2
	v_mov_b32_e32 v88, v60
	v_mov_b32_e32 v66, v68
	v_add_f32_e32 v2, 1.0, v2
	v_rcp_f32_e32 v89, v2
	s_nop 0
	v_pk_mul_f32 v[66:67], v[88:89], v[66:67]
	s_nop 0
	v_mul_f32_e32 v2, v66, v67
	v_and_b32_e32 v67, 0xffff0000, v90
	v_mul_f32_e32 v60, 0xbfb8aa3b, v67
	v_exp_f32_e32 v60, v60
	v_mov_b32_e32 v88, v61
	v_mov_b32_e32 v66, v69
	v_add_f32_e32 v60, 1.0, v60
	v_rcp_f32_e32 v89, v60
	s_nop 0
	v_pk_mul_f32 v[60:61], v[88:89], v[66:67]
	s_nop 0
	v_mul_f32_e32 v60, v60, v61
	v_lshlrev_b32_e32 v61, 16, v91
	v_cvt_pk_bf16_f32 v66, v2, v60
	v_mul_f32_e32 v2, 0xbfb8aa3b, v61
	v_exp_f32_e32 v2, v2
	v_mov_b32_e32 v88, v62
	v_mov_b32_e32 v60, v70
	v_mov_b32_e32 v62, v56
	v_add_f32_e32 v2, 1.0, v2
	v_rcp_f32_e32 v89, v2
	s_nop 0
	v_pk_mul_f32 v[60:61], v[88:89], v[60:61]
	s_nop 0
	v_mul_f32_e32 v2, v60, v61
	v_and_b32_e32 v61, 0xffff0000, v91
	v_mul_f32_e32 v60, 0xbfb8aa3b, v61
	v_exp_f32_e32 v60, v60
	v_mov_b32_e32 v88, v63
	v_add_f32_e32 v60, 1.0, v60
	v_rcp_f32_e32 v89, v60
	v_mov_b32_e32 v60, v71
	v_pk_mul_f32 v[60:61], v[88:89], v[60:61]
	s_nop 0
	v_mul_f32_e32 v60, v60, v61
	v_lshlrev_b32_e32 v61, 16, v84
	v_cvt_pk_bf16_f32 v67, v2, v60
	v_mul_f32_e32 v2, 0xbfb8aa3b, v61
	v_exp_f32_e32 v2, v2
	v_mov_b32_e32 v60, v72
	flat_store_dwordx4 v[136:137], v[64:67] offset:256
	v_add_f32_e32 v2, 1.0, v2
	v_rcp_f32_e32 v63, v2
	s_nop 0
	v_pk_mul_f32 v[60:61], v[62:63], v[60:61]
	s_nop 0
	v_mul_f32_e32 v2, v60, v61
	v_and_b32_e32 v61, 0xffff0000, v84
	v_mul_f32_e32 v56, 0xbfb8aa3b, v61
	v_exp_f32_e32 v56, v56
	v_mov_b32_e32 v62, v57
	v_mov_b32_e32 v60, v73
	v_add_f32_e32 v56, 1.0, v56
	v_rcp_f32_e32 v63, v56
	s_nop 0
	v_pk_mul_f32 v[56:57], v[62:63], v[60:61]
	s_nop 0
	v_mul_f32_e32 v56, v56, v57
	v_lshlrev_b32_e32 v61, 16, v85
	v_cvt_pk_bf16_f32 v56, v2, v56
	v_mul_f32_e32 v2, 0xbfb8aa3b, v61
	v_exp_f32_e32 v2, v2
	v_mov_b32_e32 v62, v58
	v_mov_b32_e32 v60, v74
	v_add_f32_e32 v2, 1.0, v2
	v_rcp_f32_e32 v63, v2
	s_nop 0
	v_pk_mul_f32 v[60:61], v[62:63], v[60:61]
	s_nop 0
	v_mul_f32_e32 v2, v60, v61
	v_and_b32_e32 v61, 0xffff0000, v85
	v_mul_f32_e32 v57, 0xbfb8aa3b, v61
	v_exp_f32_e32 v57, v57
	v_mov_b32_e32 v62, v59
	v_mov_b32_e32 v60, v75
	v_add_f32_e32 v57, 1.0, v57
	v_rcp_f32_e32 v63, v57
	s_nop 0
	v_pk_mul_f32 v[58:59], v[62:63], v[60:61]
	s_nop 0
	v_mul_f32_e32 v57, v58, v59
	v_lshlrev_b32_e32 v59, 16, v86
	v_cvt_pk_bf16_f32 v57, v2, v57
	v_mul_f32_e32 v2, 0xbfb8aa3b, v59
	v_exp_f32_e32 v2, v2
	v_mov_b32_e32 v60, v52
	v_mov_b32_e32 v58, v68
	v_add_f32_e32 v2, 1.0, v2
	v_rcp_f32_e32 v61, v2
	s_nop 0
	v_pk_mul_f32 v[58:59], v[60:61], v[58:59]
	s_nop 0
	v_mul_f32_e32 v2, v58, v59
	v_and_b32_e32 v59, 0xffff0000, v86
	v_mul_f32_e32 v52, 0xbfb8aa3b, v59
	v_exp_f32_e32 v52, v52
	v_mov_b32_e32 v60, v53
	v_mov_b32_e32 v58, v69
	v_add_f32_e32 v52, 1.0, v52
	v_rcp_f32_e32 v61, v52
	s_nop 0
	v_pk_mul_f32 v[52:53], v[60:61], v[58:59]
	s_nop 0
	v_mul_f32_e32 v52, v52, v53
	v_lshlrev_b32_e32 v53, 16, v87
	v_cvt_pk_bf16_f32 v58, v2, v52
	v_mul_f32_e32 v2, 0xbfb8aa3b, v53
	v_exp_f32_e32 v2, v2
	v_mov_b32_e32 v60, v54
	v_mov_b32_e32 v52, v70
	v_mov_b32_e32 v54, v48
	v_add_f32_e32 v2, 1.0, v2
	v_rcp_f32_e32 v61, v2
	s_nop 0
	v_pk_mul_f32 v[52:53], v[60:61], v[52:53]
	s_nop 0
	v_mul_f32_e32 v2, v52, v53
	v_and_b32_e32 v53, 0xffff0000, v87
	v_mul_f32_e32 v52, 0xbfb8aa3b, v53
	v_exp_f32_e32 v52, v52
	v_mov_b32_e32 v60, v55
	v_add_f32_e32 v52, 1.0, v52
	v_rcp_f32_e32 v61, v52
	v_mov_b32_e32 v52, v71
	v_pk_mul_f32 v[52:53], v[60:61], v[52:53]
	s_nop 0
	v_mul_f32_e32 v52, v52, v53
	v_lshlrev_b32_e32 v53, 16, v80
	v_cvt_pk_bf16_f32 v59, v2, v52
	v_mul_f32_e32 v2, 0xbfb8aa3b, v53
	v_exp_f32_e32 v2, v2
	v_mov_b32_e32 v52, v72
	flat_store_dwordx4 v[124:125], v[56:59] offset:256
	v_add_f32_e32 v2, 1.0, v2
	v_rcp_f32_e32 v55, v2
	s_nop 0
	v_pk_mul_f32 v[52:53], v[54:55], v[52:53]
	s_nop 0
	v_mul_f32_e32 v2, v52, v53
	v_and_b32_e32 v53, 0xffff0000, v80
	v_mul_f32_e32 v48, 0xbfb8aa3b, v53
	v_exp_f32_e32 v48, v48
	v_mov_b32_e32 v54, v49
	v_mov_b32_e32 v52, v73
	v_add_f32_e32 v48, 1.0, v48
	v_rcp_f32_e32 v55, v48
	s_nop 0
	v_pk_mul_f32 v[48:49], v[54:55], v[52:53]
	s_nop 0
	v_mul_f32_e32 v48, v48, v49
	v_lshlrev_b32_e32 v53, 16, v81
	v_cvt_pk_bf16_f32 v48, v2, v48
	v_mul_f32_e32 v2, 0xbfb8aa3b, v53
	v_exp_f32_e32 v2, v2
	v_mov_b32_e32 v54, v50
	v_mov_b32_e32 v52, v74
	v_add_f32_e32 v2, 1.0, v2
	v_rcp_f32_e32 v55, v2
; __device__ __forceinline__ float bflo(unsigned v) { return __uint_as_float(v << 16); }
; __device__ __forceinline__ float bfhi(unsigned v) { return __uint_as_float(v & 0xffff0000u); }
; __device__ __forceinline__ float siluf_(float x) { return x * __builtin_amdgcn_rcpf(1.0f + __expf(-x)); }
;   __device__ __forceinline__ void operator()(EPI_ARGS) const {
;     ...
;         for (int m = 0; m < 4; ++m) {
;           const size_t row = row0 + ai * HALF + m * 16;
;           const f32x4 v0 = acc[ai][bj][m][0], v1 = acc[ai][bj][m][1];
;           u32x4 o;
;           o.x = pack2(v0[0] * s0[0] * siluf_(bflo(z[m].x)), v0[1] * s0[1] * siluf_(bfhi(z[m].x)));
;           o.y = pack2(v0[2] * s0[2] * siluf_(bflo(z[m].y)), v0[3] * s0[3] * siluf_(bfhi(z[m].y)));
;           o.z = pack2(v1[0] * s1[0] * siluf_(bflo(z[m].z)), v1[1] * s1[1] * siluf_(bfhi(z[m].z)));
;           o.w = pack2(v1[2] * s1[2] * siluf_(bflo(z[m].w)), v1[3] * s1[3] * siluf_(bfhi(z[m].w)));
;           *(u32x4*)(y0 + row * DM + c) = o;
;         }
	s_nop 0
	v_pk_mul_f32 v[52:53], v[54:55], v[52:53]
	s_nop 0
	v_mul_f32_e32 v2, v52, v53
	v_and_b32_e32 v53, 0xffff0000, v81
	v_mul_f32_e32 v49, 0xbfb8aa3b, v53
	v_exp_f32_e32 v49, v49
	v_mov_b32_e32 v54, v51
	v_mov_b32_e32 v52, v75
	v_add_f32_e32 v49, 1.0, v49
	v_rcp_f32_e32 v55, v49
	s_nop 0
	v_pk_mul_f32 v[50:51], v[54:55], v[52:53]
	s_nop 0
	v_mul_f32_e32 v49, v50, v51
	v_lshlrev_b32_e32 v51, 16, v82
	v_cvt_pk_bf16_f32 v49, v2, v49
	v_mul_f32_e32 v2, 0xbfb8aa3b, v51
	v_exp_f32_e32 v2, v2
	v_mov_b32_e32 v52, v44
	v_mov_b32_e32 v50, v68
	v_add_f32_e32 v2, 1.0, v2
	v_rcp_f32_e32 v53, v2
	s_nop 0
	v_pk_mul_f32 v[50:51], v[52:53], v[50:51]
	s_nop 0
	v_mul_f32_e32 v2, v50, v51
	v_and_b32_e32 v51, 0xffff0000, v82
	v_mul_f32_e32 v44, 0xbfb8aa3b, v51
	v_exp_f32_e32 v44, v44
	v_mov_b32_e32 v52, v45
	v_mov_b32_e32 v50, v69
	v_add_f32_e32 v44, 1.0, v44
	v_rcp_f32_e32 v53, v44
	s_nop 0
	v_pk_mul_f32 v[44:45], v[52:53], v[50:51]
	s_nop 0
	v_mul_f32_e32 v44, v44, v45
	v_lshlrev_b32_e32 v45, 16, v83
	v_cvt_pk_bf16_f32 v50, v2, v44
	v_mul_f32_e32 v2, 0xbfb8aa3b, v45
	v_exp_f32_e32 v2, v2
	v_mov_b32_e32 v52, v46
	v_mov_b32_e32 v44, v70
	v_mov_b32_e32 v46, v40
	v_add_f32_e32 v2, 1.0, v2
	v_rcp_f32_e32 v53, v2
	s_nop 0
	v_pk_mul_f32 v[44:45], v[52:53], v[44:45]
	s_nop 0
	v_mul_f32_e32 v2, v44, v45
	v_and_b32_e32 v45, 0xffff0000, v83
	v_mul_f32_e32 v44, 0xbfb8aa3b, v45
	v_exp_f32_e32 v44, v44
	v_mov_b32_e32 v52, v47
	v_add_f32_e32 v44, 1.0, v44
	v_rcp_f32_e32 v53, v44
	v_mov_b32_e32 v44, v71
	v_pk_mul_f32 v[44:45], v[52:53], v[44:45]
	s_nop 0
	v_mul_f32_e32 v44, v44, v45
	v_lshlrev_b32_e32 v45, 16, v76
	v_cvt_pk_bf16_f32 v51, v2, v44
	v_mul_f32_e32 v2, 0xbfb8aa3b, v45
	v_exp_f32_e32 v2, v2
	v_mov_b32_e32 v44, v72
	flat_store_dwordx4 v[128:129], v[48:51] offset:256
	v_add_f32_e32 v2, 1.0, v2
	v_rcp_f32_e32 v47, v2
	s_nop 0
	v_pk_mul_f32 v[44:45], v[46:47], v[44:45]
	s_nop 0
	v_mul_f32_e32 v2, v44, v45
	v_and_b32_e32 v45, 0xffff0000, v76
	v_mul_f32_e32 v40, 0xbfb8aa3b, v45
	v_exp_f32_e32 v40, v40
	v_mov_b32_e32 v46, v41
	v_mov_b32_e32 v44, v73
	v_add_f32_e32 v40, 1.0, v40
	v_rcp_f32_e32 v47, v40
	s_nop 0
	v_pk_mul_f32 v[40:41], v[46:47], v[44:45]
	s_nop 0
	v_mul_f32_e32 v40, v40, v41
	v_lshlrev_b32_e32 v45, 16, v77
	v_cvt_pk_bf16_f32 v40, v2, v40
	v_mul_f32_e32 v2, 0xbfb8aa3b, v45
	v_exp_f32_e32 v2, v2
	v_mov_b32_e32 v46, v42
	v_mov_b32_e32 v44, v74
	v_add_f32_e32 v2, 1.0, v2
	v_rcp_f32_e32 v47, v2
	s_nop 0
	v_pk_mul_f32 v[44:45], v[46:47], v[44:45]
	s_nop 0
	v_mul_f32_e32 v2, v44, v45
	v_and_b32_e32 v45, 0xffff0000, v77
	v_mul_f32_e32 v41, 0xbfb8aa3b, v45
	v_exp_f32_e32 v41, v41
	v_mov_b32_e32 v46, v43
	v_mov_b32_e32 v44, v75
	v_add_f32_e32 v41, 1.0, v41
	v_rcp_f32_e32 v47, v41
	s_nop 0
	v_pk_mul_f32 v[42:43], v[46:47], v[44:45]
	s_nop 0
	v_mul_f32_e32 v41, v42, v43
	v_lshlrev_b32_e32 v43, 16, v78
	v_cvt_pk_bf16_f32 v41, v2, v41
	v_mul_f32_e32 v2, 0xbfb8aa3b, v43
	v_exp_f32_e32 v2, v2
	v_mov_b32_e32 v44, v36
	v_mov_b32_e32 v42, v68
	v_add_f32_e32 v2, 1.0, v2
	v_rcp_f32_e32 v45, v2
	s_nop 0
	v_pk_mul_f32 v[42:43], v[44:45], v[42:43]
	s_nop 0
	v_mul_f32_e32 v2, v42, v43
	v_and_b32_e32 v43, 0xffff0000, v78
	v_mul_f32_e32 v36, 0xbfb8aa3b, v43
	v_exp_f32_e32 v36, v36
	v_mov_b32_e32 v44, v37
	v_mov_b32_e32 v42, v69
	v_add_f32_e32 v36, 1.0, v36
	v_rcp_f32_e32 v45, v36
	s_nop 0
	v_pk_mul_f32 v[36:37], v[44:45], v[42:43]
	s_nop 0
	v_mul_f32_e32 v36, v36, v37
	v_lshlrev_b32_e32 v37, 16, v79
	v_cvt_pk_bf16_f32 v42, v2, v36
	v_mul_f32_e32 v2, 0xbfb8aa3b, v37
	v_exp_f32_e32 v2, v2
	v_mov_b32_e32 v44, v38
	v_mov_b32_e32 v36, v70
	v_add_f32_e32 v2, 1.0, v2
	v_rcp_f32_e32 v45, v2
	s_nop 0
	v_pk_mul_f32 v[36:37], v[44:45], v[36:37]
	s_nop 0
	v_mul_f32_e32 v2, v36, v37
	v_and_b32_e32 v37, 0xffff0000, v79
	v_mul_f32_e32 v36, 0xbfb8aa3b, v37
	v_exp_f32_e32 v36, v36
	v_mov_b32_e32 v44, v39
	v_add_f32_e32 v36, 1.0, v36
	v_rcp_f32_e32 v45, v36
	v_mov_b32_e32 v36, v71
	v_pk_mul_f32 v[36:37], v[44:45], v[36:37]
	s_nop 0
	v_mul_f32_e32 v36, v36, v37
	v_cvt_pk_bf16_f32 v43, v2, v36
	flat_store_dwordx4 v[126:127], v[40:43] offset:256
	v_lshl_add_u64 v[36:37], v[94:95], 0, v[130:131]
	flat_load_dwordx4 v[48:51], v[36:37]
	v_lshl_add_u64 v[36:37], v[94:95], 0, v[132:133]
	flat_load_dwordx4 v[44:47], v[36:37]
	v_lshl_add_u64 v[36:37], v[94:95], 0, v[134:135]
	flat_load_dwordx4 v[40:43], v[36:37]
	v_lshl_add_u64 v[36:37], v[94:95], 0, v[138:139]
	flat_load_dwordx4 v[36:39], v[36:37]
	s_waitcnt vmcnt(0) lgkmcnt(0)
; __device__ __forceinline__ float bflo(unsigned v) { return __uint_as_float(v << 16); }
; __device__ __forceinline__ float bfhi(unsigned v) { return __uint_as_float(v & 0xffff0000u); }
; __device__ __forceinline__ float siluf_(float x) { return x * __builtin_amdgcn_rcpf(1.0f + __expf(-x)); }
;   __device__ __forceinline__ void operator()(EPI_ARGS) const {
;     ...
;         for (int m = 0; m < 4; ++m) {
;           const size_t row = row0 + ai * HALF + m * 16;
;           const f32x4 v0 = acc[ai][bj][m][0], v1 = acc[ai][bj][m][1];
;           u32x4 o;
;           o.x = pack2(v0[0] * s0[0] * siluf_(bflo(z[m].x)), v0[1] * s0[1] * siluf_(bfhi(z[m].x)));
;           o.y = pack2(v0[2] * s0[2] * siluf_(bflo(z[m].y)), v0[3] * s0[3] * siluf_(bfhi(z[m].y)));
;           o.z = pack2(v1[0] * s1[0] * siluf_(bflo(z[m].z)), v1[1] * s1[1] * siluf_(bfhi(z[m].z)));
;           o.w = pack2(v1[2] * s1[2] * siluf_(bflo(z[m].w)), v1[3] * s1[3] * siluf_(bfhi(z[m].w)));
;           *(u32x4*)(y0 + row * DM + c) = o;
;         }
	v_lshlrev_b32_e32 v53, 16, v48
	v_mul_f32_e32 v2, 0xbfb8aa3b, v53
	v_exp_f32_e32 v2, v2
	v_mov_b32_e32 v54, v32
	v_mov_b32_e32 v52, v72
	s_and_b64 vcc, exec, s[18:19]
	v_add_f32_e32 v2, 1.0, v2
	v_rcp_f32_e32 v55, v2
	s_mov_b32 s33, s16
	s_mov_b32 s2, s14
	s_mov_b64 s[4:5], s[22:23]
	v_pk_mul_f32 v[52:53], v[54:55], v[52:53]
	v_mov_b32_e32 v54, v33
	v_mul_f32_e32 v2, v52, v53
	v_and_b32_e32 v53, 0xffff0000, v48
	v_mul_f32_e32 v32, 0xbfb8aa3b, v53
	v_exp_f32_e32 v32, v32
	v_mov_b32_e32 v52, v73
	v_mov_b32_e32 v48, v75
	s_mov_b64 s[6:7], s[20:21]
	v_add_f32_e32 v32, 1.0, v32
	v_rcp_f32_e32 v55, v32
	s_nop 0
	v_pk_mul_f32 v[32:33], v[54:55], v[52:53]
	s_nop 0
	v_mul_f32_e32 v32, v32, v33
	v_lshlrev_b32_e32 v53, 16, v49
	v_cvt_pk_bf16_f32 v32, v2, v32
	v_mul_f32_e32 v2, 0xbfb8aa3b, v53
	v_exp_f32_e32 v2, v2
	v_and_b32_e32 v49, 0xffff0000, v49
	v_mul_f32_e32 v33, 0xbfb8aa3b, v49
	v_exp_f32_e32 v33, v33
	v_add_f32_e32 v2, 1.0, v2
	v_rcp_f32_e32 v55, v2
	v_mov_b32_e32 v54, v34
	v_mov_b32_e32 v52, v74
	v_add_f32_e32 v33, 1.0, v33
	v_pk_mul_f32 v[52:53], v[54:55], v[52:53]
	s_nop 0
	v_mul_f32_e32 v2, v52, v53
	v_rcp_f32_e32 v53, v33
	v_mov_b32_e32 v52, v35
	v_pk_mul_f32 v[34:35], v[52:53], v[48:49]
	s_nop 0
	v_mul_f32_e32 v33, v34, v35
	v_lshlrev_b32_e32 v35, 16, v50
	v_cvt_pk_bf16_f32 v33, v2, v33
	v_mul_f32_e32 v2, 0xbfb8aa3b, v35
	v_exp_f32_e32 v2, v2
	v_mov_b32_e32 v48, v28
	v_mov_b32_e32 v34, v68
	v_add_f32_e32 v2, 1.0, v2
	v_rcp_f32_e32 v49, v2
	s_nop 0
	v_pk_mul_f32 v[34:35], v[48:49], v[34:35]
	s_nop 0
	v_mul_f32_e32 v2, v34, v35
	v_and_b32_e32 v35, 0xffff0000, v50
	v_mul_f32_e32 v28, 0xbfb8aa3b, v35
	v_exp_f32_e32 v28, v28
	v_mov_b32_e32 v48, v29
	v_mov_b32_e32 v34, v69
	v_add_f32_e32 v28, 1.0, v28
	v_rcp_f32_e32 v49, v28
	s_nop 0
	v_pk_mul_f32 v[28:29], v[48:49], v[34:35]
	s_nop 0
	v_mul_f32_e32 v28, v28, v29
	v_lshlrev_b32_e32 v29, 16, v51
	v_cvt_pk_bf16_f32 v34, v2, v28
	v_mul_f32_e32 v2, 0xbfb8aa3b, v29
	v_exp_f32_e32 v2, v2
	v_mov_b32_e32 v48, v30
	v_mov_b32_e32 v28, v70
	v_mov_b32_e32 v30, v24
	v_add_f32_e32 v2, 1.0, v2
	v_rcp_f32_e32 v49, v2
	s_nop 0
	v_pk_mul_f32 v[28:29], v[48:49], v[28:29]
	s_nop 0
	v_mul_f32_e32 v2, v28, v29
	v_and_b32_e32 v29, 0xffff0000, v51
	v_mul_f32_e32 v28, 0xbfb8aa3b, v29
	v_exp_f32_e32 v28, v28
	v_mov_b32_e32 v48, v31
	v_add_f32_e32 v28, 1.0, v28
	v_rcp_f32_e32 v49, v28
	v_mov_b32_e32 v28, v71
	v_pk_mul_f32 v[28:29], v[48:49], v[28:29]
	s_nop 0
	v_mul_f32_e32 v28, v28, v29
	v_lshlrev_b32_e32 v29, 16, v44
	v_cvt_pk_bf16_f32 v35, v2, v28
	v_mul_f32_e32 v2, 0xbfb8aa3b, v29
	v_exp_f32_e32 v2, v2
	v_mov_b32_e32 v28, v72
	flat_store_dwordx4 v[96:97], v[32:35] offset:256
	v_add_f32_e32 v2, 1.0, v2
	v_rcp_f32_e32 v31, v2
	s_nop 0
	v_pk_mul_f32 v[28:29], v[30:31], v[28:29]
	s_nop 0
	v_mul_f32_e32 v2, v28, v29
	v_and_b32_e32 v29, 0xffff0000, v44
	v_mul_f32_e32 v24, 0xbfb8aa3b, v29
	v_exp_f32_e32 v24, v24
	v_mov_b32_e32 v30, v25
	v_mov_b32_e32 v28, v73
	v_add_f32_e32 v24, 1.0, v24
	v_rcp_f32_e32 v31, v24
	s_nop 0
	v_pk_mul_f32 v[24:25], v[30:31], v[28:29]
	s_nop 0
	v_mul_f32_e32 v24, v24, v25
	v_lshlrev_b32_e32 v29, 16, v45
	v_cvt_pk_bf16_f32 v24, v2, v24
	v_mul_f32_e32 v2, 0xbfb8aa3b, v29
	v_exp_f32_e32 v2, v2
	v_mov_b32_e32 v30, v26
	v_mov_b32_e32 v28, v74
	v_add_f32_e32 v2, 1.0, v2
	v_rcp_f32_e32 v31, v2
	s_nop 0
	v_pk_mul_f32 v[28:29], v[30:31], v[28:29]
	s_nop 0
	v_mul_f32_e32 v2, v28, v29
	v_and_b32_e32 v29, 0xffff0000, v45
	v_mul_f32_e32 v25, 0xbfb8aa3b, v29
	v_exp_f32_e32 v25, v25
	v_mov_b32_e32 v30, v27
	v_mov_b32_e32 v28, v75
	v_add_f32_e32 v25, 1.0, v25
	v_rcp_f32_e32 v31, v25
	s_nop 0
	v_pk_mul_f32 v[26:27], v[30:31], v[28:29]
	s_nop 0
	v_mul_f32_e32 v25, v26, v27
	v_lshlrev_b32_e32 v27, 16, v46
	v_cvt_pk_bf16_f32 v25, v2, v25
	v_mul_f32_e32 v2, 0xbfb8aa3b, v27
	v_exp_f32_e32 v2, v2
	v_mov_b32_e32 v28, v20
	v_mov_b32_e32 v26, v68
	v_add_f32_e32 v2, 1.0, v2
	v_rcp_f32_e32 v29, v2
	s_nop 0
	v_pk_mul_f32 v[26:27], v[28:29], v[26:27]
	s_nop 0
	v_mul_f32_e32 v2, v26, v27
	v_and_b32_e32 v27, 0xffff0000, v46
	v_mul_f32_e32 v20, 0xbfb8aa3b, v27
	v_exp_f32_e32 v20, v20
	v_mov_b32_e32 v28, v21
	v_mov_b32_e32 v26, v69
	v_add_f32_e32 v20, 1.0, v20
	v_rcp_f32_e32 v29, v20
	s_nop 0
	v_pk_mul_f32 v[20:21], v[28:29], v[26:27]
	s_nop 0
	v_mul_f32_e32 v20, v20, v21
	v_lshlrev_b32_e32 v21, 16, v47
	v_cvt_pk_bf16_f32 v26, v2, v20
	v_mul_f32_e32 v2, 0xbfb8aa3b, v21
	v_exp_f32_e32 v2, v2
	v_mov_b32_e32 v28, v22
	v_mov_b32_e32 v20, v70
	v_mov_b32_e32 v22, v16
	v_add_f32_e32 v2, 1.0, v2
	v_rcp_f32_e32 v29, v2
	s_nop 0
	v_pk_mul_f32 v[20:21], v[28:29], v[20:21]
	s_nop 0
	v_mul_f32_e32 v2, v20, v21
	v_and_b32_e32 v21, 0xffff0000, v47
	v_mul_f32_e32 v20, 0xbfb8aa3b, v21
	v_exp_f32_e32 v20, v20
	v_mov_b32_e32 v28, v23
	v_add_f32_e32 v20, 1.0, v20
	v_rcp_f32_e32 v29, v20
	v_mov_b32_e32 v20, v71
	v_pk_mul_f32 v[20:21], v[28:29], v[20:21]
	s_nop 0
	v_mul_f32_e32 v20, v20, v21
	v_lshlrev_b32_e32 v21, 16, v40
	v_cvt_pk_bf16_f32 v27, v2, v20
	v_mul_f32_e32 v2, 0xbfb8aa3b, v21
	v_exp_f32_e32 v2, v2
	v_mov_b32_e32 v20, v72
	flat_store_dwordx4 v[98:99], v[24:27] offset:256
; __device__ __forceinline__ float bflo(unsigned v) { return __uint_as_float(v << 16); }
; __device__ __forceinline__ float bfhi(unsigned v) { return __uint_as_float(v & 0xffff0000u); }
; __device__ __forceinline__ float siluf_(float x) { return x * __builtin_amdgcn_rcpf(1.0f + __expf(-x)); }
; #define PG8_WAIT_V(n) asm volatile("s_waitcnt vmcnt(" #n ")" ::: "memory")
; #define PG8_BAR __builtin_amdgcn_s_barrier()
; template <class Epi, class AddrA, class AddrB>
; __device__ __forceinline__ void gemm_phase(const Sched S, const int lda, const int ldb, const int K, const AddrA addrA,
;                                            const AddrB addrB, const Epi E) {
;     ...
;   PG8_WAIT_V(0);
;   if (wr == 0) PG8_BAR;
;   PG8_BAR;
;   __device__ __forceinline__ void operator()(EPI_ARGS) const {
;     ...
;         for (int m = 0; m < 4; ++m) {
;           const size_t row = row0 + ai * HALF + m * 16;
;           const f32x4 v0 = acc[ai][bj][m][0], v1 = acc[ai][bj][m][1];
;           u32x4 o;
;           o.x = pack2(v0[0] * s0[0] * siluf_(bflo(z[m].x)), v0[1] * s0[1] * siluf_(bfhi(z[m].x)));
;           o.y = pack2(v0[2] * s0[2] * siluf_(bflo(z[m].y)), v0[3] * s0[3] * siluf_(bfhi(z[m].y)));
;           o.z = pack2(v1[0] * s1[0] * siluf_(bflo(z[m].z)), v1[1] * s1[1] * siluf_(bfhi(z[m].z)));
;           o.w = pack2(v1[2] * s1[2] * siluf_(bflo(z[m].w)), v1[3] * s1[3] * siluf_(bfhi(z[m].w)));
;           *(u32x4*)(y0 + row * DM + c) = o;
;         }
	v_add_f32_e32 v2, 1.0, v2
	v_rcp_f32_e32 v23, v2
	s_nop 0
	v_pk_mul_f32 v[20:21], v[22:23], v[20:21]
	s_nop 0
	v_mul_f32_e32 v2, v20, v21
	v_and_b32_e32 v21, 0xffff0000, v40
	v_mul_f32_e32 v16, 0xbfb8aa3b, v21
	v_exp_f32_e32 v16, v16
	v_mov_b32_e32 v22, v17
	v_mov_b32_e32 v20, v73
	v_add_f32_e32 v16, 1.0, v16
	v_rcp_f32_e32 v23, v16
	s_nop 0
	v_pk_mul_f32 v[16:17], v[22:23], v[20:21]
	s_nop 0
	v_mul_f32_e32 v16, v16, v17
	v_lshlrev_b32_e32 v21, 16, v41
	v_cvt_pk_bf16_f32 v16, v2, v16
	v_mul_f32_e32 v2, 0xbfb8aa3b, v21
	v_exp_f32_e32 v2, v2
	v_mov_b32_e32 v22, v18
	v_mov_b32_e32 v20, v74
	v_add_f32_e32 v2, 1.0, v2
	v_rcp_f32_e32 v23, v2
	s_nop 0
	v_pk_mul_f32 v[20:21], v[22:23], v[20:21]
	s_nop 0
	v_mul_f32_e32 v2, v20, v21
	v_and_b32_e32 v21, 0xffff0000, v41
	v_mul_f32_e32 v17, 0xbfb8aa3b, v21
	v_exp_f32_e32 v17, v17
	v_mov_b32_e32 v22, v19
	v_mov_b32_e32 v20, v75
	v_add_f32_e32 v17, 1.0, v17
	v_rcp_f32_e32 v23, v17
	s_nop 0
	v_pk_mul_f32 v[18:19], v[22:23], v[20:21]
	s_nop 0
	v_mul_f32_e32 v17, v18, v19
	v_lshlrev_b32_e32 v19, 16, v42
	v_cvt_pk_bf16_f32 v17, v2, v17
	v_mul_f32_e32 v2, 0xbfb8aa3b, v19
	v_exp_f32_e32 v2, v2
	v_mov_b32_e32 v20, v12
	v_mov_b32_e32 v18, v68
	v_add_f32_e32 v2, 1.0, v2
	v_rcp_f32_e32 v21, v2
	s_nop 0
	v_pk_mul_f32 v[18:19], v[20:21], v[18:19]
	s_nop 0
	v_mul_f32_e32 v2, v18, v19
	v_and_b32_e32 v19, 0xffff0000, v42
	v_mul_f32_e32 v12, 0xbfb8aa3b, v19
	v_exp_f32_e32 v12, v12
	v_mov_b32_e32 v20, v13
	v_mov_b32_e32 v18, v69
	v_add_f32_e32 v12, 1.0, v12
	v_rcp_f32_e32 v21, v12
	s_nop 0
	v_pk_mul_f32 v[12:13], v[20:21], v[18:19]
	s_nop 0
	v_mul_f32_e32 v12, v12, v13
	v_lshlrev_b32_e32 v13, 16, v43
	v_cvt_pk_bf16_f32 v18, v2, v12
	v_mul_f32_e32 v2, 0xbfb8aa3b, v13
	v_exp_f32_e32 v2, v2
	v_mov_b32_e32 v20, v14
	v_mov_b32_e32 v12, v70
	v_mov_b32_e32 v14, v8
	v_add_f32_e32 v2, 1.0, v2
	v_rcp_f32_e32 v21, v2
	s_nop 0
	v_pk_mul_f32 v[12:13], v[20:21], v[12:13]
	s_nop 0
	v_mul_f32_e32 v2, v12, v13
	v_and_b32_e32 v13, 0xffff0000, v43
	v_mul_f32_e32 v12, 0xbfb8aa3b, v13
	v_exp_f32_e32 v12, v12
	v_mov_b32_e32 v20, v15
	v_add_f32_e32 v12, 1.0, v12
	v_rcp_f32_e32 v21, v12
	v_mov_b32_e32 v12, v71
	v_pk_mul_f32 v[12:13], v[20:21], v[12:13]
	s_nop 0
	v_mul_f32_e32 v12, v12, v13
	v_lshlrev_b32_e32 v13, 16, v36
	v_cvt_pk_bf16_f32 v19, v2, v12
	v_mul_f32_e32 v2, 0xbfb8aa3b, v13
	v_exp_f32_e32 v2, v2
	v_mov_b32_e32 v12, v72
	flat_store_dwordx4 v[104:105], v[16:19] offset:256
	v_add_f32_e32 v2, 1.0, v2
	v_rcp_f32_e32 v15, v2
	s_nop 0
	v_pk_mul_f32 v[12:13], v[14:15], v[12:13]
	s_nop 0
	v_mul_f32_e32 v2, v12, v13
	v_and_b32_e32 v13, 0xffff0000, v36
	v_mul_f32_e32 v8, 0xbfb8aa3b, v13
	v_exp_f32_e32 v8, v8
	v_mov_b32_e32 v14, v9
	v_mov_b32_e32 v12, v73
	v_add_f32_e32 v8, 1.0, v8
	v_rcp_f32_e32 v15, v8
	s_nop 0
	v_pk_mul_f32 v[8:9], v[14:15], v[12:13]
	s_nop 0
	v_mul_f32_e32 v8, v8, v9
	v_lshlrev_b32_e32 v13, 16, v37
	v_cvt_pk_bf16_f32 v8, v2, v8
	v_mul_f32_e32 v2, 0xbfb8aa3b, v13
	v_exp_f32_e32 v2, v2
	v_mov_b32_e32 v14, v10
	v_mov_b32_e32 v12, v74
	v_add_f32_e32 v2, 1.0, v2
	v_rcp_f32_e32 v15, v2
	s_nop 0
	v_pk_mul_f32 v[12:13], v[14:15], v[12:13]
	s_nop 0
	v_mul_f32_e32 v2, v12, v13
	v_and_b32_e32 v13, 0xffff0000, v37
	v_mul_f32_e32 v9, 0xbfb8aa3b, v13
	v_exp_f32_e32 v9, v9
	v_mov_b32_e32 v14, v11
	v_mov_b32_e32 v12, v75
	v_add_f32_e32 v9, 1.0, v9
	v_rcp_f32_e32 v15, v9
	s_nop 0
	v_pk_mul_f32 v[10:11], v[14:15], v[12:13]
	s_nop 0
	v_mul_f32_e32 v9, v10, v11
	v_lshlrev_b32_e32 v11, 16, v38
	v_cvt_pk_bf16_f32 v9, v2, v9
	v_mul_f32_e32 v2, 0xbfb8aa3b, v11
	v_exp_f32_e32 v2, v2
	v_mov_b32_e32 v12, v4
	v_mov_b32_e32 v10, v68
	v_add_f32_e32 v2, 1.0, v2
	v_rcp_f32_e32 v13, v2
	s_nop 0
	v_pk_mul_f32 v[10:11], v[12:13], v[10:11]
	s_nop 0
	v_mul_f32_e32 v2, v10, v11
	v_and_b32_e32 v11, 0xffff0000, v38
	v_mul_f32_e32 v4, 0xbfb8aa3b, v11
	v_exp_f32_e32 v4, v4
	v_mov_b32_e32 v12, v5
	v_mov_b32_e32 v10, v69
	v_add_f32_e32 v4, 1.0, v4
	v_rcp_f32_e32 v13, v4
	s_nop 0
	v_pk_mul_f32 v[4:5], v[12:13], v[10:11]
	s_nop 0
	v_mul_f32_e32 v4, v4, v5
	v_lshlrev_b32_e32 v5, 16, v39
	v_cvt_pk_bf16_f32 v10, v2, v4
	v_mul_f32_e32 v2, 0xbfb8aa3b, v5
	v_exp_f32_e32 v2, v2
	v_mov_b32_e32 v12, v6
	v_mov_b32_e32 v4, v70
	v_add_f32_e32 v2, 1.0, v2
	v_rcp_f32_e32 v13, v2
	s_nop 0
	v_pk_mul_f32 v[4:5], v[12:13], v[4:5]
	s_nop 0
	v_mul_f32_e32 v2, v4, v5
	v_and_b32_e32 v5, 0xffff0000, v39
	v_mul_f32_e32 v4, 0xbfb8aa3b, v5
	v_exp_f32_e32 v4, v4
	v_mov_b32_e32 v12, v7
	v_add_f32_e32 v4, 1.0, v4
	v_rcp_f32_e32 v13, v4
	v_mov_b32_e32 v4, v71
	v_pk_mul_f32 v[4:5], v[12:13], v[4:5]
	s_nop 0
	v_mul_f32_e32 v4, v4, v5
	v_cvt_pk_bf16_f32 v11, v2, v4
	flat_store_dwordx4 v[92:93], v[8:11] offset:256
	s_cbranch_vccz .LBB0_482
	s_waitcnt vmcnt(0)
	v_readlane_b32 s44, v244, 59
	v_readlane_b32 s40, v243, 18
	s_cmpk_gt_u32 s24, 0xff
	s_mov_b32 s43, 0x800000
	v_readlane_b32 s45, v244, 60
	v_readlane_b32 s46, v244, 61
	v_readlane_b32 s47, v244, 62
	v_readlane_b32 s48, v244, 63
	v_readlane_b32 s49, v243, 0
	v_readlane_b32 s50, v243, 1
	v_readlane_b32 s51, v243, 2
	v_readlane_b32 s41, v243, 19
	s_cbranch_scc1 .LBB0_489
	s_barrier

; #define PG8_WAIT_V(n) asm volatile("s_waitcnt vmcnt(" #n ")" ::: "memory")
; #define PG8_WAIT_L(n) asm volatile("s_waitcnt lgkmcnt(" #n ")" ::: "memory")
; #define PG8_BAR __builtin_amdgcn_s_barrier()
; #define PG8_SCHED __builtin_amdgcn_sched_barrier(0)
; template <class Epi, class AddrA, class AddrB>
; __device__ __forceinline__ void gemm_phase(const Sched S, const int lda, const int ldb, const int K, const AddrA addrA,
;                                            const AddrB addrB, const Epi E) {
;     ...
;       PG8_LDB(B0, 0, 0); PG8_SCHED; PG8_LDA(At, 0, 0); PG8_STAGE(PG8_SA(1, 1), a1 + hstepA, voffA);
;       PG8_WAIT_L(8); PG8_BAR; PG8_WAIT_L(0); PG8_MMA(0, 0, At, B0); PG8_BAR; PG8_SCHED;
;       PG8_LDB(B1, 0, 1); PG8_STAGE(PG8_SB(0, 0), b2, voffB);
;       PG8_BAR; PG8_WAIT_L(0); PG8_MMA(0, 1, At, B1); PG8_BAR;
;       PG8_LDA(At, 0, 1); PG8_STAGE(PG8_SA(0, 0), a2, voffA);
;       PG8_BAR; PG8_WAIT_L(0); PG8_MMA(1, 0, At, B0); PG8_BAR; PG8_SCHED;
;       PG8_STAGE(PG8_SB(0, 1), b2 + hstepB, voffB);
;       PG8_WAIT_V(6); PG8_BAR; PG8_MMA(1, 1, At, B1); PG8_BAR;
;       PG8_LDB(B0, 1, 0); PG8_SCHED; PG8_LDA(At, 1, 0); PG8_STAGE(PG8_SA(0, 1), a2 + hstepA, voffA);
;       PG8_WAIT_L(8); PG8_BAR; PG8_WAIT_L(0); PG8_MMA(0, 0, At, B0); PG8_BAR; PG8_SCHED;
.LBB0_543:
	s_add_i32 s43, 0, 0x10000
	v_add_u32_e32 v246, s43, v167
	ds_read_b128 v[132:135], v246
	ds_read_b128 v[136:139], v246 offset:1024
	ds_read_b128 v[140:143], v246 offset:2048
	ds_read_b128 v[144:147], v246 offset:3072
	s_add_i32 m0, s28, 0xc000
	ds_read_b128 v[148:151], v188
	ds_read_b128 v[152:155], v188 offset:1024
	ds_read_b128 v[156:159], v188 offset:2048
	ds_read_b128 v[160:163], v188 offset:3072
	ds_read_b128 v[182:185], v188 offset:4096
	ds_read_b128 v[190:193], v188 offset:5120
	ds_read_b128 v[194:197], v188 offset:6144
	ds_read_b128 v[212:215], v188 offset:7168
	global_load_lds_dwordx4 v180, s[2:3]
	s_add_i32 m0, s28, 0xe000
	s_nop 0
	global_load_lds_dwordx4 v178, s[2:3]
	s_waitcnt lgkmcnt(6)
	s_setprio 1
	s_barrier
	v_mfma_f32_16x16x32_bf16 v[128:131], v[132:135], v[148:151], v[128:131]
	v_mfma_f32_16x16x32_bf16 v[128:131], v[136:139], v[152:155], v[128:131]
	s_waitcnt lgkmcnt(0)
	v_mfma_f32_16x16x32_bf16 v[120:123], v[132:135], v[156:159], v[120:123]
	v_mfma_f32_16x16x32_bf16 v[120:123], v[136:139], v[160:163], v[120:123]
	v_mfma_f32_16x16x32_bf16 v[112:115], v[132:135], v[182:185], v[112:115]
	v_mfma_f32_16x16x32_bf16 v[112:115], v[136:139], v[190:193], v[112:115]
	v_mfma_f32_16x16x32_bf16 v[104:107], v[132:135], v[194:197], v[104:107]
	v_mfma_f32_16x16x32_bf16 v[104:107], v[136:139], v[212:215], v[104:107]
	v_mfma_f32_16x16x32_bf16 v[124:127], v[140:143], v[148:151], v[124:127]
	v_mfma_f32_16x16x32_bf16 v[124:127], v[144:147], v[152:155], v[124:127]
	v_mfma_f32_16x16x32_bf16 v[116:119], v[140:143], v[156:159], v[116:119]
	v_mfma_f32_16x16x32_bf16 v[116:119], v[144:147], v[160:163], v[116:119]
	v_mfma_f32_16x16x32_bf16 v[108:111], v[140:143], v[182:185], v[108:111]
	v_mfma_f32_16x16x32_bf16 v[108:111], v[144:147], v[190:193], v[108:111]
	v_mfma_f32_16x16x32_bf16 v[100:103], v[140:143], v[194:197], v[100:103]
	v_mfma_f32_16x16x32_bf16 v[100:103], v[144:147], v[212:215], v[100:103]
	s_barrier
	s_setprio 0
	s_add_u32 s4, s2, 0xfff80080
	s_addc_u32 s5, s3, -1
	s_cmp_eq_u32 s42, 28
	s_cselect_b32 s7, s1, s5
	s_cselect_b32 s6, s9, s4
	s_cselect_b32 s5, s13, s41
	s_cselect_b32 s4, s15, s33
	s_add_i32 s46, 0, 0x14000
	s_add_i32 s43, s43, s27
	ds_read_b128 v[216:219], v246 offset:16384
	ds_read_b128 v[220:223], v246 offset:17408
	ds_read_b128 v[224:227], v246 offset:18432
	ds_read_b128 v[228:231], v246 offset:19456
	s_add_u32 s98, s4, 0x80
	s_addc_u32 s99, s5, 0
	s_mov_b32 m0, s43
	s_nop 0
	global_load_lds_dwordx4 v172, s[4:5]
	s_add_i32 m0, s43, 0x2000
	s_nop 0
	global_load_lds_dwordx4 v168, s[4:5]
	s_mov_b32 m0, s28
	s_add_u32 s100, s6, 0x80
	s_addc_u32 s101, s7, 0
	s_waitcnt vmcnt(10)
	s_waitcnt lgkmcnt(2)
	s_setprio 1
	s_barrier
	v_mfma_f32_16x16x32_bf16 v[96:99], v[216:219], v[148:151], v[96:99]
	v_mfma_f32_16x16x32_bf16 v[96:99], v[220:223], v[152:155], v[96:99]
	s_waitcnt lgkmcnt(0)
	v_mfma_f32_16x16x32_bf16 v[88:91], v[216:219], v[156:159], v[88:91]
	v_mfma_f32_16x16x32_bf16 v[88:91], v[220:223], v[160:163], v[88:91]
	v_mfma_f32_16x16x32_bf16 v[80:83], v[216:219], v[182:185], v[80:83]
	v_mfma_f32_16x16x32_bf16 v[80:83], v[220:223], v[190:193], v[80:83]
	v_mfma_f32_16x16x32_bf16 v[72:75], v[216:219], v[194:197], v[72:75]
	v_mfma_f32_16x16x32_bf16 v[72:75], v[220:223], v[212:215], v[72:75]
	v_mfma_f32_16x16x32_bf16 v[92:95], v[224:227], v[148:151], v[92:95]
	v_mfma_f32_16x16x32_bf16 v[92:95], v[228:231], v[152:155], v[92:95]
	v_mfma_f32_16x16x32_bf16 v[84:87], v[224:227], v[156:159], v[84:87]
	v_mfma_f32_16x16x32_bf16 v[84:87], v[228:231], v[160:163], v[84:87]
	v_mfma_f32_16x16x32_bf16 v[76:79], v[224:227], v[182:185], v[76:79]
	v_mfma_f32_16x16x32_bf16 v[76:79], v[228:231], v[190:193], v[76:79]
	v_mfma_f32_16x16x32_bf16 v[68:71], v[224:227], v[194:197], v[68:71]
	v_mfma_f32_16x16x32_bf16 v[68:71], v[228:231], v[212:215], v[68:71]
	s_barrier
	s_setprio 0
	ds_read_b128 v[148:151], v188 offset:16384
	ds_read_b128 v[152:155], v188 offset:17408
	ds_read_b128 v[156:159], v188 offset:18432
	ds_read_b128 v[160:163], v188 offset:19456
	ds_read_b128 v[182:185], v188 offset:20480
	ds_read_b128 v[190:193], v188 offset:21504
	ds_read_b128 v[194:197], v188 offset:22528
	ds_read_b128 v[212:215], v188 offset:23552
	global_load_lds_dwordx4 v174, s[6:7]
	s_mov_b32 m0, s29
	s_nop 0
	global_load_lds_dwordx4 v170, s[6:7]
	s_waitcnt lgkmcnt(6)
	s_setprio 1
	s_barrier
	v_mfma_f32_16x16x32_bf16 v[64:67], v[132:135], v[148:151], v[64:67]
	v_mfma_f32_16x16x32_bf16 v[64:67], v[136:139], v[152:155], v[64:67]
	s_waitcnt lgkmcnt(0)
	v_mfma_f32_16x16x32_bf16 v[56:59], v[132:135], v[156:159], v[56:59]
	v_mfma_f32_16x16x32_bf16 v[56:59], v[136:139], v[160:163], v[56:59]
	v_mfma_f32_16x16x32_bf16 v[48:51], v[132:135], v[182:185], v[48:51]
	v_mfma_f32_16x16x32_bf16 v[48:51], v[136:139], v[190:193], v[48:51]
	v_mfma_f32_16x16x32_bf16 v[40:43], v[132:135], v[194:197], v[40:43]
	v_mfma_f32_16x16x32_bf16 v[40:43], v[136:139], v[212:215], v[40:43]
	v_mfma_f32_16x16x32_bf16 v[60:63], v[140:143], v[148:151], v[60:63]
	v_mfma_f32_16x16x32_bf16 v[60:63], v[144:147], v[152:155], v[60:63]
	v_mfma_f32_16x16x32_bf16 v[52:55], v[140:143], v[156:159], v[52:55]
	v_mfma_f32_16x16x32_bf16 v[52:55], v[144:147], v[160:163], v[52:55]
	v_mfma_f32_16x16x32_bf16 v[44:47], v[140:143], v[182:185], v[44:47]
	v_mfma_f32_16x16x32_bf16 v[44:47], v[144:147], v[190:193], v[44:47]
	v_mfma_f32_16x16x32_bf16 v[36:39], v[140:143], v[194:197], v[36:39]
	v_mfma_f32_16x16x32_bf16 v[36:39], v[144:147], v[212:215], v[36:39]
	s_barrier
	s_setprio 0
	s_add_u32 s44, s4, 0x80000
	s_addc_u32 s45, s5, 0
	s_add_i32 s43, s46, s27
	s_mov_b32 m0, s43
	s_nop 0
	global_load_lds_dwordx4 v172, s[44:45]
	s_add_i32 m0, s43, 0x2000
	s_nop 0
	global_load_lds_dwordx4 v168, s[44:45]
	s_add_i32 s43, 0, 0x18000
	s_waitcnt vmcnt(8)
	s_setprio 1
	s_barrier
; #define PG8_WAIT_V(n) asm volatile("s_waitcnt vmcnt(" #n ")" ::: "memory")
; #define PG8_WAIT_L(n) asm volatile("s_waitcnt lgkmcnt(" #n ")" ::: "memory")
; #define PG8_BAR __builtin_amdgcn_s_barrier()
; #define PG8_SCHED __builtin_amdgcn_sched_barrier(0)
; template <class Epi, class AddrA, class AddrB>
; __device__ __forceinline__ void gemm_phase(const Sched S, const int lda, const int ldb, const int K, const AddrA addrA,
;                                            const AddrB addrB, const Epi E) {
;     ...
;       PG8_WAIT_V(6); PG8_BAR; PG8_MMA(1, 1, At, B1); PG8_BAR;
;       PG8_LDB(B0, 1, 0); PG8_SCHED; PG8_LDA(At, 1, 0); PG8_STAGE(PG8_SA(0, 1), a2 + hstepA, voffA);
;       PG8_WAIT_L(8); PG8_BAR; PG8_WAIT_L(0); PG8_MMA(0, 0, At, B0); PG8_BAR; PG8_SCHED;
;       PG8_LDB(B1, 1, 1); PG8_STAGE(PG8_SB(1, 0), b3, voffB);
;       PG8_BAR; PG8_WAIT_L(0); PG8_MMA(0, 1, At, B1); PG8_BAR;
;       PG8_LDA(At, 1, 1); PG8_STAGE(PG8_SA(1, 0), a3, voffA);
;       PG8_BAR; PG8_WAIT_L(0); PG8_MMA(1, 0, At, B0); PG8_BAR; PG8_SCHED;
	v_mfma_f32_16x16x32_bf16 v[32:35], v[216:219], v[148:151], v[32:35]
	v_mfma_f32_16x16x32_bf16 v[32:35], v[220:223], v[152:155], v[32:35]
	v_mfma_f32_16x16x32_bf16 v[24:27], v[216:219], v[156:159], v[24:27]
	v_mfma_f32_16x16x32_bf16 v[24:27], v[220:223], v[160:163], v[24:27]
	v_mfma_f32_16x16x32_bf16 v[16:19], v[216:219], v[182:185], v[16:19]
	v_mfma_f32_16x16x32_bf16 v[16:19], v[220:223], v[190:193], v[16:19]
	v_mfma_f32_16x16x32_bf16 v[8:11], v[216:219], v[194:197], v[8:11]
	v_mfma_f32_16x16x32_bf16 v[8:11], v[220:223], v[212:215], v[8:11]
	v_mfma_f32_16x16x32_bf16 v[28:31], v[224:227], v[148:151], v[28:31]
	v_mfma_f32_16x16x32_bf16 v[28:31], v[228:231], v[152:155], v[28:31]
	v_mfma_f32_16x16x32_bf16 v[20:23], v[224:227], v[156:159], v[20:23]
	v_mfma_f32_16x16x32_bf16 v[20:23], v[228:231], v[160:163], v[20:23]
	v_mfma_f32_16x16x32_bf16 v[12:15], v[224:227], v[182:185], v[12:15]
	v_mfma_f32_16x16x32_bf16 v[12:15], v[228:231], v[190:193], v[12:15]
	v_mfma_f32_16x16x32_bf16 v[4:7], v[224:227], v[194:197], v[4:7]
	v_mfma_f32_16x16x32_bf16 v[4:7], v[228:231], v[212:215], v[4:7]
	s_barrier
	s_setprio 0
	ds_read_b128 v[132:135], v246 offset:32768
	ds_read_b128 v[136:139], v246 offset:33792
	ds_read_b128 v[140:143], v246 offset:34816
	ds_read_b128 v[144:147], v246 offset:35840
	s_add_u32 s6, s6, 0x80000
	s_addc_u32 s7, s7, 0
	s_mov_b32 m0, s30
	ds_read_b128 v[148:151], v188 offset:32768
	ds_read_b128 v[152:155], v188 offset:33792
	ds_read_b128 v[156:159], v188 offset:34816
	ds_read_b128 v[160:163], v188 offset:35840
	ds_read_b128 v[182:185], v188 offset:36864
	ds_read_b128 v[190:193], v188 offset:37888
	ds_read_b128 v[194:197], v188 offset:38912
	ds_read_b128 v[212:215], v188 offset:39936
	global_load_lds_dwordx4 v174, s[6:7]
	s_mov_b32 m0, s31
	s_nop 0
	global_load_lds_dwordx4 v170, s[6:7]
	s_waitcnt lgkmcnt(6)
	s_setprio 1
	s_barrier
	v_mfma_f32_16x16x32_bf16 v[128:131], v[132:135], v[148:151], v[128:131]
	v_mfma_f32_16x16x32_bf16 v[128:131], v[136:139], v[152:155], v[128:131]
	s_waitcnt lgkmcnt(0)
	v_mfma_f32_16x16x32_bf16 v[120:123], v[132:135], v[156:159], v[120:123]
	v_mfma_f32_16x16x32_bf16 v[120:123], v[136:139], v[160:163], v[120:123]
	v_mfma_f32_16x16x32_bf16 v[112:115], v[132:135], v[182:185], v[112:115]
	v_mfma_f32_16x16x32_bf16 v[112:115], v[136:139], v[190:193], v[112:115]
	v_mfma_f32_16x16x32_bf16 v[104:107], v[132:135], v[194:197], v[104:107]
	v_mfma_f32_16x16x32_bf16 v[104:107], v[136:139], v[212:215], v[104:107]
	v_mfma_f32_16x16x32_bf16 v[124:127], v[140:143], v[148:151], v[124:127]
	v_mfma_f32_16x16x32_bf16 v[124:127], v[144:147], v[152:155], v[124:127]
	v_mfma_f32_16x16x32_bf16 v[116:119], v[140:143], v[156:159], v[116:119]
	v_mfma_f32_16x16x32_bf16 v[116:119], v[144:147], v[160:163], v[116:119]
	v_mfma_f32_16x16x32_bf16 v[108:111], v[140:143], v[182:185], v[108:111]
	v_mfma_f32_16x16x32_bf16 v[108:111], v[144:147], v[190:193], v[108:111]
	v_mfma_f32_16x16x32_bf16 v[100:103], v[140:143], v[194:197], v[100:103]
	v_mfma_f32_16x16x32_bf16 v[100:103], v[144:147], v[212:215], v[100:103]
	s_barrier
	s_setprio 0
	s_add_i32 s6, 0, 0x1c000
	s_add_i32 s7, s43, s27
	s_mov_b32 m0, s7
	ds_read_b128 v[216:219], v246 offset:49152
	ds_read_b128 v[220:223], v246 offset:50176
	ds_read_b128 v[224:227], v246 offset:51200
	ds_read_b128 v[228:231], v246 offset:52224
	global_load_lds_dwordx4 v172, s[98:99]
	s_add_i32 m0, s7, 0x2000
	s_nop 0
	global_load_lds_dwordx4 v168, s[98:99]
	s_mov_b32 m0, s38
	s_waitcnt vmcnt(10)
	s_waitcnt lgkmcnt(2)
	s_setprio 1
	s_barrier
	v_mfma_f32_16x16x32_bf16 v[96:99], v[216:219], v[148:151], v[96:99]
	v_mfma_f32_16x16x32_bf16 v[96:99], v[220:223], v[152:155], v[96:99]
	s_waitcnt lgkmcnt(0)
	v_mfma_f32_16x16x32_bf16 v[88:91], v[216:219], v[156:159], v[88:91]
	v_mfma_f32_16x16x32_bf16 v[88:91], v[220:223], v[160:163], v[88:91]
	v_mfma_f32_16x16x32_bf16 v[80:83], v[216:219], v[182:185], v[80:83]
	v_mfma_f32_16x16x32_bf16 v[80:83], v[220:223], v[190:193], v[80:83]
	v_mfma_f32_16x16x32_bf16 v[72:75], v[216:219], v[194:197], v[72:75]
	v_mfma_f32_16x16x32_bf16 v[72:75], v[220:223], v[212:215], v[72:75]
	v_mfma_f32_16x16x32_bf16 v[92:95], v[224:227], v[148:151], v[92:95]
	v_mfma_f32_16x16x32_bf16 v[92:95], v[228:231], v[152:155], v[92:95]
	v_mfma_f32_16x16x32_bf16 v[84:87], v[224:227], v[156:159], v[84:87]
	v_mfma_f32_16x16x32_bf16 v[84:87], v[228:231], v[160:163], v[84:87]
	v_mfma_f32_16x16x32_bf16 v[76:79], v[224:227], v[182:185], v[76:79]
	v_mfma_f32_16x16x32_bf16 v[76:79], v[228:231], v[190:193], v[76:79]
	v_mfma_f32_16x16x32_bf16 v[68:71], v[224:227], v[194:197], v[68:71]
	v_mfma_f32_16x16x32_bf16 v[68:71], v[228:231], v[212:215], v[68:71]
	s_barrier
	s_setprio 0
	ds_read_b128 v[148:151], v188 offset:49152
	ds_read_b128 v[152:155], v188 offset:50176
	ds_read_b128 v[156:159], v188 offset:51200
	ds_read_b128 v[160:163], v188 offset:52224
	ds_read_b128 v[182:185], v188 offset:53248
	ds_read_b128 v[190:193], v188 offset:54272
	ds_read_b128 v[194:197], v188 offset:55296
	ds_read_b128 v[212:215], v188 offset:56320
	global_load_lds_dwordx4 v174, s[100:101]
	s_mov_b32 m0, s39
	s_nop 0
	global_load_lds_dwordx4 v170, s[100:101]
	s_waitcnt lgkmcnt(6)
	s_setprio 1
	s_barrier
; #define PG8_WAIT_V(n) asm volatile("s_waitcnt vmcnt(" #n ")" ::: "memory")
; template <class Epi, class AddrA, class AddrB>
; __device__ __forceinline__ void gemm_phase(const Sched S, const int lda, const int ldb, const int K, const AddrA addrA,
;                                            const AddrB addrB, const Epi E) {
;     ...
;       PG8_BAR; PG8_WAIT_L(0); PG8_MMA(1, 0, At, B0); PG8_BAR; PG8_SCHED;
;       PG8_STAGE(PG8_SB(1, 1), b3 + hstepB, voffB);
;       PG8_WAIT_V(6); PG8_BAR; PG8_MMA(1, 1, At, B1); PG8_BAR;
;   __device__ __forceinline__ void operator()(EPI_ARGS) const {
;     const int col0 = u.pn * 256 + wc * 32 + 8 * fq;
;     const int br = u.br, brn = br < 2 ? br + 1 : 2;
;     const unsigned loff0 = (unsigned)((wr * 64 + fr) * PLD + wc * 32 + 8 * fq);
;     const bf16_t* pc = proj + ((size_t)((GT + br * DM) / 256 + u.pn) * MTOK + (size_t)u.pm * 256) * PLD;
;     const bf16_t* pn_ = proj + ((size_t)((GT + brn * DM) / 256 + u.pn) * MTOK + (size_t)u.pm * 256) * PLD;
;     bf16_t* mrow = merged + ((size_t)u.pm * 256 + wr * 64 + fr) * DM + col0;
; #pragma unroll
;     for (int bj = 0; bj < 2; ++bj) {
;       const int c = col0 + bj * HALF;
;       float gc[8], gn[8];
;       {
;         const f32x4 a0 = *(const f32x4*)(bg + br * DM + c), a1 = *(const f32x4*)(bg + br * DM + c + 4);
;         const f32x4 b0 = *(const f32x4*)(bg + brn * DM + c), b1 = *(const f32x4*)(bg + brn * DM + c + 4);
; #pragma unroll
;         for (int k = 0; k < 4; ++k) { gc[k] = a0[k]; gc[4 + k] = a1[k]; gn[k] = b0[k]; gn[4 + k] = b1[k]; }
;       }
; #pragma unroll
;       for (int ai = 0; ai < 2; ++ai) {
;         unsigned loff = loff0;
;         asm volatile("" : "+v"(loff));
;         u32x4 zc[4], zn[4];
; #pragma unroll
;         for (int m = 0; m < 4; ++m) {
;           const unsigned o = loff + (unsigned)((ai * HALF + m * 16) * PLD + bj * HALF);
;           zc[m] = *(const u32x4*)(pc + o);
;           zn[m] = *(const u32x4*)(pn_ + o);
;         }
;         __builtin_amdgcn_sched_barrier(0);
;         if (br < 2) {
; #pragma unroll
;           for (int m = 0; m < 4; ++m) {
;             float xc[8], xn[8];
;             unpack8(zc[m], xc);
;             unpack8(zn[m], xn);
; #pragma unroll
;             for (int k = 0; k < 8; ++k) {
;               const float ec = __expf(-fmaxf(xc[k] + gc[k], -40.f)), en = __expf(-fmaxf(xn[k] + gn[k], -40.f));
	v_mfma_f32_16x16x32_bf16 v[64:67], v[132:135], v[148:151], v[64:67]
	v_mfma_f32_16x16x32_bf16 v[64:67], v[136:139], v[152:155], v[64:67]
	s_waitcnt lgkmcnt(0)
	v_mfma_f32_16x16x32_bf16 v[56:59], v[132:135], v[156:159], v[56:59]
	v_mfma_f32_16x16x32_bf16 v[56:59], v[136:139], v[160:163], v[56:59]
	v_mfma_f32_16x16x32_bf16 v[48:51], v[132:135], v[182:185], v[48:51]
	v_mfma_f32_16x16x32_bf16 v[48:51], v[136:139], v[190:193], v[48:51]
	v_mfma_f32_16x16x32_bf16 v[40:43], v[132:135], v[194:197], v[40:43]
	v_mfma_f32_16x16x32_bf16 v[40:43], v[136:139], v[212:215], v[40:43]
	v_mfma_f32_16x16x32_bf16 v[60:63], v[140:143], v[148:151], v[60:63]
	v_mfma_f32_16x16x32_bf16 v[60:63], v[144:147], v[152:155], v[60:63]
	v_mfma_f32_16x16x32_bf16 v[52:55], v[140:143], v[156:159], v[52:55]
	v_mfma_f32_16x16x32_bf16 v[52:55], v[144:147], v[160:163], v[52:55]
	v_mfma_f32_16x16x32_bf16 v[44:47], v[140:143], v[182:185], v[44:47]
	v_mfma_f32_16x16x32_bf16 v[44:47], v[144:147], v[190:193], v[44:47]
	v_mfma_f32_16x16x32_bf16 v[36:39], v[140:143], v[194:197], v[36:39]
	v_mfma_f32_16x16x32_bf16 v[36:39], v[144:147], v[212:215], v[36:39]
	s_barrier
	s_setprio 0
	s_add_u32 s4, s4, 0x80080
	s_addc_u32 s5, s5, 0
	s_add_i32 s6, s6, s27
	s_mov_b32 m0, s6
	s_nop 0
	global_load_lds_dwordx4 v172, s[4:5]
	s_add_i32 m0, s6, 0x2000
	s_nop 0
	global_load_lds_dwordx4 v168, s[4:5]
	s_add_i32 s42, s42, 2
	s_add_u32 s33, s33, 0x100
	s_addc_u32 s41, s41, 0
	s_add_u32 s2, s2, 0x100
	s_addc_u32 s3, s3, 0
	s_waitcnt vmcnt(8)
	s_setprio 1
	s_barrier
	v_mfma_f32_16x16x32_bf16 v[32:35], v[216:219], v[148:151], v[32:35]
	v_mfma_f32_16x16x32_bf16 v[32:35], v[220:223], v[152:155], v[32:35]
	v_mfma_f32_16x16x32_bf16 v[24:27], v[216:219], v[156:159], v[24:27]
	v_mfma_f32_16x16x32_bf16 v[24:27], v[220:223], v[160:163], v[24:27]
	v_mfma_f32_16x16x32_bf16 v[16:19], v[216:219], v[182:185], v[16:19]
	v_mfma_f32_16x16x32_bf16 v[16:19], v[220:223], v[190:193], v[16:19]
	v_mfma_f32_16x16x32_bf16 v[8:11], v[216:219], v[194:197], v[8:11]
	v_mfma_f32_16x16x32_bf16 v[8:11], v[220:223], v[212:215], v[8:11]
	v_mfma_f32_16x16x32_bf16 v[28:31], v[224:227], v[148:151], v[28:31]
	v_mfma_f32_16x16x32_bf16 v[28:31], v[228:231], v[152:155], v[28:31]
	v_mfma_f32_16x16x32_bf16 v[20:23], v[224:227], v[156:159], v[20:23]
	v_mfma_f32_16x16x32_bf16 v[20:23], v[228:231], v[160:163], v[20:23]
	v_mfma_f32_16x16x32_bf16 v[12:15], v[224:227], v[182:185], v[12:15]
	v_mfma_f32_16x16x32_bf16 v[12:15], v[228:231], v[190:193], v[12:15]
	v_mfma_f32_16x16x32_bf16 v[4:7], v[224:227], v[194:197], v[4:7]
	v_mfma_f32_16x16x32_bf16 v[4:7], v[228:231], v[212:215], v[4:7]
	s_barrier
	s_setprio 0
	s_cmp_gt_u32 s42, 29
	s_cbranch_scc0 .LBB0_543
	s_cmp_gt_i32 s10, 1
	s_cselect_b64 s[6:7], -1, 0
	s_lshl_b32 s42, s10, 11
	s_add_i32 s2, s42, 0x4c00
	s_ashr_i32 s2, s2, 8
	s_add_i32 s2, s2, s11
	s_ashr_i32 s3, s2, 31
	s_min_i32 s1, s10, 1
	s_ashr_i32 s9, s8, 31
	s_lshl_b64 s[2:3], s[2:3], 23
	s_add_u32 s2, s34, s2
	s_addc_u32 s3, s35, s3
	s_lshl_b64 s[4:5], s[8:9], 17
	s_add_u32 s2, s2, s4
	s_addc_u32 s3, s3, s5
	s_lshl_b32 s1, s1, 11
	s_add_i32 s44, s1, 0x800
	s_addk_i32 s1, 0x5400
	s_ashr_i32 s1, s1, 8
	s_add_i32 s46, s1, s11
	s_ashr_i32 s47, s46, 31
	s_lshl_b64 s[46:47], s[46:47], 23
	s_add_u32 s1, s34, s46
	v_lshl_or_b32 v132, s11, 8, v187
	s_addc_u32 s11, s35, s47
	s_add_u32 s4, s1, s4
	s_addc_u32 s5, s11, s5
	s_ashr_i32 s43, s42, 31
	s_lshl_b64 s[8:9], s[8:9], 20
	s_ashr_i32 s45, s44, 31
	s_lshl_b64 s[42:43], s[42:43], 2
	s_add_u32 s42, s36, s42
	s_addc_u32 s43, s37, s43
	s_lshl_b64 s[44:45], s[44:45], 2
	s_add_u32 s44, s36, s44
	v_lshl_add_u64 v[0:1], v[176:177], 0, s[8:9]
	v_ashrrev_i32_e32 v133, 31, v132
	s_addc_u32 s45, s37, s45
	v_lshl_add_u64 v[0:1], v[132:133], 1, v[0:1]
	v_lshlrev_b64 v[132:133], 2, v[132:133]
	v_lshl_add_u64 v[182:183], s[42:43], 0, v[132:133]
	v_lshl_add_u64 v[184:185], s[44:45], 0, v[132:133]
	v_mov_b32_e32 v2, v186
	global_load_dwordx4 v[144:147], v[182:183], off
	global_load_dwordx4 v[136:139], v[182:183], off offset:16
	global_load_dwordx4 v[140:143], v[184:185], off
	global_load_dwordx4 v[132:135], v[184:185], off offset:16
	s_cmp_lt_i32 s10, 2
	v_lshlrev_b64 v[148:149], 1, v[2:3]
	v_lshl_add_u64 v[150:151], s[2:3], 0, v[148:149]
	v_lshl_add_u64 v[148:149], s[4:5], 0, v[148:149]
	flat_load_dwordx4 v[190:193], v[150:151]
	flat_load_dwordx4 v[160:163], v[148:149]
	v_add_u32_e32 v148, 0x1000, v2
	v_mov_b32_e32 v149, v3
	v_lshlrev_b64 v[148:149], 1, v[148:149]
	v_lshl_add_u64 v[150:151], s[2:3], 0, v[148:149]
	v_lshl_add_u64 v[148:149], s[4:5], 0, v[148:149]
	flat_load_dwordx4 v[194:197], v[150:151]
	flat_load_dwordx4 v[156:159], v[148:149]
	v_add_u32_e32 v148, 0x2000, v2
	v_mov_b32_e32 v149, v3
	v_lshlrev_b64 v[148:149], 1, v[148:149]
	v_lshl_add_u64 v[150:151], s[2:3], 0, v[148:149]
	v_lshl_add_u64 v[148:149], s[4:5], 0, v[148:149]
	v_add_u32_e32 v2, 0x3000, v2
	flat_load_dwordx4 v[234:237], v[150:151]
	flat_load_dwordx4 v[152:155], v[148:149]
	v_lshlrev_b64 v[148:149], 1, v[2:3]
	v_lshl_add_u64 v[150:151], s[2:3], 0, v[148:149]
	v_lshl_add_u64 v[148:149], s[4:5], 0, v[148:149]
	flat_load_dwordx4 v[238:241], v[150:151]
	s_nop 0
	flat_load_dwordx4 v[148:151], v[148:149]
	s_waitcnt vmcnt(0) lgkmcnt(0)
	v_lshlrev_b32_e32 v2, 16, v190
	v_and_b32_e32 v189, 0xffff0000, v190
	v_lshlrev_b32_e32 v190, 16, v191
	v_and_b32_e32 v191, 0xffff0000, v191
	v_lshlrev_b32_e32 v212, 16, v192
	v_and_b32_e32 v192, 0xffff0000, v192
	v_lshlrev_b32_e32 v213, 16, v193
	v_and_b32_e32 v193, 0xffff0000, v193
	v_add_f32_e32 v2, v144, v2
	v_add_f32_e32 v189, v145, v189
	v_add_f32_e32 v190, v146, v190
	v_add_f32_e32 v191, v147, v191
	v_add_f32_e32 v212, v136, v212
	v_add_f32_e32 v192, v137, v192
	v_add_f32_e32 v213, v138, v213
	v_add_f32_e32 v193, v139, v193
	s_mov_b64 s[8:9], -1
	v_max_f32_e32 v233, 0xc2200000, v2
	v_max_f32_e32 v232, 0xc2200000, v189
	v_max_f32_e32 v231, 0xc2200000, v190
	v_max_f32_e32 v230, 0xc2200000, v191
	v_max_f32_e32 v229, 0xc2200000, v212
	v_max_f32_e32 v228, 0xc2200000, v192
	v_max_f32_e32 v227, 0xc2200000, v213
	v_max_f32_e32 v226, 0xc2200000, v193
	v_lshlrev_b32_e32 v225, 16, v194
	v_and_b32_e32 v224, 0xffff0000, v194
	v_lshlrev_b32_e32 v223, 16, v195
	v_and_b32_e32 v222, 0xffff0000, v195
	v_lshlrev_b32_e32 v221, 16, v196
	v_and_b32_e32 v220, 0xffff0000, v196
	v_lshlrev_b32_e32 v219, 16, v197
	v_and_b32_e32 v218, 0xffff0000, v197
	v_lshlrev_b32_e32 v217, 16, v234
	v_and_b32_e32 v216, 0xffff0000, v234
	v_lshlrev_b32_e32 v215, 16, v235
	v_and_b32_e32 v214, 0xffff0000, v235
	v_lshlrev_b32_e32 v213, 16, v236
	v_and_b32_e32 v212, 0xffff0000, v236
	v_lshlrev_b32_e32 v197, 16, v237
	v_and_b32_e32 v196, 0xffff0000, v237
	v_lshlrev_b32_e32 v195, 16, v238
	v_and_b32_e32 v194, 0xffff0000, v238
	v_lshlrev_b32_e32 v193, 16, v239
	v_and_b32_e32 v192, 0xffff0000, v239
	v_lshlrev_b32_e32 v191, 16, v240
	v_and_b32_e32 v190, 0xffff0000, v240
	v_lshlrev_b32_e32 v189, 16, v241
	v_and_b32_e32 v2, 0xffff0000, v241
	s_cbranch_scc1 .LBB0_546
; __device__ __forceinline__ float sigmoidf_(float x) { return __builtin_amdgcn_rcpf(1.0f + __expf(-x)); }
;   __device__ __forceinline__ void operator()(EPI_ARGS) const {
;     ...
; #pragma unroll
;           for (int m = 0; m < 4; ++m) {
;             float xc[8], y[8];
;             unpack8(zc[m], xc);
; #pragma unroll
;             for (int k = 0; k < 8; ++k) y[k] = acc[ai][bj][m][k >> 2][k & 3] * sigmoidf_(fmaxf(xc[k] + gc[k], -40.f));
;             u32x4 o;
;             o.x = pack2(y[0], y[1]); o.y = pack2(y[2], y[3]); o.z = pack2(y[4], y[5]); o.w = pack2(y[6], y[7]);
;             *(u32x4*)(mrow + (size_t)(ai * HALF + m * 16) * DM + bj * HALF) = o;
;           }
	v_mul_f32_e32 v234, 0xbfb8aa3b, v233
	v_mul_f32_e32 v235, 0xbfb8aa3b, v232
	v_mul_f32_e32 v236, 0xbfb8aa3b, v231
	v_exp_f32_e32 v234, v234
	v_exp_f32_e32 v235, v235
	v_exp_f32_e32 v236, v236
	v_mul_f32_e32 v237, 0xbfb8aa3b, v230
	v_exp_f32_e32 v237, v237
	v_mul_f32_e32 v238, 0xbfb8aa3b, v229
	v_mul_f32_e32 v239, 0xbfb8aa3b, v228
	v_add_f32_e32 v234, 1.0, v234
	v_add_f32_e32 v235, 1.0, v235
	v_add_f32_e32 v236, 1.0, v236
	v_exp_f32_e32 v238, v238
	v_exp_f32_e32 v239, v239
	v_mul_f32_e32 v240, 0xbfb8aa3b, v227
	v_mul_f32_e32 v241, 0xbfb8aa3b, v226
	v_rcp_f32_e32 v234, v234
	v_rcp_f32_e32 v235, v235
	v_rcp_f32_e32 v236, v236
	v_add_f32_e32 v237, 1.0, v237
	v_exp_f32_e32 v240, v240
	v_exp_f32_e32 v241, v241
	v_rcp_f32_e32 v237, v237
	v_add_f32_e32 v238, 1.0, v238
	v_add_f32_e32 v239, 1.0, v239
	v_mul_f32_e32 v234, v128, v234
	v_mul_f32_e32 v235, v129, v235
	v_mul_f32_e32 v236, v130, v236
	v_rcp_f32_e32 v238, v238
	v_rcp_f32_e32 v239, v239
	v_add_f32_e32 v240, 1.0, v240
	v_add_f32_e32 v241, 1.0, v241
	v_mul_f32_e32 v237, v131, v237
	v_rcp_f32_e32 v240, v240
	v_rcp_f32_e32 v241, v241
	v_cvt_pk_bf16_f32 v234, v234, v235
	v_cvt_pk_bf16_f32 v235, v236, v237
	v_add_f32_e32 v236, v144, v225
	v_max_f32_e32 v236, 0xc2200000, v236
	v_mul_f32_e32 v236, 0xbfb8aa3b, v236
	v_mul_f32_e32 v238, v124, v238
	v_mul_f32_e32 v239, v125, v239
	v_exp_f32_e32 v242, v236
	v_cvt_pk_bf16_f32 v236, v238, v239
	v_mul_f32_e32 v240, v126, v240
	v_mul_f32_e32 v241, v127, v241
	v_cvt_pk_bf16_f32 v237, v240, v241
	flat_store_dwordx4 v[0:1], v[234:237]
	v_add_f32_e32 v238, v136, v221
	v_max_f32_e32 v238, 0xc2200000, v238
	v_add_f32_e32 v235, v145, v224
	v_add_f32_e32 v236, v146, v223
	v_max_f32_e32 v235, 0xc2200000, v235
	v_max_f32_e32 v236, 0xc2200000, v236
	v_add_f32_e32 v237, v147, v222
	v_add_f32_e32 v239, v137, v220
	v_mul_f32_e32 v235, 0xbfb8aa3b, v235
	v_mul_f32_e32 v236, 0xbfb8aa3b, v236
	v_max_f32_e32 v237, 0xc2200000, v237
	v_mul_f32_e32 v238, 0xbfb8aa3b, v238
	v_max_f32_e32 v239, 0xc2200000, v239
	v_exp_f32_e32 v235, v235
	v_exp_f32_e32 v236, v236
	v_mul_f32_e32 v237, 0xbfb8aa3b, v237
	v_exp_f32_e32 v238, v238
	v_mul_f32_e32 v239, 0xbfb8aa3b, v239
	v_add_f32_e32 v240, v138, v219
	v_exp_f32_e32 v237, v237
	v_exp_f32_e32 v239, v239
	v_max_f32_e32 v240, 0xc2200000, v240
	v_add_f32_e32 v241, v139, v218
	v_mul_f32_e32 v240, 0xbfb8aa3b, v240
	v_max_f32_e32 v241, 0xc2200000, v241
	v_exp_f32_e32 v240, v240
	v_mul_f32_e32 v241, 0xbfb8aa3b, v241
	v_add_f32_e32 v234, 1.0, v242
	v_add_f32_e32 v235, 1.0, v235
	v_add_f32_e32 v236, 1.0, v236
	v_add_f32_e32 v238, 1.0, v238
	v_exp_f32_e32 v241, v241
	v_rcp_f32_e32 v234, v234
	v_rcp_f32_e32 v235, v235
	v_rcp_f32_e32 v236, v236
	v_add_f32_e32 v237, 1.0, v237
	v_rcp_f32_e32 v238, v238
	v_add_f32_e32 v239, 1.0, v239
	v_rcp_f32_e32 v237, v237
	v_rcp_f32_e32 v239, v239
	v_add_f32_e32 v240, 1.0, v240
	v_rcp_f32_e32 v240, v240
	v_add_f32_e32 v241, 1.0, v241
	v_mul_f32_e32 v234, v120, v234
	v_mul_f32_e32 v235, v121, v235
	v_mul_f32_e32 v236, v122, v236
	v_rcp_f32_e32 v241, v241
	v_mul_f32_e32 v238, v116, v238
	v_mul_f32_e32 v237, v123, v237
	v_mul_f32_e32 v239, v117, v239
	v_cvt_pk_bf16_f32 v234, v234, v235
	v_cvt_pk_bf16_f32 v235, v236, v237
	v_cvt_pk_bf16_f32 v236, v238, v239
	v_add_f32_e32 v238, v144, v217
	v_max_f32_e32 v238, 0xc2200000, v238
	v_mul_f32_e32 v240, v118, v240
	v_mul_f32_e32 v238, 0xbfb8aa3b, v238
	v_mul_f32_e32 v241, v119, v241
	v_cvt_pk_bf16_f32 v237, v240, v241
	v_exp_f32_e32 v240, v238
	v_add_co_u32_e32 v238, vcc, s67, v0
	v_add_f32_e32 v241, v139, v196
	s_nop 0
	v_addc_co_u32_e32 v239, vcc, 0, v1, vcc
	flat_store_dwordx4 v[238:239], v[234:237]
	v_add_f32_e32 v238, v136, v213
	v_max_f32_e32 v238, 0xc2200000, v238
	v_add_f32_e32 v235, v145, v216
	v_add_f32_e32 v236, v146, v215
	v_max_f32_e32 v235, 0xc2200000, v235
; __device__ __forceinline__ float sigmoidf_(float x) { return __builtin_amdgcn_rcpf(1.0f + __expf(-x)); }
;   __device__ __forceinline__ void operator()(EPI_ARGS) const {
;     ...
; #pragma unroll
;           for (int m = 0; m < 4; ++m) {
;             float xc[8], y[8];
;             unpack8(zc[m], xc);
; #pragma unroll
;             for (int k = 0; k < 8; ++k) y[k] = acc[ai][bj][m][k >> 2][k & 3] * sigmoidf_(fmaxf(xc[k] + gc[k], -40.f));
;             u32x4 o;
;             o.x = pack2(y[0], y[1]); o.y = pack2(y[2], y[3]); o.z = pack2(y[4], y[5]); o.w = pack2(y[6], y[7]);
;             *(u32x4*)(mrow + (size_t)(ai * HALF + m * 16) * DM + bj * HALF) = o;
;           }
	v_max_f32_e32 v236, 0xc2200000, v236
	v_add_f32_e32 v237, v147, v214
	v_add_f32_e32 v239, v137, v212
	v_mul_f32_e32 v235, 0xbfb8aa3b, v235
	v_mul_f32_e32 v236, 0xbfb8aa3b, v236
	v_max_f32_e32 v237, 0xc2200000, v237
	v_mul_f32_e32 v238, 0xbfb8aa3b, v238
	v_max_f32_e32 v239, 0xc2200000, v239
	v_add_f32_e32 v234, 1.0, v240
	v_exp_f32_e32 v235, v235
	v_exp_f32_e32 v236, v236
	v_mul_f32_e32 v237, 0xbfb8aa3b, v237
	v_exp_f32_e32 v238, v238
	v_mul_f32_e32 v239, 0xbfb8aa3b, v239
	v_add_f32_e32 v240, v138, v197
	v_exp_f32_e32 v237, v237
	v_exp_f32_e32 v239, v239
	v_max_f32_e32 v240, 0xc2200000, v240
	v_mul_f32_e32 v240, 0xbfb8aa3b, v240
	v_max_f32_e32 v241, 0xc2200000, v241
	v_exp_f32_e32 v240, v240
	v_mul_f32_e32 v241, 0xbfb8aa3b, v241
	v_add_f32_e32 v235, 1.0, v235
	v_add_f32_e32 v236, 1.0, v236
	v_add_f32_e32 v238, 1.0, v238
	v_exp_f32_e32 v241, v241
	v_rcp_f32_e32 v234, v234
	v_rcp_f32_e32 v235, v235
	v_rcp_f32_e32 v236, v236
	v_add_f32_e32 v237, 1.0, v237
	v_rcp_f32_e32 v238, v238
	v_add_f32_e32 v239, 1.0, v239
	v_rcp_f32_e32 v237, v237
	v_rcp_f32_e32 v239, v239
	v_add_f32_e32 v240, 1.0, v240
	v_rcp_f32_e32 v240, v240
	v_add_f32_e32 v241, 1.0, v241
	v_mul_f32_e32 v234, v112, v234
	v_mul_f32_e32 v235, v113, v235
	v_mul_f32_e32 v236, v114, v236
	v_rcp_f32_e32 v241, v241
	v_mul_f32_e32 v238, v108, v238
	v_mul_f32_e32 v237, v115, v237
	v_mul_f32_e32 v239, v109, v239
	v_cvt_pk_bf16_f32 v234, v234, v235
	v_cvt_pk_bf16_f32 v235, v236, v237
	v_cvt_pk_bf16_f32 v236, v238, v239
	v_add_f32_e32 v238, v144, v195
	v_max_f32_e32 v238, 0xc2200000, v238
	v_mul_f32_e32 v240, v110, v240
	v_mul_f32_e32 v238, 0xbfb8aa3b, v238
	s_mov_b32 s1, 0x20000
	v_mul_f32_e32 v241, v111, v241
	v_cvt_pk_bf16_f32 v237, v240, v241
	v_exp_f32_e32 v240, v238
	v_add_co_u32_e32 v238, vcc, s1, v0
	v_add_f32_e32 v241, v139, v2
	s_nop 0
	v_addc_co_u32_e32 v239, vcc, 0, v1, vcc
	flat_store_dwordx4 v[238:239], v[234:237]
	v_add_f32_e32 v238, v136, v191
	v_max_f32_e32 v238, 0xc2200000, v238
	v_add_f32_e32 v235, v145, v194
	v_add_f32_e32 v236, v146, v193
	v_max_f32_e32 v235, 0xc2200000, v235
	v_max_f32_e32 v236, 0xc2200000, v236
	v_add_f32_e32 v237, v147, v192
	v_add_f32_e32 v239, v137, v190
	v_mul_f32_e32 v235, 0xbfb8aa3b, v235
	v_mul_f32_e32 v236, 0xbfb8aa3b, v236
	v_max_f32_e32 v237, 0xc2200000, v237
	v_mul_f32_e32 v238, 0xbfb8aa3b, v238
	v_max_f32_e32 v239, 0xc2200000, v239
	v_add_f32_e32 v234, 1.0, v240
	v_exp_f32_e32 v235, v235
	v_exp_f32_e32 v236, v236
	v_mul_f32_e32 v237, 0xbfb8aa3b, v237
	v_exp_f32_e32 v238, v238
	v_mul_f32_e32 v239, 0xbfb8aa3b, v239
	v_add_f32_e32 v240, v138, v189
	v_exp_f32_e32 v237, v237
	v_exp_f32_e32 v239, v239
	v_max_f32_e32 v240, 0xc2200000, v240
	v_max_f32_e32 v241, 0xc2200000, v241
	v_mul_f32_e32 v240, 0xbfb8aa3b, v240
	v_mul_f32_e32 v241, 0xbfb8aa3b, v241
	v_exp_f32_e32 v240, v240
	v_exp_f32_e32 v241, v241
	v_add_f32_e32 v235, 1.0, v235
	v_add_f32_e32 v236, 1.0, v236
	v_add_f32_e32 v238, 1.0, v238
	v_rcp_f32_e32 v234, v234
	v_rcp_f32_e32 v235, v235
	v_rcp_f32_e32 v236, v236
	v_add_f32_e32 v237, 1.0, v237
	v_rcp_f32_e32 v238, v238
	v_add_f32_e32 v239, 1.0, v239
	v_rcp_f32_e32 v237, v237
	v_rcp_f32_e32 v239, v239
	v_add_f32_e32 v240, 1.0, v240
	v_add_f32_e32 v241, 1.0, v241
	v_rcp_f32_e32 v240, v240
	v_rcp_f32_e32 v241, v241
	v_mul_f32_e32 v234, v104, v234
	v_mul_f32_e32 v235, v105, v235
	v_mul_f32_e32 v236, v106, v236
	v_mul_f32_e32 v238, v100, v238
	v_mul_f32_e32 v237, v107, v237
	v_mul_f32_e32 v239, v101, v239
	v_cvt_pk_bf16_f32 v234, v234, v235
	v_cvt_pk_bf16_f32 v235, v236, v237
	v_cvt_pk_bf16_f32 v236, v238, v239
	v_add_co_u32_e32 v238, vcc, 0x30000, v0
	s_mov_b64 s[8:9], 0
	s_nop 0
	v_addc_co_u32_e32 v239, vcc, 0, v1, vcc
	v_mul_f32_e32 v240, v102, v240
	v_mul_f32_e32 v241, v103, v241
	v_cvt_pk_bf16_f32 v237, v240, v241
	flat_store_dwordx4 v[238:239], v[234:237]

; #define PG8_WAIT_L(n) asm volatile("s_waitcnt lgkmcnt(" #n ")" ::: "memory")
; #define PG8_BAR __builtin_amdgcn_s_barrier()
; #define PG8_SCHED __builtin_amdgcn_sched_barrier(0)
; template <class Epi, class AddrA, class AddrB>
; __device__ __forceinline__ void gemm_phase(const Sched S, const int lda, const int ldb, const int K, const AddrA addrA,
;                                            const AddrB addrB, const Epi E) {
;     ...
;       PG8_LDB(B0, 0, 0); PG8_SCHED; PG8_LDA(At, 0, 0); PG8_STAGE(PG8_SA(1, 1), a1 + hstepA, voffA);
;       PG8_WAIT_L(8); PG8_BAR; PG8_WAIT_L(0); PG8_MMA(0, 0, At, B0); PG8_BAR; PG8_SCHED;
;       PG8_LDB(B1, 0, 1); PG8_STAGE(PG8_SB(0, 0), b2, voffB);
;       PG8_BAR; PG8_WAIT_L(0); PG8_MMA(0, 1, At, B1); PG8_BAR;
;       PG8_LDA(At, 0, 1); PG8_STAGE(PG8_SA(0, 0), a2, voffA);
;       PG8_BAR; PG8_WAIT_L(0); PG8_MMA(1, 0, At, B0); PG8_BAR; PG8_SCHED;
.LBB0_618:
	s_ashr_i32 s3, s2, 31
	s_lshl_b64 s[8:9], s[2:3], 20
	s_add_u32 s8, s23, s8
	s_addc_u32 s9, s24, s9
	s_and_b64 s[10:11], s[18:19], exec
	s_cselect_b32 s3, s9, s17
	s_cselect_b32 s13, s8, s16
	s_ashr_i32 s5, s4, 31
	s_lshl_b64 s[10:11], s[4:5], 20
	s_add_u32 s10, s21, s10
	s_addc_u32 s11, s22, s11
	s_and_b64 s[18:19], s[18:19], exec
	s_cselect_b32 s5, s11, s15
	s_cselect_b32 s35, s10, s14
	s_add_u32 s36, s14, 0x100
	s_addc_u32 s37, s15, 0
	s_add_u32 s14, s16, 0x80080
	s_addc_u32 s15, s17, 0
	s_mov_b32 s38, -2
	s_add_i32 s39, 0, 0x10000
	v_add_u32_e32 v246, s39, v144
	ds_read_b128 v[148:151], v246
	ds_read_b128 v[152:155], v246 offset:1024
	ds_read_b128 v[156:159], v246 offset:2048
	ds_read_b128 v[160:163], v246 offset:3072
	s_add_i32 m0, s26, 0xc000
	ds_read_b128 v[168:171], v146
	ds_read_b128 v[172:175], v146 offset:1024
	ds_read_b128 v[176:179], v146 offset:2048
	ds_read_b128 v[180:183], v146 offset:3072
	ds_read_b128 v[184:187], v146 offset:4096
	ds_read_b128 v[188:191], v146 offset:5120
	ds_read_b128 v[192:195], v146 offset:6144
	ds_read_b128 v[212:215], v146 offset:7168
	global_load_lds_dwordx4 v140, s[14:15]
	s_add_i32 m0, s26, 0xe000
	s_nop 0
	global_load_lds_dwordx4 v138, s[14:15]
	s_waitcnt lgkmcnt(6)
	s_setprio 1
	s_barrier
	v_mfma_f32_16x16x32_bf16 v[128:131], v[148:151], v[168:171], 0
	v_mfma_f32_16x16x32_bf16 v[128:131], v[152:155], v[172:175], v[128:131]
	s_waitcnt lgkmcnt(0)
	v_mfma_f32_16x16x32_bf16 v[120:123], v[148:151], v[176:179], 0
	v_mfma_f32_16x16x32_bf16 v[120:123], v[152:155], v[180:183], v[120:123]
	v_mfma_f32_16x16x32_bf16 v[112:115], v[148:151], v[184:187], 0
	v_mfma_f32_16x16x32_bf16 v[112:115], v[152:155], v[188:191], v[112:115]
	v_mfma_f32_16x16x32_bf16 v[104:107], v[148:151], v[192:195], 0
	v_mfma_f32_16x16x32_bf16 v[104:107], v[152:155], v[212:215], v[104:107]
	v_mfma_f32_16x16x32_bf16 v[124:127], v[156:159], v[168:171], 0
	v_mfma_f32_16x16x32_bf16 v[124:127], v[160:163], v[172:175], v[124:127]
	v_mfma_f32_16x16x32_bf16 v[116:119], v[156:159], v[176:179], 0
	v_mfma_f32_16x16x32_bf16 v[116:119], v[160:163], v[180:183], v[116:119]
	v_mfma_f32_16x16x32_bf16 v[108:111], v[156:159], v[184:187], 0
	v_mfma_f32_16x16x32_bf16 v[108:111], v[160:163], v[188:191], v[108:111]
	v_mfma_f32_16x16x32_bf16 v[100:103], v[156:159], v[192:195], 0
	v_mfma_f32_16x16x32_bf16 v[100:103], v[160:163], v[212:215], v[100:103]
	s_barrier
	s_setprio 0
	s_add_u32 s16, s14, 0xfff80080
	s_addc_u32 s17, s15, -1
	s_cmp_eq_u32 s38, 28
	s_cselect_b32 s19, s3, s17
	s_cselect_b32 s18, s13, s16
	s_cselect_b32 s17, s5, s37
	s_cselect_b32 s16, s35, s36
	s_add_i32 s42, 0, 0x14000
	s_add_i32 s39, s39, s25
	ds_read_b128 v[216:219], v246 offset:16384
	ds_read_b128 v[220:223], v246 offset:17408
	ds_read_b128 v[224:227], v246 offset:18432
	ds_read_b128 v[228:231], v246 offset:19456
	s_add_u32 s98, s16, 0x80
	s_addc_u32 s99, s17, 0
	s_mov_b32 m0, s39
	s_nop 0
	global_load_lds_dwordx4 v2, s[16:17]
	s_add_i32 m0, s39, 0x2000
	s_nop 0
	global_load_lds_dwordx4 v0, s[16:17]
	s_mov_b32 m0, s26
	s_add_u32 s100, s18, 0x80
	s_addc_u32 s101, s19, 0
	s_waitcnt vmcnt(10)
	s_waitcnt lgkmcnt(2)
	s_setprio 1
	s_barrier
	v_mfma_f32_16x16x32_bf16 v[96:99], v[216:219], v[168:171], 0
	v_mfma_f32_16x16x32_bf16 v[96:99], v[220:223], v[172:175], v[96:99]
	s_waitcnt lgkmcnt(0)
	v_mfma_f32_16x16x32_bf16 v[88:91], v[216:219], v[176:179], 0
	v_mfma_f32_16x16x32_bf16 v[88:91], v[220:223], v[180:183], v[88:91]
	v_mfma_f32_16x16x32_bf16 v[80:83], v[216:219], v[184:187], 0
	v_mfma_f32_16x16x32_bf16 v[80:83], v[220:223], v[188:191], v[80:83]
	v_mfma_f32_16x16x32_bf16 v[72:75], v[216:219], v[192:195], 0
	v_mfma_f32_16x16x32_bf16 v[72:75], v[220:223], v[212:215], v[72:75]
	v_mfma_f32_16x16x32_bf16 v[92:95], v[224:227], v[168:171], 0
	v_mfma_f32_16x16x32_bf16 v[92:95], v[228:231], v[172:175], v[92:95]
	v_mfma_f32_16x16x32_bf16 v[84:87], v[224:227], v[176:179], 0
	v_mfma_f32_16x16x32_bf16 v[84:87], v[228:231], v[180:183], v[84:87]
	v_mfma_f32_16x16x32_bf16 v[76:79], v[224:227], v[184:187], 0
	v_mfma_f32_16x16x32_bf16 v[76:79], v[228:231], v[188:191], v[76:79]
	v_mfma_f32_16x16x32_bf16 v[68:71], v[224:227], v[192:195], 0
	v_mfma_f32_16x16x32_bf16 v[68:71], v[228:231], v[212:215], v[68:71]
	s_barrier
	s_setprio 0
	ds_read_b128 v[168:171], v146 offset:16384
	ds_read_b128 v[172:175], v146 offset:17408
	ds_read_b128 v[176:179], v146 offset:18432
	ds_read_b128 v[180:183], v146 offset:19456
	ds_read_b128 v[184:187], v146 offset:20480
	ds_read_b128 v[188:191], v146 offset:21504
	ds_read_b128 v[192:195], v146 offset:22528
	ds_read_b128 v[212:215], v146 offset:23552
	global_load_lds_dwordx4 v134, s[18:19]
	s_mov_b32 m0, s27
	s_nop 0
	global_load_lds_dwordx4 v132, s[18:19]
	s_waitcnt lgkmcnt(6)
	s_setprio 1
	s_barrier
	v_mfma_f32_16x16x32_bf16 v[64:67], v[148:151], v[168:171], 0
	v_mfma_f32_16x16x32_bf16 v[64:67], v[152:155], v[172:175], v[64:67]
	s_waitcnt lgkmcnt(0)
	v_mfma_f32_16x16x32_bf16 v[56:59], v[148:151], v[176:179], 0
	v_mfma_f32_16x16x32_bf16 v[56:59], v[152:155], v[180:183], v[56:59]
	v_mfma_f32_16x16x32_bf16 v[48:51], v[148:151], v[184:187], 0
	v_mfma_f32_16x16x32_bf16 v[48:51], v[152:155], v[188:191], v[48:51]
	v_mfma_f32_16x16x32_bf16 v[40:43], v[148:151], v[192:195], 0
	v_mfma_f32_16x16x32_bf16 v[40:43], v[152:155], v[212:215], v[40:43]
	v_mfma_f32_16x16x32_bf16 v[60:63], v[156:159], v[168:171], 0
	v_mfma_f32_16x16x32_bf16 v[60:63], v[160:163], v[172:175], v[60:63]
	v_mfma_f32_16x16x32_bf16 v[52:55], v[156:159], v[176:179], 0
	v_mfma_f32_16x16x32_bf16 v[52:55], v[160:163], v[180:183], v[52:55]
	v_mfma_f32_16x16x32_bf16 v[44:47], v[156:159], v[184:187], 0
	v_mfma_f32_16x16x32_bf16 v[44:47], v[160:163], v[188:191], v[44:47]
	v_mfma_f32_16x16x32_bf16 v[36:39], v[156:159], v[192:195], 0
	v_mfma_f32_16x16x32_bf16 v[36:39], v[160:163], v[212:215], v[36:39]
	s_barrier
; #define PG8_WAIT_V(n) asm volatile("s_waitcnt vmcnt(" #n ")" ::: "memory")
; #define PG8_WAIT_L(n) asm volatile("s_waitcnt lgkmcnt(" #n ")" ::: "memory")
; #define PG8_BAR __builtin_amdgcn_s_barrier()
; #define PG8_SCHED __builtin_amdgcn_sched_barrier(0)
; template <class Epi, class AddrA, class AddrB>
; __device__ __forceinline__ void gemm_phase(const Sched S, const int lda, const int ldb, const int K, const AddrA addrA,
;                                            const AddrB addrB, const Epi E) {
;     ...
;       PG8_BAR; PG8_WAIT_L(0); PG8_MMA(1, 0, At, B0); PG8_BAR; PG8_SCHED;
;       PG8_STAGE(PG8_SB(0, 1), b2 + hstepB, voffB);
;       PG8_WAIT_V(6); PG8_BAR; PG8_MMA(1, 1, At, B1); PG8_BAR;
;       PG8_LDB(B0, 1, 0); PG8_SCHED; PG8_LDA(At, 1, 0); PG8_STAGE(PG8_SA(0, 1), a2 + hstepA, voffA);
;       PG8_WAIT_L(8); PG8_BAR; PG8_WAIT_L(0); PG8_MMA(0, 0, At, B0); PG8_BAR; PG8_SCHED;
;       PG8_LDB(B1, 1, 1); PG8_STAGE(PG8_SB(1, 0), b3, voffB);
;       PG8_BAR; PG8_WAIT_L(0); PG8_MMA(0, 1, At, B1); PG8_BAR;
;       PG8_LDA(At, 1, 1); PG8_STAGE(PG8_SA(1, 0), a3, voffA);
;       PG8_BAR; PG8_WAIT_L(0); PG8_MMA(1, 0, At, B0); PG8_BAR; PG8_SCHED;
	s_setprio 0
	s_add_u32 s40, s16, 0x80000
	s_addc_u32 s41, s17, 0
	s_add_i32 s39, s42, s25
	s_mov_b32 m0, s39
	s_nop 0
	global_load_lds_dwordx4 v2, s[40:41]
	s_add_i32 m0, s39, 0x2000
	s_nop 0
	global_load_lds_dwordx4 v0, s[40:41]
	s_add_i32 s39, 0, 0x18000
	s_waitcnt vmcnt(8)
	s_setprio 1
	s_barrier
	v_mfma_f32_16x16x32_bf16 v[32:35], v[216:219], v[168:171], 0
	v_mfma_f32_16x16x32_bf16 v[32:35], v[220:223], v[172:175], v[32:35]
	v_mfma_f32_16x16x32_bf16 v[24:27], v[216:219], v[176:179], 0
	v_mfma_f32_16x16x32_bf16 v[24:27], v[220:223], v[180:183], v[24:27]
	v_mfma_f32_16x16x32_bf16 v[16:19], v[216:219], v[184:187], 0
	v_mfma_f32_16x16x32_bf16 v[16:19], v[220:223], v[188:191], v[16:19]
	v_mfma_f32_16x16x32_bf16 v[8:11], v[216:219], v[192:195], 0
	v_mfma_f32_16x16x32_bf16 v[8:11], v[220:223], v[212:215], v[8:11]
	v_mfma_f32_16x16x32_bf16 v[28:31], v[224:227], v[168:171], 0
	v_mfma_f32_16x16x32_bf16 v[28:31], v[228:231], v[172:175], v[28:31]
	v_mfma_f32_16x16x32_bf16 v[20:23], v[224:227], v[176:179], 0
	v_mfma_f32_16x16x32_bf16 v[20:23], v[228:231], v[180:183], v[20:23]
	v_mfma_f32_16x16x32_bf16 v[12:15], v[224:227], v[184:187], 0
	v_mfma_f32_16x16x32_bf16 v[12:15], v[228:231], v[188:191], v[12:15]
	v_mfma_f32_16x16x32_bf16 v[4:7], v[224:227], v[192:195], 0
	v_mfma_f32_16x16x32_bf16 v[4:7], v[228:231], v[212:215], v[4:7]
	s_barrier
	s_setprio 0
	ds_read_b128 v[148:151], v246 offset:32768
	ds_read_b128 v[152:155], v246 offset:33792
	ds_read_b128 v[156:159], v246 offset:34816
	ds_read_b128 v[160:163], v246 offset:35840
	s_add_u32 s18, s18, 0x80000
	s_addc_u32 s19, s19, 0
	s_mov_b32 m0, s28
	ds_read_b128 v[168:171], v146 offset:32768
	ds_read_b128 v[172:175], v146 offset:33792
	ds_read_b128 v[176:179], v146 offset:34816
	ds_read_b128 v[180:183], v146 offset:35840
	ds_read_b128 v[184:187], v146 offset:36864
	ds_read_b128 v[188:191], v146 offset:37888
	ds_read_b128 v[192:195], v146 offset:38912
	ds_read_b128 v[212:215], v146 offset:39936
	global_load_lds_dwordx4 v134, s[18:19]
	s_mov_b32 m0, s29
	s_nop 0
	global_load_lds_dwordx4 v132, s[18:19]
	s_waitcnt lgkmcnt(6)
	s_setprio 1
	s_barrier
	v_mfma_f32_16x16x32_bf16 v[128:131], v[148:151], v[168:171], v[128:131]
	v_mfma_f32_16x16x32_bf16 v[128:131], v[152:155], v[172:175], v[128:131]
	s_waitcnt lgkmcnt(0)
	v_mfma_f32_16x16x32_bf16 v[120:123], v[148:151], v[176:179], v[120:123]
	v_mfma_f32_16x16x32_bf16 v[120:123], v[152:155], v[180:183], v[120:123]
	v_mfma_f32_16x16x32_bf16 v[112:115], v[148:151], v[184:187], v[112:115]
	v_mfma_f32_16x16x32_bf16 v[112:115], v[152:155], v[188:191], v[112:115]
	v_mfma_f32_16x16x32_bf16 v[104:107], v[148:151], v[192:195], v[104:107]
	v_mfma_f32_16x16x32_bf16 v[104:107], v[152:155], v[212:215], v[104:107]
	v_mfma_f32_16x16x32_bf16 v[124:127], v[156:159], v[168:171], v[124:127]
	v_mfma_f32_16x16x32_bf16 v[124:127], v[160:163], v[172:175], v[124:127]
	v_mfma_f32_16x16x32_bf16 v[116:119], v[156:159], v[176:179], v[116:119]
	v_mfma_f32_16x16x32_bf16 v[116:119], v[160:163], v[180:183], v[116:119]
	v_mfma_f32_16x16x32_bf16 v[108:111], v[156:159], v[184:187], v[108:111]
	v_mfma_f32_16x16x32_bf16 v[108:111], v[160:163], v[188:191], v[108:111]
	v_mfma_f32_16x16x32_bf16 v[100:103], v[156:159], v[192:195], v[100:103]
	v_mfma_f32_16x16x32_bf16 v[100:103], v[160:163], v[212:215], v[100:103]
	s_barrier
	s_setprio 0
	s_add_i32 s18, 0, 0x1c000
	s_add_i32 s19, s39, s25
	s_mov_b32 m0, s19
	ds_read_b128 v[216:219], v246 offset:49152
	ds_read_b128 v[220:223], v246 offset:50176
	ds_read_b128 v[224:227], v246 offset:51200
	ds_read_b128 v[228:231], v246 offset:52224
	global_load_lds_dwordx4 v2, s[98:99]
	s_add_i32 m0, s19, 0x2000
	s_nop 0
	global_load_lds_dwordx4 v0, s[98:99]
	s_mov_b32 m0, s30
	s_waitcnt vmcnt(10)
	s_waitcnt lgkmcnt(2)
	s_setprio 1
	s_barrier
	v_mfma_f32_16x16x32_bf16 v[96:99], v[216:219], v[168:171], v[96:99]
	v_mfma_f32_16x16x32_bf16 v[96:99], v[220:223], v[172:175], v[96:99]
	s_waitcnt lgkmcnt(0)
	v_mfma_f32_16x16x32_bf16 v[88:91], v[216:219], v[176:179], v[88:91]
	v_mfma_f32_16x16x32_bf16 v[88:91], v[220:223], v[180:183], v[88:91]
	v_mfma_f32_16x16x32_bf16 v[80:83], v[216:219], v[184:187], v[80:83]
	v_mfma_f32_16x16x32_bf16 v[80:83], v[220:223], v[188:191], v[80:83]
	v_mfma_f32_16x16x32_bf16 v[72:75], v[216:219], v[192:195], v[72:75]
	v_mfma_f32_16x16x32_bf16 v[72:75], v[220:223], v[212:215], v[72:75]
	v_mfma_f32_16x16x32_bf16 v[92:95], v[224:227], v[168:171], v[92:95]
	v_mfma_f32_16x16x32_bf16 v[92:95], v[228:231], v[172:175], v[92:95]
	v_mfma_f32_16x16x32_bf16 v[84:87], v[224:227], v[176:179], v[84:87]
	v_mfma_f32_16x16x32_bf16 v[84:87], v[228:231], v[180:183], v[84:87]
	v_mfma_f32_16x16x32_bf16 v[76:79], v[224:227], v[184:187], v[76:79]
	v_mfma_f32_16x16x32_bf16 v[76:79], v[228:231], v[188:191], v[76:79]
	v_mfma_f32_16x16x32_bf16 v[68:71], v[224:227], v[192:195], v[68:71]
	v_mfma_f32_16x16x32_bf16 v[68:71], v[228:231], v[212:215], v[68:71]
	s_barrier
	s_setprio 0
	ds_read_b128 v[168:171], v146 offset:49152
	ds_read_b128 v[172:175], v146 offset:50176
	ds_read_b128 v[176:179], v146 offset:51200
	ds_read_b128 v[180:183], v146 offset:52224
	ds_read_b128 v[184:187], v146 offset:53248
	ds_read_b128 v[188:191], v146 offset:54272
	ds_read_b128 v[192:195], v146 offset:55296
	ds_read_b128 v[212:215], v146 offset:56320
	global_load_lds_dwordx4 v134, s[100:101]
	s_mov_b32 m0, s31
	s_nop 0
	global_load_lds_dwordx4 v132, s[100:101]
	s_waitcnt lgkmcnt(6)
	s_setprio 1
	s_barrier
; #define PG8_WAIT_V(n) asm volatile("s_waitcnt vmcnt(" #n ")" ::: "memory")
; #define PG8_WAIT_L(n) asm volatile("s_waitcnt lgkmcnt(" #n ")" ::: "memory")
; #define PG8_BAR __builtin_amdgcn_s_barrier()
; #define PG8_SCHED __builtin_amdgcn_sched_barrier(0)
; template <class Epi, class AddrA, class AddrB>
; __device__ __forceinline__ void gemm_phase(const Sched S, const int lda, const int ldb, const int K, const AddrA addrA,
;                                            const AddrB addrB, const Epi E) {
;     ...
;       PG8_LDB(B0, 0, 0); PG8_SCHED; PG8_LDA(At, 0, 0); PG8_STAGE(PG8_SA(1, 1), a1 + hstepA, voffA);
;       PG8_WAIT_L(8); PG8_BAR; PG8_WAIT_L(0); PG8_MMA(0, 0, At, B0); PG8_BAR; PG8_SCHED;
;     ...
;       PG8_BAR; PG8_WAIT_L(0); PG8_MMA(1, 0, At, B0); PG8_BAR; PG8_SCHED;
;       PG8_STAGE(PG8_SB(1, 1), b3 + hstepB, voffB);
;       PG8_WAIT_V(6); PG8_BAR; PG8_MMA(1, 1, At, B1); PG8_BAR;
	v_mfma_f32_16x16x32_bf16 v[64:67], v[148:151], v[168:171], v[64:67]
	v_mfma_f32_16x16x32_bf16 v[64:67], v[152:155], v[172:175], v[64:67]
	s_waitcnt lgkmcnt(0)
	v_mfma_f32_16x16x32_bf16 v[56:59], v[148:151], v[176:179], v[56:59]
	v_mfma_f32_16x16x32_bf16 v[56:59], v[152:155], v[180:183], v[56:59]
	v_mfma_f32_16x16x32_bf16 v[48:51], v[148:151], v[184:187], v[48:51]
	v_mfma_f32_16x16x32_bf16 v[48:51], v[152:155], v[188:191], v[48:51]
	v_mfma_f32_16x16x32_bf16 v[40:43], v[148:151], v[192:195], v[40:43]
	v_mfma_f32_16x16x32_bf16 v[40:43], v[152:155], v[212:215], v[40:43]
	v_mfma_f32_16x16x32_bf16 v[60:63], v[156:159], v[168:171], v[60:63]
	v_mfma_f32_16x16x32_bf16 v[60:63], v[160:163], v[172:175], v[60:63]
	v_mfma_f32_16x16x32_bf16 v[52:55], v[156:159], v[176:179], v[52:55]
	v_mfma_f32_16x16x32_bf16 v[52:55], v[160:163], v[180:183], v[52:55]
	v_mfma_f32_16x16x32_bf16 v[44:47], v[156:159], v[184:187], v[44:47]
	v_mfma_f32_16x16x32_bf16 v[44:47], v[160:163], v[188:191], v[44:47]
	v_mfma_f32_16x16x32_bf16 v[36:39], v[156:159], v[192:195], v[36:39]
	v_mfma_f32_16x16x32_bf16 v[36:39], v[160:163], v[212:215], v[36:39]
	s_barrier
	s_setprio 0
	s_add_u32 s16, s16, 0x80080
	s_addc_u32 s17, s17, 0
	s_add_i32 s18, s18, s25
	s_mov_b32 m0, s18
	s_nop 0
	global_load_lds_dwordx4 v2, s[16:17]
	s_add_i32 m0, s18, 0x2000
	s_nop 0
	global_load_lds_dwordx4 v0, s[16:17]
	s_add_i32 s38, s38, 2
	s_add_u32 s36, s36, 0x100
	s_addc_u32 s37, s37, 0
	s_add_u32 s14, s14, 0x100
	s_addc_u32 s15, s15, 0
	s_waitcnt vmcnt(8)
	s_setprio 1
	s_barrier
	v_mfma_f32_16x16x32_bf16 v[32:35], v[216:219], v[168:171], v[32:35]
	v_mfma_f32_16x16x32_bf16 v[32:35], v[220:223], v[172:175], v[32:35]
	v_mfma_f32_16x16x32_bf16 v[24:27], v[216:219], v[176:179], v[24:27]
	v_mfma_f32_16x16x32_bf16 v[24:27], v[220:223], v[180:183], v[24:27]
	v_mfma_f32_16x16x32_bf16 v[16:19], v[216:219], v[184:187], v[16:19]
	v_mfma_f32_16x16x32_bf16 v[16:19], v[220:223], v[188:191], v[16:19]
	v_mfma_f32_16x16x32_bf16 v[8:11], v[216:219], v[192:195], v[8:11]
	v_mfma_f32_16x16x32_bf16 v[8:11], v[220:223], v[212:215], v[8:11]
	v_mfma_f32_16x16x32_bf16 v[28:31], v[224:227], v[168:171], v[28:31]
	v_mfma_f32_16x16x32_bf16 v[28:31], v[228:231], v[172:175], v[28:31]
	v_mfma_f32_16x16x32_bf16 v[20:23], v[224:227], v[176:179], v[20:23]
	v_mfma_f32_16x16x32_bf16 v[20:23], v[228:231], v[180:183], v[20:23]
	v_mfma_f32_16x16x32_bf16 v[12:15], v[224:227], v[184:187], v[12:15]
	v_mfma_f32_16x16x32_bf16 v[12:15], v[228:231], v[188:191], v[12:15]
	v_mfma_f32_16x16x32_bf16 v[4:7], v[224:227], v[192:195], v[4:7]
	v_mfma_f32_16x16x32_bf16 v[4:7], v[228:231], v[212:215], v[4:7]
	s_barrier
	s_setprio 0
	s_cmp_gt_u32 s38, 29
.LBB0_619:
	s_add_i32 s39, 0, 0x10000
	v_add_u32_e32 v246, s39, v144
	ds_read_b128 v[148:151], v246
	ds_read_b128 v[152:155], v246 offset:1024
	ds_read_b128 v[156:159], v246 offset:2048
	ds_read_b128 v[160:163], v246 offset:3072
	s_add_i32 m0, s26, 0xc000
	ds_read_b128 v[168:171], v146
	ds_read_b128 v[172:175], v146 offset:1024
	ds_read_b128 v[176:179], v146 offset:2048
	ds_read_b128 v[180:183], v146 offset:3072
	ds_read_b128 v[184:187], v146 offset:4096
	ds_read_b128 v[188:191], v146 offset:5120
	ds_read_b128 v[192:195], v146 offset:6144
	ds_read_b128 v[212:215], v146 offset:7168
	global_load_lds_dwordx4 v140, s[14:15]
	s_add_i32 m0, s26, 0xe000
	s_nop 0
	global_load_lds_dwordx4 v138, s[14:15]
	s_waitcnt lgkmcnt(6)
	s_setprio 1
	s_barrier
	v_mfma_f32_16x16x32_bf16 v[128:131], v[148:151], v[168:171], v[128:131]
	v_mfma_f32_16x16x32_bf16 v[128:131], v[152:155], v[172:175], v[128:131]
	s_waitcnt lgkmcnt(0)
	v_mfma_f32_16x16x32_bf16 v[120:123], v[148:151], v[176:179], v[120:123]
	v_mfma_f32_16x16x32_bf16 v[120:123], v[152:155], v[180:183], v[120:123]
	v_mfma_f32_16x16x32_bf16 v[112:115], v[148:151], v[184:187], v[112:115]
	v_mfma_f32_16x16x32_bf16 v[112:115], v[152:155], v[188:191], v[112:115]
	v_mfma_f32_16x16x32_bf16 v[104:107], v[148:151], v[192:195], v[104:107]
	v_mfma_f32_16x16x32_bf16 v[104:107], v[152:155], v[212:215], v[104:107]
	v_mfma_f32_16x16x32_bf16 v[124:127], v[156:159], v[168:171], v[124:127]
	v_mfma_f32_16x16x32_bf16 v[124:127], v[160:163], v[172:175], v[124:127]
	v_mfma_f32_16x16x32_bf16 v[116:119], v[156:159], v[176:179], v[116:119]
	v_mfma_f32_16x16x32_bf16 v[116:119], v[160:163], v[180:183], v[116:119]
	v_mfma_f32_16x16x32_bf16 v[108:111], v[156:159], v[184:187], v[108:111]
	v_mfma_f32_16x16x32_bf16 v[108:111], v[160:163], v[188:191], v[108:111]
	v_mfma_f32_16x16x32_bf16 v[100:103], v[156:159], v[192:195], v[100:103]
	v_mfma_f32_16x16x32_bf16 v[100:103], v[160:163], v[212:215], v[100:103]
	s_barrier
	s_setprio 0
	s_add_u32 s16, s14, 0xfff80080
	s_addc_u32 s17, s15, -1
	s_cmp_eq_u32 s38, 28
	s_cselect_b32 s19, s3, s17
	s_cselect_b32 s18, s13, s16
	s_cselect_b32 s17, s5, s37
	s_cselect_b32 s16, s35, s36
	s_add_i32 s42, 0, 0x14000
	s_add_i32 s39, s39, s25
	ds_read_b128 v[216:219], v246 offset:16384
	ds_read_b128 v[220:223], v246 offset:17408
	ds_read_b128 v[224:227], v246 offset:18432
	ds_read_b128 v[228:231], v246 offset:19456
	s_add_u32 s98, s16, 0x80
	s_addc_u32 s99, s17, 0
	s_mov_b32 m0, s39
	s_nop 0
	global_load_lds_dwordx4 v2, s[16:17]
	s_add_i32 m0, s39, 0x2000
	s_nop 0
	global_load_lds_dwordx4 v0, s[16:17]
	s_mov_b32 m0, s26
	s_add_u32 s100, s18, 0x80
	s_addc_u32 s101, s19, 0
	s_waitcnt vmcnt(10)
	s_waitcnt lgkmcnt(2)
	s_setprio 1
	s_barrier
; #define PG8_WAIT_V(n) asm volatile("s_waitcnt vmcnt(" #n ")" ::: "memory")
; #define PG8_WAIT_L(n) asm volatile("s_waitcnt lgkmcnt(" #n ")" ::: "memory")
; #define PG8_BAR __builtin_amdgcn_s_barrier()
; #define PG8_SCHED __builtin_amdgcn_sched_barrier(0)
; template <class Epi, class AddrA, class AddrB>
; __device__ __forceinline__ void gemm_phase(const Sched S, const int lda, const int ldb, const int K, const AddrA addrA,
;                                            const AddrB addrB, const Epi E) {
;     ...
;       PG8_BAR; PG8_WAIT_L(0); PG8_MMA(0, 1, At, B1); PG8_BAR;
;       PG8_LDA(At, 0, 1); PG8_STAGE(PG8_SA(0, 0), a2, voffA);
;       PG8_BAR; PG8_WAIT_L(0); PG8_MMA(1, 0, At, B0); PG8_BAR; PG8_SCHED;
;       PG8_STAGE(PG8_SB(0, 1), b2 + hstepB, voffB);
;       PG8_WAIT_V(6); PG8_BAR; PG8_MMA(1, 1, At, B1); PG8_BAR;
;       PG8_LDB(B0, 1, 0); PG8_SCHED; PG8_LDA(At, 1, 0); PG8_STAGE(PG8_SA(0, 1), a2 + hstepA, voffA);
;       PG8_WAIT_L(8); PG8_BAR; PG8_WAIT_L(0); PG8_MMA(0, 0, At, B0); PG8_BAR; PG8_SCHED;
	v_mfma_f32_16x16x32_bf16 v[96:99], v[216:219], v[168:171], v[96:99]
	v_mfma_f32_16x16x32_bf16 v[96:99], v[220:223], v[172:175], v[96:99]
	s_waitcnt lgkmcnt(0)
	v_mfma_f32_16x16x32_bf16 v[88:91], v[216:219], v[176:179], v[88:91]
	v_mfma_f32_16x16x32_bf16 v[88:91], v[220:223], v[180:183], v[88:91]
	v_mfma_f32_16x16x32_bf16 v[80:83], v[216:219], v[184:187], v[80:83]
	v_mfma_f32_16x16x32_bf16 v[80:83], v[220:223], v[188:191], v[80:83]
	v_mfma_f32_16x16x32_bf16 v[72:75], v[216:219], v[192:195], v[72:75]
	v_mfma_f32_16x16x32_bf16 v[72:75], v[220:223], v[212:215], v[72:75]
	v_mfma_f32_16x16x32_bf16 v[92:95], v[224:227], v[168:171], v[92:95]
	v_mfma_f32_16x16x32_bf16 v[92:95], v[228:231], v[172:175], v[92:95]
	v_mfma_f32_16x16x32_bf16 v[84:87], v[224:227], v[176:179], v[84:87]
	v_mfma_f32_16x16x32_bf16 v[84:87], v[228:231], v[180:183], v[84:87]
	v_mfma_f32_16x16x32_bf16 v[76:79], v[224:227], v[184:187], v[76:79]
	v_mfma_f32_16x16x32_bf16 v[76:79], v[228:231], v[188:191], v[76:79]
	v_mfma_f32_16x16x32_bf16 v[68:71], v[224:227], v[192:195], v[68:71]
	v_mfma_f32_16x16x32_bf16 v[68:71], v[228:231], v[212:215], v[68:71]
	s_barrier
	s_setprio 0
	ds_read_b128 v[168:171], v146 offset:16384
	ds_read_b128 v[172:175], v146 offset:17408
	ds_read_b128 v[176:179], v146 offset:18432
	ds_read_b128 v[180:183], v146 offset:19456
	ds_read_b128 v[184:187], v146 offset:20480
	ds_read_b128 v[188:191], v146 offset:21504
	ds_read_b128 v[192:195], v146 offset:22528
	ds_read_b128 v[212:215], v146 offset:23552
	global_load_lds_dwordx4 v134, s[18:19]
	s_mov_b32 m0, s27
	s_nop 0
	global_load_lds_dwordx4 v132, s[18:19]
	s_waitcnt lgkmcnt(6)
	s_setprio 1
	s_barrier
	v_mfma_f32_16x16x32_bf16 v[64:67], v[148:151], v[168:171], v[64:67]
	v_mfma_f32_16x16x32_bf16 v[64:67], v[152:155], v[172:175], v[64:67]
	s_waitcnt lgkmcnt(0)
	v_mfma_f32_16x16x32_bf16 v[56:59], v[148:151], v[176:179], v[56:59]
	v_mfma_f32_16x16x32_bf16 v[56:59], v[152:155], v[180:183], v[56:59]
	v_mfma_f32_16x16x32_bf16 v[48:51], v[148:151], v[184:187], v[48:51]
	v_mfma_f32_16x16x32_bf16 v[48:51], v[152:155], v[188:191], v[48:51]
	v_mfma_f32_16x16x32_bf16 v[40:43], v[148:151], v[192:195], v[40:43]
	v_mfma_f32_16x16x32_bf16 v[40:43], v[152:155], v[212:215], v[40:43]
	v_mfma_f32_16x16x32_bf16 v[60:63], v[156:159], v[168:171], v[60:63]
	v_mfma_f32_16x16x32_bf16 v[60:63], v[160:163], v[172:175], v[60:63]
	v_mfma_f32_16x16x32_bf16 v[52:55], v[156:159], v[176:179], v[52:55]
	v_mfma_f32_16x16x32_bf16 v[52:55], v[160:163], v[180:183], v[52:55]
	v_mfma_f32_16x16x32_bf16 v[44:47], v[156:159], v[184:187], v[44:47]
	v_mfma_f32_16x16x32_bf16 v[44:47], v[160:163], v[188:191], v[44:47]
	v_mfma_f32_16x16x32_bf16 v[36:39], v[156:159], v[192:195], v[36:39]
	v_mfma_f32_16x16x32_bf16 v[36:39], v[160:163], v[212:215], v[36:39]
	s_barrier
	s_setprio 0
	s_add_u32 s40, s16, 0x80000
	s_addc_u32 s41, s17, 0
	s_add_i32 s39, s42, s25
	s_mov_b32 m0, s39
	s_nop 0
	global_load_lds_dwordx4 v2, s[40:41]
	s_add_i32 m0, s39, 0x2000
	s_nop 0
	global_load_lds_dwordx4 v0, s[40:41]
	s_add_i32 s39, 0, 0x18000
	s_waitcnt vmcnt(8)
	s_setprio 1
	s_barrier
	v_mfma_f32_16x16x32_bf16 v[32:35], v[216:219], v[168:171], v[32:35]
	v_mfma_f32_16x16x32_bf16 v[32:35], v[220:223], v[172:175], v[32:35]
	v_mfma_f32_16x16x32_bf16 v[24:27], v[216:219], v[176:179], v[24:27]
	v_mfma_f32_16x16x32_bf16 v[24:27], v[220:223], v[180:183], v[24:27]
	v_mfma_f32_16x16x32_bf16 v[16:19], v[216:219], v[184:187], v[16:19]
	v_mfma_f32_16x16x32_bf16 v[16:19], v[220:223], v[188:191], v[16:19]
	v_mfma_f32_16x16x32_bf16 v[8:11], v[216:219], v[192:195], v[8:11]
	v_mfma_f32_16x16x32_bf16 v[8:11], v[220:223], v[212:215], v[8:11]
	v_mfma_f32_16x16x32_bf16 v[28:31], v[224:227], v[168:171], v[28:31]
	v_mfma_f32_16x16x32_bf16 v[28:31], v[228:231], v[172:175], v[28:31]
	v_mfma_f32_16x16x32_bf16 v[20:23], v[224:227], v[176:179], v[20:23]
	v_mfma_f32_16x16x32_bf16 v[20:23], v[228:231], v[180:183], v[20:23]
	v_mfma_f32_16x16x32_bf16 v[12:15], v[224:227], v[184:187], v[12:15]
	v_mfma_f32_16x16x32_bf16 v[12:15], v[228:231], v[188:191], v[12:15]
	v_mfma_f32_16x16x32_bf16 v[4:7], v[224:227], v[192:195], v[4:7]
	v_mfma_f32_16x16x32_bf16 v[4:7], v[228:231], v[212:215], v[4:7]
	s_barrier
	s_setprio 0
	ds_read_b128 v[148:151], v246 offset:32768
	ds_read_b128 v[152:155], v246 offset:33792
	ds_read_b128 v[156:159], v246 offset:34816
	ds_read_b128 v[160:163], v246 offset:35840
	s_add_u32 s18, s18, 0x80000
	s_addc_u32 s19, s19, 0
	s_mov_b32 m0, s28
	ds_read_b128 v[168:171], v146 offset:32768
	ds_read_b128 v[172:175], v146 offset:33792
	ds_read_b128 v[176:179], v146 offset:34816
	ds_read_b128 v[180:183], v146 offset:35840
	ds_read_b128 v[184:187], v146 offset:36864
	ds_read_b128 v[188:191], v146 offset:37888
	ds_read_b128 v[192:195], v146 offset:38912
	ds_read_b128 v[212:215], v146 offset:39936
	global_load_lds_dwordx4 v134, s[18:19]
	s_mov_b32 m0, s29
	s_nop 0
	global_load_lds_dwordx4 v132, s[18:19]
	s_waitcnt lgkmcnt(6)
	s_setprio 1
	s_barrier
	v_mfma_f32_16x16x32_bf16 v[128:131], v[148:151], v[168:171], v[128:131]
	v_mfma_f32_16x16x32_bf16 v[128:131], v[152:155], v[172:175], v[128:131]
	s_waitcnt lgkmcnt(0)
	v_mfma_f32_16x16x32_bf16 v[120:123], v[148:151], v[176:179], v[120:123]
	v_mfma_f32_16x16x32_bf16 v[120:123], v[152:155], v[180:183], v[120:123]
	v_mfma_f32_16x16x32_bf16 v[112:115], v[148:151], v[184:187], v[112:115]
	v_mfma_f32_16x16x32_bf16 v[112:115], v[152:155], v[188:191], v[112:115]
	v_mfma_f32_16x16x32_bf16 v[104:107], v[148:151], v[192:195], v[104:107]
	v_mfma_f32_16x16x32_bf16 v[104:107], v[152:155], v[212:215], v[104:107]
	v_mfma_f32_16x16x32_bf16 v[124:127], v[156:159], v[168:171], v[124:127]
	v_mfma_f32_16x16x32_bf16 v[124:127], v[160:163], v[172:175], v[124:127]
	v_mfma_f32_16x16x32_bf16 v[116:119], v[156:159], v[176:179], v[116:119]
	v_mfma_f32_16x16x32_bf16 v[116:119], v[160:163], v[180:183], v[116:119]
	v_mfma_f32_16x16x32_bf16 v[108:111], v[156:159], v[184:187], v[108:111]
	v_mfma_f32_16x16x32_bf16 v[108:111], v[160:163], v[188:191], v[108:111]
	v_mfma_f32_16x16x32_bf16 v[100:103], v[156:159], v[192:195], v[100:103]
	v_mfma_f32_16x16x32_bf16 v[100:103], v[160:163], v[212:215], v[100:103]
	s_barrier
; #define PG8_WAIT_V(n) asm volatile("s_waitcnt vmcnt(" #n ")" ::: "memory")
; #define PG8_WAIT_L(n) asm volatile("s_waitcnt lgkmcnt(" #n ")" ::: "memory")
; #define PG8_BAR __builtin_amdgcn_s_barrier()
; #define PG8_SCHED __builtin_amdgcn_sched_barrier(0)
; template <class Epi, class AddrA, class AddrB>
; __device__ __forceinline__ void gemm_phase(const Sched S, const int lda, const int ldb, const int K, const AddrA addrA,
;                                            const AddrB addrB, const Epi E) {
;     ...
;       PG8_LDB(B1, 1, 1); PG8_STAGE(PG8_SB(1, 0), b3, voffB);
;       PG8_BAR; PG8_WAIT_L(0); PG8_MMA(0, 1, At, B1); PG8_BAR;
;       PG8_LDA(At, 1, 1); PG8_STAGE(PG8_SA(1, 0), a3, voffA);
;       PG8_BAR; PG8_WAIT_L(0); PG8_MMA(1, 0, At, B0); PG8_BAR; PG8_SCHED;
;       PG8_STAGE(PG8_SB(1, 1), b3 + hstepB, voffB);
;       PG8_WAIT_V(6); PG8_BAR; PG8_MMA(1, 1, At, B1); PG8_BAR;
	s_setprio 0
	s_add_i32 s18, 0, 0x1c000
	s_add_i32 s19, s39, s25
	s_mov_b32 m0, s19
	ds_read_b128 v[216:219], v246 offset:49152
	ds_read_b128 v[220:223], v246 offset:50176
	ds_read_b128 v[224:227], v246 offset:51200
	ds_read_b128 v[228:231], v246 offset:52224
	global_load_lds_dwordx4 v2, s[98:99]
	s_add_i32 m0, s19, 0x2000
	s_nop 0
	global_load_lds_dwordx4 v0, s[98:99]
	s_mov_b32 m0, s30
	s_waitcnt vmcnt(10)
	s_waitcnt lgkmcnt(2)
	s_setprio 1
	s_barrier
	v_mfma_f32_16x16x32_bf16 v[96:99], v[216:219], v[168:171], v[96:99]
	v_mfma_f32_16x16x32_bf16 v[96:99], v[220:223], v[172:175], v[96:99]
	s_waitcnt lgkmcnt(0)
	v_mfma_f32_16x16x32_bf16 v[88:91], v[216:219], v[176:179], v[88:91]
	v_mfma_f32_16x16x32_bf16 v[88:91], v[220:223], v[180:183], v[88:91]
	v_mfma_f32_16x16x32_bf16 v[80:83], v[216:219], v[184:187], v[80:83]
	v_mfma_f32_16x16x32_bf16 v[80:83], v[220:223], v[188:191], v[80:83]
	v_mfma_f32_16x16x32_bf16 v[72:75], v[216:219], v[192:195], v[72:75]
	v_mfma_f32_16x16x32_bf16 v[72:75], v[220:223], v[212:215], v[72:75]
	v_mfma_f32_16x16x32_bf16 v[92:95], v[224:227], v[168:171], v[92:95]
	v_mfma_f32_16x16x32_bf16 v[92:95], v[228:231], v[172:175], v[92:95]
	v_mfma_f32_16x16x32_bf16 v[84:87], v[224:227], v[176:179], v[84:87]
	v_mfma_f32_16x16x32_bf16 v[84:87], v[228:231], v[180:183], v[84:87]
	v_mfma_f32_16x16x32_bf16 v[76:79], v[224:227], v[184:187], v[76:79]
	v_mfma_f32_16x16x32_bf16 v[76:79], v[228:231], v[188:191], v[76:79]
	v_mfma_f32_16x16x32_bf16 v[68:71], v[224:227], v[192:195], v[68:71]
	v_mfma_f32_16x16x32_bf16 v[68:71], v[228:231], v[212:215], v[68:71]
	s_barrier
	s_setprio 0
	ds_read_b128 v[168:171], v146 offset:49152
	ds_read_b128 v[172:175], v146 offset:50176
	ds_read_b128 v[176:179], v146 offset:51200
	ds_read_b128 v[180:183], v146 offset:52224
	ds_read_b128 v[184:187], v146 offset:53248
	ds_read_b128 v[188:191], v146 offset:54272
	ds_read_b128 v[192:195], v146 offset:55296
	ds_read_b128 v[212:215], v146 offset:56320
	global_load_lds_dwordx4 v134, s[100:101]
	s_mov_b32 m0, s31
	s_nop 0
	global_load_lds_dwordx4 v132, s[100:101]
	s_waitcnt lgkmcnt(6)
	s_setprio 1
	s_barrier
	v_mfma_f32_16x16x32_bf16 v[64:67], v[148:151], v[168:171], v[64:67]
	v_mfma_f32_16x16x32_bf16 v[64:67], v[152:155], v[172:175], v[64:67]
	s_waitcnt lgkmcnt(0)
	v_mfma_f32_16x16x32_bf16 v[56:59], v[148:151], v[176:179], v[56:59]
	v_mfma_f32_16x16x32_bf16 v[56:59], v[152:155], v[180:183], v[56:59]
	v_mfma_f32_16x16x32_bf16 v[48:51], v[148:151], v[184:187], v[48:51]
	v_mfma_f32_16x16x32_bf16 v[48:51], v[152:155], v[188:191], v[48:51]
	v_mfma_f32_16x16x32_bf16 v[40:43], v[148:151], v[192:195], v[40:43]
	v_mfma_f32_16x16x32_bf16 v[40:43], v[152:155], v[212:215], v[40:43]
	v_mfma_f32_16x16x32_bf16 v[60:63], v[156:159], v[168:171], v[60:63]
	v_mfma_f32_16x16x32_bf16 v[60:63], v[160:163], v[172:175], v[60:63]
	v_mfma_f32_16x16x32_bf16 v[52:55], v[156:159], v[176:179], v[52:55]
	v_mfma_f32_16x16x32_bf16 v[52:55], v[160:163], v[180:183], v[52:55]
	v_mfma_f32_16x16x32_bf16 v[44:47], v[156:159], v[184:187], v[44:47]
	v_mfma_f32_16x16x32_bf16 v[44:47], v[160:163], v[188:191], v[44:47]
	v_mfma_f32_16x16x32_bf16 v[36:39], v[156:159], v[192:195], v[36:39]
	v_mfma_f32_16x16x32_bf16 v[36:39], v[160:163], v[212:215], v[36:39]
	s_barrier
	s_setprio 0
	s_add_u32 s16, s16, 0x80080
	s_addc_u32 s17, s17, 0
	s_add_i32 s18, s18, s25
	s_mov_b32 m0, s18
	s_nop 0
	global_load_lds_dwordx4 v2, s[16:17]
	s_add_i32 m0, s18, 0x2000
	s_nop 0
	global_load_lds_dwordx4 v0, s[16:17]
	s_add_i32 s38, s38, 2
	s_add_u32 s36, s36, 0x100
	s_addc_u32 s37, s37, 0
	s_add_u32 s14, s14, 0x100
	s_addc_u32 s15, s15, 0
	s_waitcnt vmcnt(8)
	s_setprio 1
	s_barrier
	v_mfma_f32_16x16x32_bf16 v[32:35], v[216:219], v[168:171], v[32:35]
	v_mfma_f32_16x16x32_bf16 v[32:35], v[220:223], v[172:175], v[32:35]
	v_mfma_f32_16x16x32_bf16 v[24:27], v[216:219], v[176:179], v[24:27]
	v_mfma_f32_16x16x32_bf16 v[24:27], v[220:223], v[180:183], v[24:27]
	v_mfma_f32_16x16x32_bf16 v[16:19], v[216:219], v[184:187], v[16:19]
	v_mfma_f32_16x16x32_bf16 v[16:19], v[220:223], v[188:191], v[16:19]
	v_mfma_f32_16x16x32_bf16 v[8:11], v[216:219], v[192:195], v[8:11]
	v_mfma_f32_16x16x32_bf16 v[8:11], v[220:223], v[212:215], v[8:11]
	v_mfma_f32_16x16x32_bf16 v[28:31], v[224:227], v[168:171], v[28:31]
	v_mfma_f32_16x16x32_bf16 v[28:31], v[228:231], v[172:175], v[28:31]
	v_mfma_f32_16x16x32_bf16 v[20:23], v[224:227], v[176:179], v[20:23]
	v_mfma_f32_16x16x32_bf16 v[20:23], v[228:231], v[180:183], v[20:23]
	v_mfma_f32_16x16x32_bf16 v[12:15], v[224:227], v[184:187], v[12:15]
	v_mfma_f32_16x16x32_bf16 v[12:15], v[228:231], v[188:191], v[12:15]
	v_mfma_f32_16x16x32_bf16 v[4:7], v[224:227], v[192:195], v[4:7]
	v_mfma_f32_16x16x32_bf16 v[4:7], v[228:231], v[212:215], v[4:7]
	s_barrier
	s_setprio 0
	s_cmp_gt_u32 s38, 29
	s_cbranch_scc0 .LBB0_619
;   __device__ __forceinline__ void operator()(EPI_ARGS) const {
;     ...
;     for (int ai = 0; ai < 2; ++ai)
; #pragma unroll
;       for (int bj = 0; bj < 2; ++bj) {
;         f32x4 x0[4], x1[4];
; #pragma unroll
;         for (int m = 0; m < 4; ++m) {
;           const size_t o = (row0 + ai * HALF + m * 16) * DM + col0 + bj * HALF;
;           x0[m] = *(const f32x4*)(xres + o);
;           x1[m] = *(const f32x4*)(xres + o + 4);
;         }
;         __builtin_amdgcn_sched_barrier(0);
; #pragma unroll
;         for (int m = 0; m < 4; ++m) {
;           const size_t o = (row0 + ai * HALF + m * 16) * DM + col0 + bj * HALF;
;           *(f32x4*)(hbuf + o) = acc[ai][bj][m][0] + x0[m] * ALPHA;
;           *(f32x4*)(hbuf + o + 4) = acc[ai][bj][m][1] + x1[m] * ALPHA;
;         }
	s_ashr_i32 s13, s12, 31
	v_lshl_or_b32 v142, s34, 8, v145
	v_ashrrev_i32_e32 v143, 31, v142
	s_lshl_b64 s[12:13], s[12:13], 21
	v_lshlrev_b64 v[184:185], 2, v[142:143]
	v_lshl_add_u64 v[188:189], s[12:13], 0, v[136:137]
	v_lshl_add_u64 v[186:187], s[0:1], 0, v[184:185]
	v_or_b32_e32 v190, 0x20000, v188
	v_mov_b32_e32 v191, v189
	v_or_b32_e32 v192, 0x40000, v188
	v_mov_b32_e32 v193, v189
	v_or_b32_e32 v194, 0x60000, v188
	v_mov_b32_e32 v195, v189
	v_lshl_add_u64 v[142:143], v[186:187], 0, v[188:189]
	v_lshl_add_u64 v[160:161], v[186:187], 0, v[190:191]
	v_lshl_add_u64 v[172:173], v[186:187], 0, v[192:193]
	v_lshl_add_u64 v[180:181], v[186:187], 0, v[194:195]
	flat_load_dwordx4 v[148:151], v[142:143]
	flat_load_dwordx4 v[152:155], v[142:143] offset:16
	flat_load_dwordx4 v[156:159], v[160:161]
	s_nop 0
	flat_load_dwordx4 v[160:163], v[160:161] offset:16
	s_nop 0
	flat_load_dwordx4 v[168:171], v[172:173]
	s_nop 0
	flat_load_dwordx4 v[172:175], v[172:173] offset:16
	s_nop 0
	flat_load_dwordx4 v[176:179], v[180:181]
	s_nop 0
	flat_load_dwordx4 v[180:183], v[180:181] offset:16
	v_lshl_add_u64 v[184:185], s[48:49], 0, v[184:185]
	s_mov_b32 s14, 0x3fb504f3
	s_waitcnt vmcnt(0) lgkmcnt(0)
	v_pk_fma_f32 v[148:149], v[148:149], s[14:15], v[128:129] op_sel_hi:[1,0,1]
	v_lshl_add_u64 v[128:129], v[184:185], 0, v[188:189]
	v_pk_fma_f32 v[126:127], v[154:155], s[14:15], v[126:127] op_sel_hi:[1,0,1]
	v_pk_fma_f32 v[124:125], v[152:153], s[14:15], v[124:125] op_sel_hi:[1,0,1]
	global_store_dwordx4 v[128:129], v[124:127], off offset:16
	v_pk_fma_f32 v[118:119], v[162:163], s[14:15], v[118:119] op_sel_hi:[1,0,1]
	v_pk_fma_f32 v[116:117], v[160:161], s[14:15], v[116:117] op_sel_hi:[1,0,1]
	v_lshl_add_u64 v[124:125], v[184:185], 0, v[190:191]
	v_pk_fma_f32 v[122:123], v[158:159], s[14:15], v[122:123] op_sel_hi:[1,0,1]
	v_pk_fma_f32 v[120:121], v[156:157], s[14:15], v[120:121] op_sel_hi:[1,0,1]
	global_store_dwordx4 v[124:125], v[116:119], off offset:16
	v_pk_fma_f32 v[110:111], v[174:175], s[14:15], v[110:111] op_sel_hi:[1,0,1]
	v_pk_fma_f32 v[108:109], v[172:173], s[14:15], v[108:109] op_sel_hi:[1,0,1]
	v_lshl_add_u64 v[116:117], v[184:185], 0, v[192:193]
	s_mov_b64 s[12:13], 0x200
	v_pk_fma_f32 v[150:151], v[150:151], s[14:15], v[130:131] op_sel_hi:[1,0,1]
	global_store_dwordx4 v[124:125], v[120:123], off
	v_pk_fma_f32 v[114:115], v[170:171], s[14:15], v[114:115] op_sel_hi:[1,0,1]
	v_pk_fma_f32 v[112:113], v[168:169], s[14:15], v[112:113] op_sel_hi:[1,0,1]
	global_store_dwordx4 v[116:117], v[108:111], off offset:16
	v_pk_fma_f32 v[106:107], v[178:179], s[14:15], v[106:107] op_sel_hi:[1,0,1]
	v_pk_fma_f32 v[104:105], v[176:177], s[14:15], v[104:105] op_sel_hi:[1,0,1]
	v_lshl_add_u64 v[108:109], v[184:185], 0, v[194:195]
	v_pk_fma_f32 v[102:103], v[182:183], s[14:15], v[102:103] op_sel_hi:[1,0,1]
	v_pk_fma_f32 v[100:101], v[180:181], s[14:15], v[100:101] op_sel_hi:[1,0,1]
	v_lshl_add_u64 v[124:125], v[186:187], 0, s[12:13]
	global_store_dwordx4 v[128:129], v[148:151], off
	global_store_dwordx4 v[116:117], v[112:115], off
	global_store_dwordx4 v[108:109], v[104:107], off
	global_store_dwordx4 v[108:109], v[100:103], off offset:16
	v_lshl_add_u64 v[112:113], v[124:125], 0, v[190:191]
	v_lshl_add_u64 v[120:121], v[124:125], 0, v[192:193]
	v_lshl_add_u64 v[130:131], v[124:125], 0, v[194:195]
	flat_load_dwordx4 v[100:103], v[142:143] offset:512
	flat_load_dwordx4 v[104:107], v[142:143] offset:528
	flat_load_dwordx4 v[108:111], v[112:113]
	s_nop 0
	flat_load_dwordx4 v[112:115], v[112:113] offset:16
	s_nop 0
	flat_load_dwordx4 v[116:119], v[120:121]
	s_nop 0
	flat_load_dwordx4 v[120:123], v[120:121] offset:16
	s_nop 0
	flat_load_dwordx4 v[124:127], v[130:131]
	flat_load_dwordx4 v[148:151], v[130:131] offset:16
	s_mov_b32 s3, 0x100000
	s_waitcnt vmcnt(0) lgkmcnt(0)
	v_pk_fma_f32 v[96:97], v[100:101], s[14:15], v[96:97] op_sel_hi:[1,0,1]
	v_add_co_u32_e32 v100, vcc, s3, v142
	s_mov_b32 s5, 0x120000
	s_nop 0
	v_addc_co_u32_e32 v101, vcc, 0, v143, vcc
	v_pk_fma_f32 v[98:99], v[102:103], s[14:15], v[98:99] op_sel_hi:[1,0,1]
	v_add_co_u32_e32 v102, vcc, s5, v142
	v_lshl_add_u64 v[130:131], v[184:185], 0, s[12:13]
	v_pk_fma_f32 v[94:95], v[106:107], s[14:15], v[94:95] op_sel_hi:[1,0,1]
	v_pk_fma_f32 v[92:93], v[104:105], s[14:15], v[92:93] op_sel_hi:[1,0,1]
	v_addc_co_u32_e32 v103, vcc, 0, v143, vcc
	s_mov_b32 s12, 0x140000
	global_store_dwordx4 v[128:129], v[92:95], off offset:528
	v_pk_fma_f32 v[86:87], v[114:115], s[14:15], v[86:87] op_sel_hi:[1,0,1]
	v_pk_fma_f32 v[84:85], v[112:113], s[14:15], v[84:85] op_sel_hi:[1,0,1]
	v_lshl_add_u64 v[92:93], v[130:131], 0, v[190:191]
	v_add_co_u32_e32 v104, vcc, s12, v142
	global_store_dwordx4 v[92:93], v[84:87], off offset:16
	v_pk_fma_f32 v[78:79], v[122:123], s[14:15], v[78:79] op_sel_hi:[1,0,1]
	v_pk_fma_f32 v[76:77], v[120:121], s[14:15], v[76:77] op_sel_hi:[1,0,1]
	v_lshl_add_u64 v[84:85], v[130:131], 0, v[192:193]
	v_addc_co_u32_e32 v105, vcc, 0, v143, vcc
	s_mov_b32 s13, 0x160000
	v_pk_fma_f32 v[90:91], v[110:111], s[14:15], v[90:91] op_sel_hi:[1,0,1]
	v_pk_fma_f32 v[88:89], v[108:109], s[14:15], v[88:89] op_sel_hi:[1,0,1]
	v_pk_fma_f32 v[82:83], v[118:119], s[14:15], v[82:83] op_sel_hi:[1,0,1]
	v_pk_fma_f32 v[80:81], v[116:117], s[14:15], v[80:81] op_sel_hi:[1,0,1]
	global_store_dwordx4 v[84:85], v[76:79], off offset:16
	v_pk_fma_f32 v[74:75], v[126:127], s[14:15], v[74:75] op_sel_hi:[1,0,1]
	v_pk_fma_f32 v[72:73], v[124:125], s[14:15], v[72:73] op_sel_hi:[1,0,1]
	v_lshl_add_u64 v[76:77], v[130:131], 0, v[194:195]
	v_pk_fma_f32 v[70:71], v[150:151], s[14:15], v[70:71] op_sel_hi:[1,0,1]
	v_pk_fma_f32 v[68:69], v[148:149], s[14:15], v[68:69] op_sel_hi:[1,0,1]
	s_mov_b64 s[16:17], 0x100000
	s_mov_b64 s[18:19], 0x120000
	s_mov_b64 s[34:35], 0x140000
	s_mov_b64 s[36:37], 0x160000
	v_add_co_u32_e32 v106, vcc, s13, v142
	global_store_dwordx4 v[128:129], v[96:99], off offset:512
	global_store_dwordx4 v[92:93], v[88:91], off
	global_store_dwordx4 v[84:85], v[80:83], off
	global_store_dwordx4 v[76:77], v[72:75], off
	global_store_dwordx4 v[76:77], v[68:71], off offset:16
	v_lshl_add_u64 v[80:81], v[142:143], 0, s[18:19]
	v_lshl_add_u64 v[72:73], v[142:143], 0, s[16:17]
	v_lshl_add_u64 v[88:89], v[142:143], 0, s[34:35]
	v_lshl_add_u64 v[96:97], v[142:143], 0, s[36:37]
	v_addc_co_u32_e32 v107, vcc, 0, v143, vcc
	flat_load_dwordx4 v[68:71], v[100:101]
	s_nop 0
	flat_load_dwordx4 v[72:75], v[72:73] offset:16
	s_nop 0
	flat_load_dwordx4 v[76:79], v[102:103]
	s_nop 0
	flat_load_dwordx4 v[80:83], v[80:81] offset:16
	s_nop 0
	flat_load_dwordx4 v[84:87], v[104:105]
	s_nop 0
	flat_load_dwordx4 v[88:91], v[88:89] offset:16
	s_nop 0
	flat_load_dwordx4 v[92:95], v[106:107]
	s_nop 0
	flat_load_dwordx4 v[96:99], v[96:97] offset:16
	s_waitcnt vmcnt(0) lgkmcnt(0)
; #define PG8_WAIT_V(n) asm volatile("s_waitcnt vmcnt(" #n ")" ::: "memory")
; #define PG8_BAR __builtin_amdgcn_s_barrier()
; template <class Epi, class AddrA, class AddrB>
; __device__ __forceinline__ void gemm_phase(const Sched S, const int lda, const int ldb, const int K, const AddrA addrA,
;                                            const AddrB addrB, const Epi E) {
;     ...
;   PG8_WAIT_V(0);
;   if (wr == 0) PG8_BAR;
;   PG8_BAR;
;   __device__ __forceinline__ void operator()(EPI_ARGS) const {
;     ...
;     for (int ai = 0; ai < 2; ++ai)
; #pragma unroll
;       for (int bj = 0; bj < 2; ++bj) {
;         f32x4 x0[4], x1[4];
; #pragma unroll
;         for (int m = 0; m < 4; ++m) {
;           const size_t o = (row0 + ai * HALF + m * 16) * DM + col0 + bj * HALF;
;           x0[m] = *(const f32x4*)(xres + o);
;           x1[m] = *(const f32x4*)(xres + o + 4);
;         }
;         __builtin_amdgcn_sched_barrier(0);
; #pragma unroll
;         for (int m = 0; m < 4; ++m) {
;           const size_t o = (row0 + ai * HALF + m * 16) * DM + col0 + bj * HALF;
;           *(f32x4*)(hbuf + o) = acc[ai][bj][m][0] + x0[m] * ALPHA;
;           *(f32x4*)(hbuf + o + 4) = acc[ai][bj][m][1] + x1[m] * ALPHA;
;         }
	v_pk_fma_f32 v[66:67], v[70:71], s[14:15], v[66:67] op_sel_hi:[1,0,1]
	v_add_co_u32_e32 v70, vcc, s3, v128
	v_pk_fma_f32 v[64:65], v[68:69], s[14:15], v[64:65] op_sel_hi:[1,0,1]
	v_lshl_add_u64 v[68:69], v[128:129], 0, s[16:17]
	v_addc_co_u32_e32 v71, vcc, 0, v129, vcc
	v_pk_fma_f32 v[62:63], v[74:75], s[14:15], v[62:63] op_sel_hi:[1,0,1]
	v_pk_fma_f32 v[60:61], v[72:73], s[14:15], v[60:61] op_sel_hi:[1,0,1]
	global_store_dwordx4 v[68:69], v[60:63], off offset:16
	v_add_co_u32_e32 v68, vcc, s5, v128
	s_nop 0
	v_lshl_add_u64 v[60:61], v[128:129], 0, s[18:19]
	v_addc_co_u32_e32 v69, vcc, 0, v129, vcc
	v_add_co_u32_e32 v72, vcc, s12, v128
	v_pk_fma_f32 v[54:55], v[82:83], s[14:15], v[54:55] op_sel_hi:[1,0,1]
	v_pk_fma_f32 v[52:53], v[80:81], s[14:15], v[52:53] op_sel_hi:[1,0,1]
	v_addc_co_u32_e32 v73, vcc, 0, v129, vcc
	global_store_dwordx4 v[60:61], v[52:55], off offset:16
	v_pk_fma_f32 v[46:47], v[90:91], s[14:15], v[46:47] op_sel_hi:[1,0,1]
	v_pk_fma_f32 v[44:45], v[88:89], s[14:15], v[44:45] op_sel_hi:[1,0,1]
	v_lshl_add_u64 v[52:53], v[128:129], 0, s[34:35]
	v_add_co_u32_e32 v74, vcc, s13, v128
	v_pk_fma_f32 v[58:59], v[78:79], s[14:15], v[58:59] op_sel_hi:[1,0,1]
	v_pk_fma_f32 v[56:57], v[76:77], s[14:15], v[56:57] op_sel_hi:[1,0,1]
	v_pk_fma_f32 v[50:51], v[86:87], s[14:15], v[50:51] op_sel_hi:[1,0,1]
	v_pk_fma_f32 v[48:49], v[84:85], s[14:15], v[48:49] op_sel_hi:[1,0,1]
	global_store_dwordx4 v[52:53], v[44:47], off offset:16
	v_pk_fma_f32 v[42:43], v[94:95], s[14:15], v[42:43] op_sel_hi:[1,0,1]
	v_pk_fma_f32 v[40:41], v[92:93], s[14:15], v[40:41] op_sel_hi:[1,0,1]
	v_lshl_add_u64 v[44:45], v[128:129], 0, s[36:37]
	v_addc_co_u32_e32 v75, vcc, 0, v129, vcc
	v_pk_fma_f32 v[38:39], v[98:99], s[14:15], v[38:39] op_sel_hi:[1,0,1]
	v_pk_fma_f32 v[36:37], v[96:97], s[14:15], v[36:37] op_sel_hi:[1,0,1]
	s_mov_b64 s[12:13], 0x100200
	s_mov_b64 s[16:17], 0x120200
	s_mov_b64 s[18:19], 0x140200
	s_mov_b64 s[34:35], 0x160200
	global_store_dwordx4 v[70:71], v[64:67], off
	global_store_dwordx4 v[68:69], v[56:59], off
	global_store_dwordx4 v[72:73], v[48:51], off
	global_store_dwordx4 v[74:75], v[40:43], off
	global_store_dwordx4 v[44:45], v[36:39], off offset:16
	v_lshl_add_u64 v[44:45], v[142:143], 0, s[12:13]
	v_lshl_add_u64 v[48:49], v[142:143], 0, s[16:17]
	v_lshl_add_u64 v[60:61], v[142:143], 0, s[18:19]
	v_lshl_add_u64 v[64:65], v[142:143], 0, s[34:35]
	flat_load_dwordx4 v[36:39], v[100:101] offset:512
	flat_load_dwordx4 v[40:43], v[102:103] offset:512
	s_nop 0
	flat_load_dwordx4 v[44:47], v[44:45] offset:16
	s_nop 0
	flat_load_dwordx4 v[48:51], v[48:49] offset:16
	s_nop 0
	flat_load_dwordx4 v[52:55], v[104:105] offset:512
	flat_load_dwordx4 v[56:59], v[106:107] offset:512
	s_nop 0
	flat_load_dwordx4 v[60:63], v[60:61] offset:16
	s_nop 0
	flat_load_dwordx4 v[64:67], v[64:65] offset:16
	s_waitcnt vmcnt(0) lgkmcnt(0)
	v_pk_fma_f32 v[32:33], v[36:37], s[14:15], v[32:33] op_sel_hi:[1,0,1]
	v_lshl_add_u64 v[36:37], v[128:129], 0, s[12:13]
	v_pk_fma_f32 v[30:31], v[46:47], s[14:15], v[30:31] op_sel_hi:[1,0,1]
	v_pk_fma_f32 v[28:29], v[44:45], s[14:15], v[28:29] op_sel_hi:[1,0,1]
	global_store_dwordx4 v[36:37], v[28:31], off offset:16
	v_pk_fma_f32 v[22:23], v[50:51], s[14:15], v[22:23] op_sel_hi:[1,0,1]
	v_pk_fma_f32 v[20:21], v[48:49], s[14:15], v[20:21] op_sel_hi:[1,0,1]
	v_lshl_add_u64 v[28:29], v[128:129], 0, s[16:17]
	global_store_dwordx4 v[28:29], v[20:23], off offset:16
	v_pk_fma_f32 v[14:15], v[62:63], s[14:15], v[14:15] op_sel_hi:[1,0,1]
	v_pk_fma_f32 v[12:13], v[60:61], s[14:15], v[12:13] op_sel_hi:[1,0,1]
	v_lshl_add_u64 v[20:21], v[128:129], 0, s[18:19]
	v_pk_fma_f32 v[34:35], v[38:39], s[14:15], v[34:35] op_sel_hi:[1,0,1]
	v_pk_fma_f32 v[26:27], v[42:43], s[14:15], v[26:27] op_sel_hi:[1,0,1]
	v_pk_fma_f32 v[24:25], v[40:41], s[14:15], v[24:25] op_sel_hi:[1,0,1]
	v_pk_fma_f32 v[18:19], v[54:55], s[14:15], v[18:19] op_sel_hi:[1,0,1]
	v_pk_fma_f32 v[16:17], v[52:53], s[14:15], v[16:17] op_sel_hi:[1,0,1]
	global_store_dwordx4 v[20:21], v[12:15], off offset:16
	v_pk_fma_f32 v[10:11], v[58:59], s[14:15], v[10:11] op_sel_hi:[1,0,1]
	v_pk_fma_f32 v[8:9], v[56:57], s[14:15], v[8:9] op_sel_hi:[1,0,1]
	v_lshl_add_u64 v[12:13], v[128:129], 0, s[34:35]
	v_pk_fma_f32 v[6:7], v[66:67], s[14:15], v[6:7] op_sel_hi:[1,0,1]
	v_pk_fma_f32 v[4:5], v[64:65], s[14:15], v[4:5] op_sel_hi:[1,0,1]
	s_and_b64 vcc, exec, s[6:7]
	s_mov_b32 s34, s4
	s_mov_b32 s12, s2
	s_mov_b64 s[14:15], s[10:11]
	s_mov_b64 s[16:17], s[8:9]
	global_store_dwordx4 v[70:71], v[32:35], off offset:512
	global_store_dwordx4 v[68:69], v[24:27], off offset:512
	global_store_dwordx4 v[72:73], v[16:19], off offset:512
	global_store_dwordx4 v[74:75], v[8:11], off offset:512
	global_store_dwordx4 v[12:13], v[4:7], off offset:16
	s_cbranch_vccz .LBB0_616
	s_waitcnt vmcnt(0)
	s_cmpk_gt_u32 s20, 0xff
	s_cbranch_scc1 .LBB0_623
	s_barrier
